# mixer units: nt hint on the once-read PXA streaming loads (retention rows, conv rows, FFT stage-1/context-DFT rows, gate rows); K/V tiles and counter-gated hand-off data unchanged
# speedup vs baseline: 1.0013x; 1.0013x over previous
.LBB0_646:
	s_andn2_b64 vcc, exec, s[6:7]
	s_mov_b32 s94, s18
	s_cbranch_vccnz .LBB0_648
	s_lshl_b32 s6, s12, 1
	s_add_i32 s0, s6, 0xfbe0
	s_and_b32 s7, s0, 0xfffe
	s_mul_i32 s7, s7, 0xf0f1
	s_lshr_b32 s7, s7, 21
	s_mul_i32 s7, s7, 34
	s_sub_i32 s0, s0, s7
	s_and_b32 s0, s0, 0xfffe
	s_lshl_b32 s7, s0, 7
	s_cmp_eq_u32 s0, 0
	s_movk_i32 s16, 0xff00
	s_movk_i32 s17, 0x300
	s_cselect_b32 s8, 0x4000, s16
	s_cselect_b32 s9, s17, 0x3000
	s_add_i32 s6, s6, 0xfbe1
	s_add_i32 s13, s8, s7
	s_and_b32 s7, s6, 0xffff
	s_mul_i32 s7, s7, 0xf0f1
	s_lshr_b32 s7, s7, 21
	s_mul_i32 s7, s7, 34
	s_sub_i32 s6, s6, s7
	s_and_b32 s8, s6, 0xffff
	s_add_i32 s13, s13, s9
	s_lshl_b32 s6, s8, 7
	s_cmp_eq_u32 s8, 1
	s_cselect_b32 s7, 0x4000, s16
	s_cselect_b32 s9, s17, 0x3000
	s_add_i32 s6, s7, s6
	s_add_i32 s9, s6, s9
	s_lshl_b32 s6, s5, 3
	s_ashr_i32 s7, s6, 31
	s_lshl_b64 s[6:7], s[6:7], 2
	s_add_u32 s6, s42, s6
	s_addc_u32 s7, s43, s7
	global_load_dword v0, v33, s[6:7] offset:12
	global_load_dword v1, v33, s[6:7] offset:28
	s_mov_b32 s6, 0xbfb8aa3b
	s_mov_b32 s16, 0x3f317218
	s_mov_b32 s7, 0x7f800000
	s_mov_b32 s17, 0x33800000
	v_ashrrev_i32_e32 v31, 3, v206
	v_readlane_b32 s20, v254, 56
	v_readlane_b32 s21, v254, 57
	v_and_b32_e32 v16, 15, v206
	v_lshlrev_b32_e32 v102, 2, v16
	v_and_b32_e32 v86, 12, v102
	v_mov_b32_e32 v62, 0x1400
	v_mov_b32_e32 v80, 0x1e00
	s_mov_b32 s94, 2
	s_waitcnt vmcnt(1)
	v_mul_f32_e32 v2, 0xbfb8aa3b, v0
	s_waitcnt vmcnt(0)
	v_mul_f32_e32 v3, 0xbfb8aa3b, v1
	v_fma_f32 v4, v0, s6, -v2
	v_rndne_f32_e32 v5, v2
	v_fma_f32 v6, v1, s6, -v3
	v_rndne_f32_e32 v7, v3
	v_fmac_f32_e32 v4, 0xb2a5705f, v0
	v_sub_f32_e32 v2, v2, v5
	v_fmac_f32_e32 v6, 0xb2a5705f, v1
	v_sub_f32_e32 v3, v3, v7
	v_add_f32_e32 v2, v2, v4
	v_cvt_i32_f32_e32 v5, v5
	v_add_f32_e32 v3, v3, v6
	v_exp_f32_e32 v2, v2
	v_cvt_i32_f32_e32 v7, v7
	v_exp_f32_e32 v3, v3
	s_mov_b32 s6, 0x42ce8ed0
	v_ldexp_f32 v2, v2, v5
	v_cmp_nlt_f32_e32 vcc, s6, v0
	v_ldexp_f32 v3, v3, v7
	s_nop 0
	v_cndmask_b32_e32 v2, 0, v2, vcc
	v_cmp_nlt_f32_e32 vcc, s6, v1
	s_mov_b32 s6, 0xc2b17218
	s_nop 0
	v_cndmask_b32_e32 v3, 0, v3, vcc
	v_cmp_ngt_f32_e32 vcc, s6, v0
	s_nop 1
	v_cndmask_b32_e32 v17, v227, v2, vcc
	v_cmp_ngt_f32_e32 vcc, s6, v1
	v_add_f32_e32 v1, 1.0, v17
	v_frexp_mant_f32_e32 v7, v1
	v_cndmask_b32_e32 v0, v227, v3, vcc
	v_cvt_f64_f32_e32 v[2:3], v1
	s_mov_b32 s6, 0x3f2aaaab
	v_add_f32_e32 v20, 1.0, v0
	v_add_f32_e32 v6, -1.0, v1
	v_frexp_exp_i32_f64_e32 v2, v[2:3]
	v_cmp_gt_f32_e32 vcc, s6, v7
	v_add_f32_e32 v8, -1.0, v20
	v_cvt_f64_f32_e32 v[4:5], v20
	v_sub_f32_e32 v9, v6, v1
	v_subbrev_co_u32_e32 v2, vcc, 0, v2, vcc
	v_sub_f32_e32 v6, v17, v6
	v_sub_f32_e32 v3, v8, v20
	v_frexp_exp_i32_f64_e32 v22, v[4:5]
	v_add_f32_e32 v4, 1.0, v9
	v_sub_u32_e32 v5, 0, v2
	v_sub_f32_e32 v8, v0, v8
	v_add_f32_e32 v3, 1.0, v3
	v_add_f32_e32 v4, v6, v4
	v_ldexp_f32 v1, v1, v5
	v_add_f32_e32 v23, v8, v3
	v_ldexp_f32 v3, v4, v5
	v_add_f32_e32 v4, -1.0, v1
	v_add_f32_e32 v6, 1.0, v1
	v_add_f32_e32 v5, 1.0, v4
	v_add_f32_e32 v7, -1.0, v6
	v_sub_f32_e32 v5, v1, v5
	v_sub_f32_e32 v1, v1, v7
	v_add_f32_e32 v1, v3, v1
	v_add_f32_e32 v7, v3, v5
	v_add_f32_e32 v3, v6, v1
	v_rcp_f32_e32 v10, v3
	v_add_f32_e32 v5, v4, v7
	v_sub_f32_e32 v6, v6, v3
	v_add_f32_e32 v1, v1, v6
	v_mul_f32_e32 v12, v5, v10
	v_mul_f32_e32 v6, v3, v12
	v_fma_f32 v8, v12, v3, -v6
	v_sub_f32_e32 v4, v4, v5
	v_fmac_f32_e32 v8, v12, v1
	v_add_f32_e32 v11, v7, v4
	v_add_f32_e32 v4, v6, v8
	v_sub_f32_e32 v7, v5, v4
	v_mov_b32_e32 v9, v4
	v_pk_add_f32 v[4:5], v[4:5], v[6:7] neg_lo:[0,1] neg_hi:[0,1]
	v_cvt_f32_i32_e32 v2, v2
	v_pk_add_f32 v[4:5], v[4:5], v[8:9] neg_lo:[0,1] neg_hi:[0,1]
	v_cmp_neq_f32_e32 vcc, s7, v17
	v_add_f32_e32 v5, v11, v5
	v_add_f32_e32 v4, v4, v5
	v_add_f32_e32 v5, v7, v4
	v_mul_f32_e32 v9, v10, v5
	v_mul_f32_e32 v6, v3, v9
	v_fma_f32 v8, v9, v3, -v6
	v_sub_f32_e32 v7, v7, v5
	v_fmac_f32_e32 v8, v9, v1
	v_add_f32_e32 v11, v4, v7
	v_add_f32_e32 v13, v12, v9
	v_add_f32_e32 v4, v6, v8
	v_sub_f32_e32 v3, v13, v12
	v_sub_f32_e32 v7, v5, v4
	v_sub_f32_e32 v1, v9, v3
	v_mov_b32_e32 v9, v4
	v_pk_add_f32 v[4:5], v[4:5], v[6:7] neg_lo:[0,1] neg_hi:[0,1]
	v_frexp_mant_f32_e32 v21, v20
	v_pk_add_f32 v[4:5], v[4:5], v[8:9] neg_lo:[0,1] neg_hi:[0,1]
	s_nop 0
	v_add_f32_e32 v3, v11, v5
	v_add_f32_e32 v3, v4, v3
	v_add_f32_e32 v3, v7, v3
	v_mul_f32_e32 v3, v10, v3
	v_add_f32_e32 v1, v1, v3
	v_add_f32_e32 v3, v13, v1
	v_mul_f32_e32 v4, v3, v3
	v_fmamk_f32 v7, v4, 0x3e9b6dac, v252
	v_sub_f32_e32 v6, v3, v13
	v_ldexp_f32 v5, v3, 1
	v_mul_f32_e32 v3, v3, v4
	v_fmaak_f32 v201, v4, v7, 0x3f2aaada
	v_sub_f32_e32 v1, v1, v6
	v_pk_mul_f32 v[6:7], v[2:3], v[200:201]
	v_ldexp_f32 v1, v1, 1
	v_fma_f32 v4, v2, s16, -v6
	v_fmac_f32_e32 v4, 0xb102e308, v2
	v_pk_add_f32 v[2:3], v[6:7], v[4:5]
	v_mov_b32_e32 v8, v6
	v_sub_f32_e32 v9, v3, v5
	v_pk_add_f32 v[10:11], v[2:3], v[6:7] neg_lo:[0,1] neg_hi:[0,1]
	v_sub_f32_e32 v7, v7, v9
	v_add_f32_e32 v9, v1, v7
	v_pk_add_f32 v[14:15], v[2:3], v[8:9]
	v_mov_b32_e32 v5, v2
	v_mov_b32_e32 v11, v15
	v_pk_add_f32 v[18:19], v[4:5], v[10:11] neg_lo:[0,1] neg_hi:[0,1]
	v_pk_add_f32 v[4:5], v[4:5], v[10:11]
	v_mov_b32_e32 v6, v3
	v_mov_b32_e32 v13, v2
	v_pk_add_f32 v[2:3], v[4:5], v[2:3] op_sel:[1,0] op_sel_hi:[0,1] neg_lo:[0,1] neg_hi:[0,1]
	v_mov_b32_e32 v12, v9
	v_mov_b32_e32 v8, v15
	v_mov_b32_e32 v9, v5
	v_mov_b32_e32 v7, v2
	v_pk_add_f32 v[10:11], v[14:15], v[2:3] op_sel_hi:[1,0] neg_lo:[0,1] neg_hi:[0,1]
	v_pk_add_f32 v[2:3], v[8:9], v[6:7] neg_lo:[0,1] neg_hi:[0,1]
	v_mov_b32_e32 v10, v18
	v_pk_add_f32 v[2:3], v[12:13], v[2:3] neg_lo:[0,1] neg_hi:[0,1]
	v_mov_b32_e32 v19, v5
	v_pk_add_f32 v[6:7], v[10:11], v[2:3]
	s_nop 0
	v_pk_add_f32 v[8:9], v[6:7], v[6:7] op_sel:[0,1] op_sel_hi:[1,0]
	s_nop 0
	v_pk_add_f32 v[4:5], v[4:5], v[8:9] op_sel:[1,0] op_sel_hi:[0,1]
	v_mov_b32_e32 v7, v4
	v_mov_b32_e32 v3, v8
	v_pk_add_f32 v[8:9], v[6:7], v[18:19] neg_lo:[0,1] neg_hi:[0,1]
	s_nop 0
	v_sub_f32_e32 v1, v6, v8
	v_pk_add_f32 v[2:3], v[2:3], v[8:9] neg_lo:[0,1] neg_hi:[0,1]
	v_sub_f32_e32 v1, v18, v1
	v_add_f32_e32 v1, v2, v1
	v_add_f32_e32 v1, v1, v3
	v_add_f32_e32 v1, v4, v1
	v_cndmask_b32_e32 v1, v227, v1, vcc
	v_cmp_lt_f32_e64 vcc, |v17|, s17
	s_nop 1
	v_cndmask_b32_e32 v17, v1, v17, vcc
	v_cmp_gt_f32_e32 vcc, s6, v21
	s_movk_i32 s6, 0x1000
	s_nop 0
	v_subbrev_co_u32_e32 v1, vcc, 0, v22, vcc
	v_sub_u32_e32 v2, 0, v1
	v_ldexp_f32 v3, v20, v2
	v_add_f32_e32 v4, -1.0, v3
	v_add_f32_e32 v6, 1.0, v3
	v_add_f32_e32 v5, 1.0, v4
	v_add_f32_e32 v7, -1.0, v6
	v_ldexp_f32 v2, v23, v2
	v_sub_f32_e32 v5, v3, v5
	v_sub_f32_e32 v3, v3, v7
	v_add_f32_e32 v5, v2, v5
	v_add_f32_e32 v2, v2, v3
	v_add_f32_e32 v10, v6, v2
	v_rcp_f32_e32 v12, v10
	v_sub_f32_e32 v3, v6, v10
	v_add_f32_e32 v11, v2, v3
	v_add_f32_e32 v3, v4, v5
	v_mul_f32_e32 v14, v3, v12
	v_sub_f32_e32 v2, v4, v3
	v_mul_f32_e32 v4, v10, v14
	v_fma_f32 v6, v14, v10, -v4
	v_fmac_f32_e32 v6, v14, v11
	v_add_f32_e32 v13, v5, v2
	v_add_f32_e32 v2, v4, v6
	v_sub_f32_e32 v5, v3, v2
	v_pk_add_f32 v[8:9], v[2:3], v[4:5] neg_lo:[0,1] neg_hi:[0,1]
	v_mov_b32_e32 v7, v2
	v_pk_add_f32 v[2:3], v[8:9], v[6:7] neg_lo:[0,1] neg_hi:[0,1]
	s_nop 0
	v_add_f32_e32 v3, v13, v3
	v_add_f32_e32 v2, v2, v3
	v_add_f32_e32 v3, v5, v2
	v_mul_f32_e32 v13, v12, v3
	v_mul_f32_e32 v4, v10, v13
	v_fma_f32 v6, v13, v10, -v4
	v_fmac_f32_e32 v6, v13, v11
	v_sub_f32_e32 v5, v5, v3
	v_add_f32_e32 v10, v2, v5
	v_add_f32_e32 v2, v4, v6
	v_sub_f32_e32 v5, v3, v2
	v_pk_add_f32 v[8:9], v[2:3], v[4:5] neg_lo:[0,1] neg_hi:[0,1]
	v_mov_b32_e32 v7, v2
	v_pk_add_f32 v[2:3], v[8:9], v[6:7] neg_lo:[0,1] neg_hi:[0,1]
	s_nop 0
	v_add_f32_e32 v3, v10, v3
	v_add_f32_e32 v2, v2, v3
	v_add_f32_e32 v3, v14, v13
	v_add_f32_e32 v2, v5, v2
	v_sub_f32_e32 v4, v3, v14
	v_mul_f32_e32 v2, v12, v2
	v_sub_f32_e32 v4, v13, v4
	v_add_f32_e32 v4, v4, v2
	v_add_f32_e32 v6, v3, v4
	v_mul_f32_e32 v7, v6, v6
	v_fmamk_f32 v2, v7, 0x3e9b6dac, v252
	v_fmaak_f32 v201, v7, v2, 0x3f2aaada
	v_cvt_f32_i32_e32 v2, v1
	v_sub_f32_e32 v1, v6, v3
	v_mul_f32_e32 v3, v6, v7
	v_ldexp_f32 v5, v6, 1
	v_pk_mul_f32 v[6:7], v[2:3], v[200:201]
	v_sub_f32_e32 v1, v4, v1
	v_fma_f32 v4, v2, s16, -v6
	v_fmac_f32_e32 v4, 0xb102e308, v2
	v_pk_add_f32 v[2:3], v[6:7], v[4:5]
	v_ldexp_f32 v1, v1, 1
	v_sub_f32_e32 v5, v3, v5
	v_sub_f32_e32 v5, v7, v5
	v_add_f32_e32 v9, v1, v5
	v_lshlrev_b32_e32 v1, 3, v206
	v_and_b32_e32 v30, 56, v1
	v_add_u32_e32 v12, s13, v31
	v_mov_b32_e32 v8, v6
	v_lshlrev_b32_e32 v32, 1, v30
	v_ashrrev_i32_e32 v13, 31, v12
	v_pk_add_f32 v[6:7], v[2:3], v[6:7] neg_lo:[0,1] neg_hi:[0,1]
	v_pk_add_f32 v[10:11], v[2:3], v[8:9]
	v_lshl_add_u64 v[34:35], s[20:21], 0, v[32:33]
	v_lshlrev_b64 v[12:13], 13, v[12:13]
	v_lshl_add_u64 v[12:13], v[34:35], 0, v[12:13]
	v_mov_b32_e32 v7, v11
	v_mov_b32_e32 v5, v2
	v_add_co_u32_e32 v12, vcc, s6, v12
	v_pk_add_f32 v[14:15], v[4:5], v[6:7] neg_lo:[0,1] neg_hi:[0,1]
	v_pk_add_f32 v[4:5], v[4:5], v[6:7]
	v_addc_co_u32_e32 v13, vcc, 0, v13, vcc
	v_pk_add_f32 v[6:7], v[4:5], v[2:3] op_sel:[1,0] op_sel_hi:[0,1] neg_lo:[0,1] neg_hi:[0,1]
	global_load_dwordx4 v[18:21], v[12:13], off offset:1024 nt
	v_pk_add_f32 v[22:23], v[10:11], v[6:7] op_sel_hi:[1,0] neg_lo:[0,1] neg_hi:[0,1]
	v_mov_b32_e32 v10, v11
	v_mov_b32_e32 v11, v5
	v_mov_b32_e32 v24, v3
	v_mov_b32_e32 v25, v6
	v_pk_add_f32 v[6:7], v[10:11], v[24:25] neg_lo:[0,1] neg_hi:[0,1]
	v_mov_b32_e32 v8, v9
	v_mov_b32_e32 v9, v2
	v_pk_add_f32 v[2:3], v[8:9], v[6:7] neg_lo:[0,1] neg_hi:[0,1]
	v_mov_b32_e32 v22, v14
	v_pk_add_f32 v[6:7], v[22:23], v[2:3]
	v_mov_b32_e32 v15, v5
	v_pk_add_f32 v[8:9], v[6:7], v[6:7] op_sel:[0,1] op_sel_hi:[1,0]
	v_cmp_neq_f32_e32 vcc, s7, v0
	v_pk_add_f32 v[4:5], v[4:5], v[8:9] op_sel:[1,0] op_sel_hi:[0,1]
	v_mov_b32_e32 v7, v4
	v_pk_add_f32 v[10:11], v[6:7], v[14:15] neg_lo:[0,1] neg_hi:[0,1]
	v_mov_b32_e32 v3, v8
	v_sub_f32_e32 v1, v6, v10
	v_pk_add_f32 v[2:3], v[2:3], v[10:11] neg_lo:[0,1] neg_hi:[0,1]
	v_sub_f32_e32 v1, v14, v1
	v_add_f32_e32 v1, v2, v1
	v_add_f32_e32 v1, v1, v3
	v_add_f32_e32 v1, v4, v1
	v_cndmask_b32_e32 v1, v227, v1, vcc
	v_cmp_lt_f32_e64 vcc, |v0|, s17
	global_load_dwordx4 v[22:25], v[12:13], off offset:1536 nt
	v_cndmask_b32_e32 v32, v1, v0, vcc
	v_add_u32_e32 v0, 0x200, v206
	v_ashrrev_i32_e32 v37, 3, v0
	v_add_u32_e32 v0, s13, v37
	v_ashrrev_i32_e32 v1, 31, v0
	v_lshlrev_b64 v[0:1], 13, v[0:1]
	v_lshl_add_u64 v[0:1], v[34:35], 0, v[0:1]
	v_add_co_u32_e32 v0, vcc, s6, v0
	s_nop 0
	v_addc_co_u32_e32 v1, vcc, 0, v1, vcc
	global_load_dwordx4 v[26:29], v[0:1], off offset:1024 nt
	global_load_dwordx4 v[38:41], v[0:1], off offset:1536 nt
	v_add_u32_e32 v0, s9, v31
	v_ashrrev_i32_e32 v1, 31, v0
	v_lshlrev_b64 v[0:1], 13, v[0:1]
	v_lshl_add_u64 v[0:1], v[34:35], 0, v[0:1]
	v_add_co_u32_e32 v0, vcc, s6, v0
	s_nop 0
	v_addc_co_u32_e32 v1, vcc, 0, v1, vcc
	global_load_dwordx4 v[12:15], v[0:1], off offset:1024 nt
	global_load_dwordx4 v[8:11], v[0:1], off offset:1536 nt
	v_add_u32_e32 v0, s9, v37
	v_ashrrev_i32_e32 v1, 31, v0
	v_lshlrev_b64 v[0:1], 13, v[0:1]
	v_lshl_add_u64 v[0:1], v[34:35], 0, v[0:1]
	v_add_co_u32_e32 v0, vcc, s6, v0
	v_lshrrev_b32_e32 v34, 4, v207
	s_nop 0
	v_addc_co_u32_e32 v1, vcc, 0, v1, vcc
	global_load_dwordx4 v[4:7], v[0:1], off offset:1024 nt
	s_nop 0
	global_load_dwordx4 v[0:3], v[0:1], off offset:1536 nt
	s_waitcnt vmcnt(7)
	v_lshlrev_b32_e32 v46, 16, v20
	v_and_b32_e32 v47, 0xffff0000, v20
	v_cvt_f32_i32_e32 v20, v31
	v_mul_f32_e32 v35, 0xbfb8aa3b, v17
	v_bfe_u32 v17, v206, 2, 2
	v_lshl_or_b32 v76, v34, 3, v17
	v_sub_u32_e32 v17, 0x7f, v31
	v_cvt_f32_i32_e32 v17, v17
	v_lshlrev_b32_e32 v42, 16, v18
	v_and_b32_e32 v43, 0xffff0000, v18
	v_mul_f32_e32 v32, 0xbfb8aa3b, v32
	v_mul_f32_e32 v16, v35, v17
	v_exp_f32_e32 v103, v16
	v_lshlrev_b32_e32 v44, 16, v19
	v_and_b32_e32 v45, 0xffff0000, v19
	v_mul_f32_e32 v20, v32, v20
	v_mul_f32_e32 v16, v103, v42
	v_mul_f32_e32 v17, v103, v43
	v_cvt_pk_bf16_f32 v16, v16, v17
	v_mul_f32_e32 v17, v103, v44
	v_mul_f32_e32 v18, v103, v45
	v_cvt_pk_bf16_f32 v17, v17, v18
	v_mul_f32_e32 v18, v103, v46
	v_mul_f32_e32 v19, v103, v47
	v_lshlrev_b32_e32 v48, 16, v21
	v_and_b32_e32 v49, 0xffff0000, v21
	v_exp_f32_e32 v104, v20
	v_cvt_pk_bf16_f32 v18, v18, v19
	v_mul_f32_e32 v19, v103, v48
	v_mul_f32_e32 v21, v103, v49
	s_movk_i32 s9, 0x50
	v_cvt_pk_bf16_f32 v19, v19, v21
	v_mad_u64_u32 v[20:21], s[6:7], v31, s9, v[30:31]
	v_lshl_add_u32 v105, v20, 1, 0
	s_barrier
	ds_write_b128 v105, v[16:19]
	v_mul_f32_e32 v16, v104, v42
	v_mul_f32_e32 v17, v104, v43
	v_cvt_pk_bf16_f32 v16, v16, v17
	v_mul_f32_e32 v17, v104, v44
	v_mul_f32_e32 v18, v104, v45
	v_cvt_pk_bf16_f32 v17, v17, v18
	v_mul_f32_e32 v18, v104, v46
	v_mul_f32_e32 v19, v104, v47
	v_cvt_pk_bf16_f32 v18, v18, v19
	v_sub_u32_e32 v19, 0x7f, v37
	v_cvt_f32_i32_e32 v20, v19
	v_mul_f32_e32 v19, v104, v48
	v_mul_f32_e32 v21, v104, v49
	v_cvt_pk_bf16_f32 v19, v19, v21
	v_mul_f32_e32 v20, v35, v20
	v_exp_f32_e32 v35, v20
	v_cvt_f32_i32_e32 v20, v37
	ds_write_b128 v105, v[16:19] offset:20480
	s_waitcnt vmcnt(6)
	ds_write_b128 v105, v[22:25] offset:40960
	v_mad_u32_u24 v62, v76, s9, v62
	v_mad_u32_u24 v87, v76, s9, v80
	v_mul_f32_e32 v20, v32, v20
	v_exp_f32_e32 v32, v20
	s_waitcnt vmcnt(5)
	v_lshlrev_b32_e32 v22, 16, v26
	v_and_b32_e32 v23, 0xffff0000, v26
	v_mul_f32_e32 v16, v35, v22
	v_mul_f32_e32 v17, v35, v23
	v_lshlrev_b32_e32 v24, 16, v27
	v_and_b32_e32 v25, 0xffff0000, v27
	v_cvt_pk_bf16_f32 v16, v16, v17
	v_mul_f32_e32 v17, v35, v24
	v_mul_f32_e32 v18, v35, v25
	v_lshlrev_b32_e32 v26, 16, v28
	v_and_b32_e32 v27, 0xffff0000, v28
	v_cvt_pk_bf16_f32 v17, v17, v18
	v_mul_f32_e32 v18, v35, v26
	v_mul_f32_e32 v19, v35, v27
	v_lshlrev_b32_e32 v28, 16, v29
	v_and_b32_e32 v29, 0xffff0000, v29
	v_cvt_pk_bf16_f32 v18, v18, v19
	v_mul_f32_e32 v19, v35, v28
	v_mul_f32_e32 v21, v35, v29
	v_cvt_pk_bf16_f32 v19, v19, v21
	v_mad_u64_u32 v[20:21], s[6:7], v37, s9, v[30:31]
	v_lshl_add_u32 v37, v20, 1, 0
	ds_write_b128 v37, v[16:19]
	v_mul_f32_e32 v16, v32, v22
	v_mul_f32_e32 v17, v32, v23
	v_cvt_pk_bf16_f32 v16, v16, v17
	v_mul_f32_e32 v17, v32, v24
	v_mul_f32_e32 v18, v32, v25
	v_cvt_pk_bf16_f32 v17, v17, v18
	v_mul_f32_e32 v18, v32, v26
	v_mul_f32_e32 v19, v32, v27
	v_cvt_pk_bf16_f32 v18, v18, v19
	v_mul_f32_e32 v19, v32, v28
	v_mul_f32_e32 v20, v32, v29
	v_cvt_pk_bf16_f32 v19, v19, v20
	v_readlane_b32 s6, v254, 42
	v_mov_b32_e32 v30, 0xa00
	ds_write_b128 v37, v[16:19] offset:20480
	s_waitcnt vmcnt(4)
	ds_write_b128 v37, v[38:41] offset:40960
	v_or_b32_e32 v77, s6, v86
	v_mul_u32_u24_e32 v16, 0x50, v76
	v_mad_u32_u24 v46, v76, s9, v30
	v_mad_u32_u24 v17, v76, s9, v77
	v_or_b32_e32 v16, v16, v86
	v_add_u32_e32 v30, v46, v77
	v_or_b32_e32 v46, v46, v86
	v_add_u32_e32 v63, v62, v77
	v_or_b32_e32 v62, v62, v86
	v_or_b32_e32 v86, v87, v86
	v_lshl_add_u32 v106, v17, 1, 0
	v_lshl_add_u32 v107, v16, 1, s72
	v_lshl_add_u32 v109, v46, 1, s72
	v_lshl_add_u32 v110, v63, 1, 0
	v_lshl_add_u32 v111, v62, 1, s72
	v_add_u32_e32 v76, v87, v77
	v_lshl_add_u32 v113, v86, 1, s72
	s_waitcnt lgkmcnt(0)
	s_barrier
	ds_read_b64_tr_b16 v[16:17], v106 offset:40960
	ds_read_b64_tr_b16 v[18:19], v106 offset:41600
	ds_read_b64_tr_b16 v[20:21], v107
	ds_read_b64_tr_b16 v[24:25], v107 offset:32
	ds_read_b64_tr_b16 v[22:23], v107 offset:640
	ds_read_b64_tr_b16 v[26:27], v107 offset:672
	ds_read_b64_tr_b16 v[28:29], v107 offset:64
	ds_read_b64_tr_b16 v[38:39], v107 offset:96
	v_lshl_add_u32 v108, v30, 1, 0
	ds_read_b64_tr_b16 v[30:31], v107 offset:704
	ds_read_b64_tr_b16 v[40:41], v107 offset:736
	ds_read_b64_tr_b16 v[42:43], v108 offset:40960
	ds_read_b64_tr_b16 v[44:45], v108 offset:41600
	ds_read_b64_tr_b16 v[46:47], v109
	ds_read_b64_tr_b16 v[50:51], v109 offset:32
	ds_read_b64_tr_b16 v[54:55], v109 offset:64
	ds_read_b64_tr_b16 v[58:59], v109 offset:96
	ds_read_b64_tr_b16 v[48:49], v109 offset:640
	ds_read_b64_tr_b16 v[52:53], v109 offset:672
	ds_read_b64_tr_b16 v[56:57], v109 offset:704
	ds_read_b64_tr_b16 v[60:61], v109 offset:736
	ds_read_b64_tr_b16 v[62:63], v110 offset:40960
	ds_read_b64_tr_b16 v[64:65], v110 offset:41600
	ds_read_b64_tr_b16 v[66:67], v111
	ds_read_b64_tr_b16 v[70:71], v111 offset:32
	ds_read_b64_tr_b16 v[68:69], v111 offset:640
	ds_read_b64_tr_b16 v[72:73], v111 offset:672
	ds_read_b64_tr_b16 v[74:75], v111 offset:64
	ds_read_b64_tr_b16 v[78:79], v111 offset:96
	v_lshl_add_u32 v112, v76, 1, 0
	ds_read_b64_tr_b16 v[76:77], v111 offset:704
	ds_read_b64_tr_b16 v[80:81], v111 offset:736
	ds_read_b64_tr_b16 v[82:83], v112 offset:40960
	ds_read_b64_tr_b16 v[84:85], v112 offset:41600
	ds_read_b64_tr_b16 v[86:87], v113
	ds_read_b64_tr_b16 v[90:91], v113 offset:32
	ds_read_b64_tr_b16 v[94:95], v113 offset:64
	ds_read_b64_tr_b16 v[98:99], v113 offset:96
	ds_read_b64_tr_b16 v[88:89], v113 offset:640
	ds_read_b64_tr_b16 v[92:93], v113 offset:672
	ds_read_b64_tr_b16 v[96:97], v113 offset:704
	ds_read_b64_tr_b16 v[100:101], v113 offset:736
	v_lshlrev_b32_e32 v34, 10, v34
	s_waitcnt lgkmcnt(14)
	v_mfma_f32_16x16x32_bf16 v[20:23], v[16:19], v[20:23], 0
	v_readlane_b32 s6, v254, 40
	s_lshl_b32 s0, s0, 13
	v_readlane_b32 s7, v254, 55
	v_mfma_f32_16x16x32_bf16 v[24:27], v[16:19], v[24:27], 0
	v_add3_u32 v34, s6, v34, v102
	v_add_u32_e32 v34, 0xf000, v34
	s_add_i32 s0, s0, s7
	v_mfma_f32_16x16x32_bf16 v[28:31], v[16:19], v[28:31], 0
	v_readlane_b32 s20, v254, 19
	v_readlane_b32 s21, v254, 20
	v_readlane_b32 s22, v254, 21
	v_mfma_f32_16x16x32_bf16 v[16:19], v[16:19], v[38:41], 0
	v_readlane_b32 s23, v254, 22
	v_mfma_f32_16x16x32_bf16 v[20:23], v[42:45], v[46:49], v[20:23]
	v_mfma_f32_16x16x32_bf16 v[24:27], v[42:45], v[50:53], v[24:27]
	v_mfma_f32_16x16x32_bf16 v[28:31], v[42:45], v[54:57], v[28:31]
	v_mfma_f32_16x16x32_bf16 v[16:19], v[42:45], v[58:61], v[16:19]
	v_mfma_f32_16x16x32_bf16 v[20:23], v[62:65], v[66:69], v[20:23]
	v_mfma_f32_16x16x32_bf16 v[24:27], v[62:65], v[70:73], v[24:27]
	s_waitcnt lgkmcnt(11)
	v_mfma_f32_16x16x32_bf16 v[28:31], v[62:65], v[74:77], v[28:31]
	s_waitcnt lgkmcnt(10)
	v_mfma_f32_16x16x32_bf16 v[16:19], v[62:65], v[78:81], v[16:19]
	s_waitcnt lgkmcnt(3)
	v_mfma_f32_16x16x32_bf16 v[20:23], v[82:85], v[86:89], v[20:23]
	v_lshl_add_u32 v87, v207, 4, s6
	v_lshlrev_b32_e32 v86, 2, v207
	v_or_b32_e32 v38, s0, v86
	s_waitcnt lgkmcnt(2)
	v_mfma_f32_16x16x32_bf16 v[24:27], v[82:85], v[90:93], v[24:27]
	v_lshlrev_b32_e32 v38, 2, v38
	s_waitcnt lgkmcnt(1)
	v_mfma_f32_16x16x32_bf16 v[28:31], v[82:85], v[94:97], v[28:31]
	s_waitcnt lgkmcnt(0)
	v_mfma_f32_16x16x32_bf16 v[16:19], v[82:85], v[98:101], v[16:19]
	s_nop 2
	ds_write2_b32 v34, v20, v24 offset1:16
	ds_write2_b32 v34, v21, v25 offset0:64 offset1:80
	ds_write2_b32 v34, v22, v26 offset0:128 offset1:144
	ds_write2_b32 v34, v23, v27 offset0:192 offset1:208
	s_nop 0
	ds_write2_b32 v34, v28, v16 offset0:32 offset1:48
	ds_write2_b32 v34, v29, v17 offset0:96 offset1:112
	ds_write2_b32 v34, v30, v18 offset0:160 offset1:176
	ds_write2_b32 v34, v31, v19 offset0:224 offset1:240
	s_waitcnt lgkmcnt(0)
	ds_read_b128 v[16:19], v87 offset:61440
	ds_read_b128 v[20:23], v87 offset:62464
	ds_read_b128 v[24:27], v87 offset:63488
	ds_read_b128 v[28:31], v87 offset:64512
	s_waitcnt lgkmcnt(3)
	buffer_store_dwordx4 v[16:19], v38, s[20:23], 0 offen sc1
	s_waitcnt lgkmcnt(2)
	buffer_store_dwordx4 v[20:23], v38, s[20:23], 0 offen offset:1024 sc1
	s_waitcnt lgkmcnt(1)
	buffer_store_dwordx4 v[24:27], v38, s[20:23], 0 offen offset:2048 sc1
	s_waitcnt lgkmcnt(0)
	buffer_store_dwordx4 v[28:31], v38, s[20:23], 0 offen offset:3072 sc1
	s_waitcnt vmcnt(7)
	v_lshlrev_b32_e32 v16, 16, v12
	v_and_b32_e32 v18, 0xffff0000, v12
	v_mul_f32_e32 v17, v103, v16
	v_mul_f32_e32 v12, v103, v18
	v_cvt_pk_bf16_f32 v12, v17, v12
	v_lshlrev_b32_e32 v17, 16, v13
	v_and_b32_e32 v20, 0xffff0000, v13
	v_mul_f32_e32 v19, v103, v17
	v_mul_f32_e32 v13, v103, v20
	v_cvt_pk_bf16_f32 v13, v19, v13
	v_lshlrev_b32_e32 v19, 16, v14
	v_and_b32_e32 v22, 0xffff0000, v14
	v_mul_f32_e32 v21, v103, v19
	v_mul_f32_e32 v14, v103, v22
	v_cvt_pk_bf16_f32 v14, v21, v14
	v_lshlrev_b32_e32 v21, 16, v15
	v_and_b32_e32 v24, 0xffff0000, v15
	v_mul_f32_e32 v23, v103, v21
	v_mul_f32_e32 v15, v103, v24
	v_cvt_pk_bf16_f32 v15, v23, v15
	s_waitcnt lgkmcnt(0)
	s_barrier
	ds_write_b128 v105, v[12:15]
	v_mul_f32_e32 v12, v104, v16
	v_mul_f32_e32 v13, v104, v18
	v_cvt_pk_bf16_f32 v12, v12, v13
	v_mul_f32_e32 v13, v104, v17
	v_mul_f32_e32 v14, v104, v20
	v_cvt_pk_bf16_f32 v13, v13, v14
	v_mul_f32_e32 v14, v104, v19
	v_mul_f32_e32 v15, v104, v22
	v_cvt_pk_bf16_f32 v14, v14, v15
	v_mul_f32_e32 v15, v104, v21
	v_mul_f32_e32 v16, v104, v24
	v_cvt_pk_bf16_f32 v15, v15, v16
	ds_write_b128 v105, v[12:15] offset:20480
	s_waitcnt vmcnt(6)
	ds_write_b128 v105, v[8:11] offset:40960
	s_waitcnt vmcnt(5)
	v_lshlrev_b32_e32 v8, 16, v4
	v_and_b32_e32 v10, 0xffff0000, v4
	v_mul_f32_e32 v9, v35, v8
	v_mul_f32_e32 v4, v35, v10
	v_cvt_pk_bf16_f32 v4, v9, v4
	v_lshlrev_b32_e32 v9, 16, v5
	v_and_b32_e32 v12, 0xffff0000, v5
	v_mul_f32_e32 v11, v35, v9
	v_mul_f32_e32 v5, v35, v12
	v_cvt_pk_bf16_f32 v5, v11, v5
	v_lshlrev_b32_e32 v11, 16, v6
	v_and_b32_e32 v14, 0xffff0000, v6
	v_mul_f32_e32 v13, v35, v11
	v_mul_f32_e32 v6, v35, v14
	v_cvt_pk_bf16_f32 v6, v13, v6
	v_lshlrev_b32_e32 v13, 16, v7
	v_and_b32_e32 v16, 0xffff0000, v7
	v_mul_f32_e32 v15, v35, v13
	v_mul_f32_e32 v7, v35, v16
	v_cvt_pk_bf16_f32 v7, v15, v7
	ds_write_b128 v37, v[4:7]
	v_mul_f32_e32 v4, v32, v8
	v_mul_f32_e32 v5, v32, v10
	v_cvt_pk_bf16_f32 v4, v4, v5
	v_mul_f32_e32 v5, v32, v9
	v_mul_f32_e32 v6, v32, v12
	v_cvt_pk_bf16_f32 v5, v5, v6
	v_mul_f32_e32 v6, v32, v11
	v_mul_f32_e32 v7, v32, v14
	v_cvt_pk_bf16_f32 v6, v6, v7
	v_mul_f32_e32 v7, v32, v13
	v_mul_f32_e32 v8, v32, v16
	v_cvt_pk_bf16_f32 v7, v7, v8
	ds_write_b128 v37, v[4:7] offset:20480
	s_waitcnt vmcnt(4)
	ds_write_b128 v37, v[0:3] offset:40960
	s_waitcnt lgkmcnt(0)
	s_barrier
	ds_read_b64_tr_b16 v[0:1], v106 offset:40960
	ds_read_b64_tr_b16 v[2:3], v106 offset:41600
	ds_read_b64_tr_b16 v[4:5], v107
	ds_read_b64_tr_b16 v[8:9], v107 offset:32
	ds_read_b64_tr_b16 v[6:7], v107 offset:640
	ds_read_b64_tr_b16 v[10:11], v107 offset:672
	ds_read_b64_tr_b16 v[12:13], v107 offset:64
	ds_read_b64_tr_b16 v[16:17], v107 offset:96
	ds_read_b64_tr_b16 v[14:15], v107 offset:704
	ds_read_b64_tr_b16 v[18:19], v107 offset:736
	ds_read_b64_tr_b16 v[20:21], v108 offset:40960
	ds_read_b64_tr_b16 v[22:23], v108 offset:41600
	ds_read_b64_tr_b16 v[24:25], v109
	ds_read_b64_tr_b16 v[28:29], v109 offset:32
	ds_read_b64_tr_b16 v[38:39], v109 offset:64
	ds_read_b64_tr_b16 v[42:43], v109 offset:96
	ds_read_b64_tr_b16 v[26:27], v109 offset:640
	ds_read_b64_tr_b16 v[30:31], v109 offset:672
	ds_read_b64_tr_b16 v[40:41], v109 offset:704
	ds_read_b64_tr_b16 v[44:45], v109 offset:736
	ds_read_b64_tr_b16 v[46:47], v110 offset:40960
	ds_read_b64_tr_b16 v[48:49], v110 offset:41600
	ds_read_b64_tr_b16 v[50:51], v111
	ds_read_b64_tr_b16 v[54:55], v111 offset:32
	ds_read_b64_tr_b16 v[52:53], v111 offset:640
	ds_read_b64_tr_b16 v[56:57], v111 offset:672
	ds_read_b64_tr_b16 v[58:59], v111 offset:64
	ds_read_b64_tr_b16 v[62:63], v111 offset:96
	ds_read_b64_tr_b16 v[60:61], v111 offset:704
	ds_read_b64_tr_b16 v[64:65], v111 offset:736
	ds_read_b64_tr_b16 v[66:67], v112 offset:40960
	ds_read_b64_tr_b16 v[68:69], v112 offset:41600
	ds_read_b64_tr_b16 v[70:71], v113
	ds_read_b64_tr_b16 v[74:75], v113 offset:32
	ds_read_b64_tr_b16 v[78:79], v113 offset:64
	ds_read_b64_tr_b16 v[82:83], v113 offset:96
	ds_read_b64_tr_b16 v[72:73], v113 offset:640
	ds_read_b64_tr_b16 v[76:77], v113 offset:672
	ds_read_b64_tr_b16 v[80:81], v113 offset:704
	ds_read_b64_tr_b16 v[84:85], v113 offset:736
	s_waitcnt lgkmcnt(14)
	v_mfma_f32_16x16x32_bf16 v[4:7], v[0:3], v[4:7], 0
	s_lshl_b32 s0, s8, 13
	s_add_i32 s0, s0, s7
	s_lshl_b32 s6, s5, 8
	v_mfma_f32_16x16x32_bf16 v[8:11], v[0:3], v[8:11], 0
	s_ashr_i32 s7, s6, 31
	s_lshl_b64 s[6:7], s[6:7], 2
	v_mfma_f32_16x16x32_bf16 v[12:15], v[0:3], v[12:15], 0
	v_mfma_f32_16x16x32_bf16 v[0:3], v[0:3], v[16:19], 0
	v_or_b32_e32 v16, s0, v86
	v_lshlrev_b32_e32 v16, 2, v16
	s_add_u32 s0, s48, s6
	v_mfma_f32_16x16x32_bf16 v[4:7], v[20:23], v[24:27], v[4:7]
	s_addc_u32 s6, s49, s7
	s_add_u32 s76, s0, 0x53c0
	s_addc_u32 s77, s6, 0
	v_mfma_f32_16x16x32_bf16 v[8:11], v[20:23], v[28:31], v[8:11]
	v_mfma_f32_16x16x32_bf16 v[12:15], v[20:23], v[38:41], v[12:15]
	v_mfma_f32_16x16x32_bf16 v[0:3], v[20:23], v[42:45], v[0:3]
	v_mfma_f32_16x16x32_bf16 v[4:7], v[46:49], v[50:53], v[4:7]
	v_mfma_f32_16x16x32_bf16 v[8:11], v[46:49], v[54:57], v[8:11]
	s_waitcnt lgkmcnt(11)
	v_mfma_f32_16x16x32_bf16 v[12:15], v[46:49], v[58:61], v[12:15]
	s_waitcnt lgkmcnt(10)
	v_mfma_f32_16x16x32_bf16 v[0:3], v[46:49], v[62:65], v[0:3]
	s_waitcnt lgkmcnt(3)
	v_mfma_f32_16x16x32_bf16 v[4:7], v[66:69], v[70:73], v[4:7]
	s_waitcnt lgkmcnt(2)
	v_mfma_f32_16x16x32_bf16 v[8:11], v[66:69], v[74:77], v[8:11]
	s_waitcnt lgkmcnt(1)
	v_mfma_f32_16x16x32_bf16 v[12:15], v[66:69], v[78:81], v[12:15]
	s_waitcnt lgkmcnt(0)
	v_mfma_f32_16x16x32_bf16 v[0:3], v[66:69], v[82:85], v[0:3]
	s_nop 3
	ds_write2_b32 v34, v4, v8 offset1:16
	ds_write2_b32 v34, v5, v9 offset0:64 offset1:80
	ds_write2_b32 v34, v6, v10 offset0:128 offset1:144
	ds_write2_b32 v34, v7, v11 offset0:192 offset1:208
	ds_write2_b32 v34, v12, v0 offset0:32 offset1:48
	ds_write2_b32 v34, v13, v1 offset0:96 offset1:112
	ds_write2_b32 v34, v14, v2 offset0:160 offset1:176
	ds_write2_b32 v34, v15, v3 offset0:224 offset1:240
	s_waitcnt lgkmcnt(0)
	ds_read_b128 v[0:3], v87 offset:61440
	ds_read_b128 v[4:7], v87 offset:62464
	ds_read_b128 v[8:11], v87 offset:63488
	ds_read_b128 v[12:15], v87 offset:64512
	s_waitcnt lgkmcnt(3)
	buffer_store_dwordx4 v[0:3], v16, s[20:23], 0 offen sc1
	s_waitcnt lgkmcnt(2)
	buffer_store_dwordx4 v[4:7], v16, s[20:23], 0 offen offset:1024 sc1
	s_waitcnt lgkmcnt(1)
	buffer_store_dwordx4 v[8:11], v16, s[20:23], 0 offen offset:2048 sc1
	s_waitcnt lgkmcnt(0)
	buffer_store_dwordx4 v[12:15], v16, s[20:23], 0 offen offset:3072 sc1
	s_waitcnt lgkmcnt(0)

.LBB0_650:
	s_mov_b64 s[10:11], 0
	s_and_b64 vcc, exec, s[6:7]
	s_cbranch_vccz .LBB0_652
	s_lshl_b32 s0, s12, 6
	v_ashrrev_i32_e32 v0, 3, v206
	s_addk_i32 s0, 0x8000
	v_and_b32_e32 v0, -4, v0
	v_add_u32_e32 v34, s0, v0
	v_lshlrev_b32_e32 v0, 3, v206
	s_movk_i32 s13, 0x4000
	v_and_b32_e32 v18, 0xf8, v0
	v_cmp_gt_i32_e32 vcc, s13, v34
	v_bfrev_b32_e32 v0, 0.5
	v_mov_b32_e32 v1, 0xffc
	v_cndmask_b32_e32 v0, v0, v1, vcc
	v_ashrrev_i32_e32 v35, 31, v34
	v_and_b32_e32 v2, v0, v34
	v_lshlrev_b64 v[0:1], 13, v[34:35]
	v_lshl_add_u64 v[0:1], s[70:71], 0, v[0:1]
	v_lshlrev_b32_e32 v32, 1, v18
	v_lshl_add_u64 v[8:9], v[0:1], 0, v[32:33]
	s_movk_i32 s0, 0x2000
	v_add_co_u32_e64 v10, s[8:9], s0, v8
	v_cmp_ne_u32_e64 s[6:7], 0, v2
	s_nop 0
	v_addc_co_u32_e64 v11, s[8:9], 0, v9, s[8:9]
	v_cndmask_b32_e64 v0, 0, -1, s[6:7]
	v_add_co_u32_e64 v12, s[8:9], s13, v8
	v_mov_b32_e32 v1, v0
	s_nop 0
	v_addc_co_u32_e64 v13, s[8:9], 0, v9, s[8:9]
	s_movk_i32 s0, 0x6000
	v_lshlrev_b64 v[0:1], 13, v[0:1]
	v_add_co_u32_e64 v14, s[8:9], s0, v8
	v_lshl_add_u64 v[0:1], v[8:9], 0, v[0:1]
	s_nop 0
	v_addc_co_u32_e64 v15, s[8:9], 0, v9, s[8:9]
	v_cndmask_b32_e64 v122, 0, 1.0, s[6:7]
	s_lshl_b32 s6, s5, 8
	global_load_dwordx4 v[116:119], v[0:1], off offset:2560 nt
	global_load_dwordx4 v[98:101], v[0:1], off offset:3584 nt
	global_load_dwordx4 v[86:89], v[8:9], off offset:2560 nt
	global_load_dwordx4 v[90:93], v[8:9], off offset:3584 nt
	v_or_b32_e32 v0, 3, v2
	v_mov_b32_e32 v1, 0xff
	v_mov_b32_e32 v2, 0xfff
	s_ashr_i32 s7, s6, 31
	s_mul_i32 s8, s5, 0x300
	v_cndmask_b32_e32 v1, v1, v2, vcc
	s_ashr_i32 s9, s8, 31
	s_lshl_b64 s[6:7], s[6:7], 2
	v_cmp_lt_u32_e32 vcc, v0, v1
	v_mov_b32_e32 v0, 0x6000
	v_mov_b32_e32 v1, 0x8000
	s_add_u32 s16, s40, s6
	s_movk_i32 s0, 0x1000
	v_cndmask_b32_e32 v0, v0, v1, vcc
	v_mov_b32_e32 v1, v33
	s_addc_u32 s17, s41, s7
	v_add_co_u32_e64 v16, s[6:7], s0, v8
	v_lshl_add_u64 v[0:1], v[8:9], 0, v[0:1]
	s_nop 0
	v_addc_co_u32_e64 v17, s[6:7], 0, v9, s[6:7]
	s_movk_i32 s0, 0x3000
	global_load_dwordx4 v[102:105], v[10:11], off offset:2560 nt
	global_load_dwordx4 v[94:97], v[10:11], off offset:3584 nt
	global_load_dwordx4 v[74:77], v[12:13], off offset:2560 nt
	global_load_dwordx4 v[70:73], v[12:13], off offset:3584 nt
	global_load_dwordx4 v[58:61], v[14:15], off offset:2560 nt
	global_load_dwordx4 v[54:57], v[14:15], off offset:3584 nt
	global_load_dwordx4 v[4:7], v[0:1], off offset:2560 nt
	s_nop 0
	global_load_dwordx4 v[0:3], v[0:1], off offset:3584 nt
	v_lshlrev_b32_e32 v35, 2, v18
	global_load_dwordx4 v[110:113], v[8:9], off offset:3072 nt
	global_load_dwordx4 v[106:109], v[16:17], off nt
	global_load_dwordx4 v[82:85], v[10:11], off offset:3072 nt
	v_add_co_u32_e64 v10, s[6:7], s0, v8
	s_movk_i32 s0, 0x5000
	s_nop 0
	v_addc_co_u32_e64 v11, s[6:7], 0, v9, s[6:7]
	global_load_dwordx4 v[78:81], v[10:11], off nt
	global_load_dwordx4 v[66:69], v[12:13], off offset:3072 nt
	v_add_co_u32_e64 v10, s[6:7], s0, v8
	s_movk_i32 s0, 0x7000
	s_nop 0
	v_addc_co_u32_e64 v11, s[6:7], 0, v9, s[6:7]
	v_add_co_u32_e64 v8, s[6:7], s0, v8
	global_load_dwordx4 v[62:65], v[10:11], off nt
	global_load_dwordx4 v[28:31], v[14:15], off offset:3072 nt
	v_addc_co_u32_e64 v9, s[6:7], 0, v9, s[6:7]
	s_lshl_b64 s[6:7], s[8:9], 2
	s_add_u32 s6, s38, s6
	global_load_dwordx4 v[24:27], v[8:9], off nt
	s_addc_u32 s7, s39, s7
	global_load_dwordx4 v[8:11], v35, s[16:17] offset:16 nt
	global_load_dwordx4 v[38:41], v35, s[16:17] nt
	global_load_dwordx4 v[12:15], v35, s[6:7] offset:16 nt
	global_load_dwordx4 v[42:45], v35, s[6:7] nt
	global_load_dwordx4 v[16:19], v35, s[6:7] offset:1040 nt
	global_load_dwordx4 v[46:49], v35, s[6:7] offset:1024 nt
	global_load_dwordx4 v[20:23], v35, s[6:7] offset:2064 nt
	global_load_dwordx4 v[50:53], v35, s[6:7] offset:2048 nt
	v_cndmask_b32_e64 v114, 0, 1.0, vcc
	s_waitcnt vmcnt(14)
	v_lshlrev_b32_e32 v132, 16, v106
	v_mul_f32_e32 v35, 0xbfb8aa3b, v132
	v_exp_f32_e32 v35, v35
	v_and_b32_e32 v133, 0xffff0000, v106
	v_lshlrev_b32_e32 v120, 16, v116
	v_and_b32_e32 v121, 0xffff0000, v116
	v_add_f32_e32 v35, 1.0, v35
	v_rcp_f32_e32 v134, v35
	v_mul_f32_e32 v35, 0xbfb8aa3b, v133
	v_exp_f32_e32 v35, v35
	v_lshlrev_b32_e32 v128, 16, v117
	v_and_b32_e32 v129, 0xffff0000, v117
	v_lshlrev_b32_e32 v126, 16, v118
	v_and_b32_e32 v127, 0xffff0000, v118
	v_lshlrev_b32_e32 v124, 16, v119
	v_and_b32_e32 v125, 0xffff0000, v119
	v_lshlrev_b32_e32 v116, 16, v98
	v_and_b32_e32 v117, 0xffff0000, v98
	v_pk_mul_f32 v[118:119], v[122:123], v[120:121] op_sel_hi:[0,1]
	v_pk_mul_f32 v[120:121], v[118:119], v[116:117]
	v_lshlrev_b32_e32 v116, 16, v86
	v_and_b32_e32 v117, 0xffff0000, v86
	v_lshlrev_b32_e32 v118, 16, v90
	v_and_b32_e32 v119, 0xffff0000, v90
	v_pk_mul_f32 v[118:119], v[116:117], v[118:119]
	v_add_f32_e32 v35, 1.0, v35
	v_lshlrev_b32_e32 v116, 16, v102
	v_and_b32_e32 v117, 0xffff0000, v102
	v_lshlrev_b32_e32 v130, 16, v94
	v_and_b32_e32 v131, 0xffff0000, v94
	s_waitcnt vmcnt(2)
	v_pk_mul_f32 v[136:137], v[118:119], v[46:47]
	v_rcp_f32_e32 v135, v35
	v_pk_mul_f32 v[116:117], v[116:117], v[130:131]
	v_pk_fma_f32 v[120:121], v[120:121], v[42:43], v[136:137]
	v_lshlrev_b32_e32 v102, 16, v107
	s_waitcnt vmcnt(0)
	v_pk_fma_f32 v[120:121], v[116:117], v[50:51], v[120:121]
	v_lshlrev_b32_e32 v130, 16, v110
	v_and_b32_e32 v131, 0xffff0000, v110
	v_pk_add_f32 v[120:121], v[38:39], v[120:121]
	v_mul_f32_e32 v35, 0xbfb8aa3b, v102
	v_pk_mul_f32 v[120:121], v[120:121], v[130:131]
	v_pk_mul_f32 v[130:131], v[134:135], v[132:133]
	v_exp_f32_e32 v35, v35
	v_pk_mul_f32 v[120:121], v[130:131], v[120:121]
	v_lshlrev_b32_e32 v98, 16, v99
	v_cvt_pk_bf16_f32 v86, v120, v121
	v_and_b32_e32 v99, 0xffff0000, v99
	v_pk_mul_f32 v[120:121], v[122:123], v[128:129] op_sel_hi:[0,1]
	v_pk_mul_f32 v[98:99], v[120:121], v[98:99]
	v_lshlrev_b32_e32 v120, 16, v87
	v_and_b32_e32 v121, 0xffff0000, v87
	v_lshlrev_b32_e32 v90, 16, v91
	v_and_b32_e32 v91, 0xffff0000, v91
	v_pk_mul_f32 v[120:121], v[120:121], v[90:91]
	v_lshlrev_b32_e32 v90, 16, v103
	v_and_b32_e32 v91, 0xffff0000, v103
	v_and_b32_e32 v103, 0xffff0000, v107
	v_add_f32_e32 v35, 1.0, v35
	v_rcp_f32_e32 v106, v35
	v_mul_f32_e32 v35, 0xbfb8aa3b, v103
	v_exp_f32_e32 v35, v35
	v_lshlrev_b32_e32 v94, 16, v95
	v_and_b32_e32 v95, 0xffff0000, v95
	v_pk_mul_f32 v[94:95], v[90:91], v[94:95]
	v_lshlrev_b32_e32 v90, 16, v111
	v_and_b32_e32 v91, 0xffff0000, v111
	v_pk_mul_f32 v[110:111], v[120:121], v[48:49]
	v_add_f32_e32 v35, 1.0, v35
	v_pk_fma_f32 v[98:99], v[98:99], v[44:45], v[110:111]
	v_lshlrev_b32_e32 v110, 16, v108
	v_rcp_f32_e32 v107, v35
	v_mul_f32_e32 v35, 0xbfb8aa3b, v110
	v_exp_f32_e32 v35, v35
	v_pk_fma_f32 v[98:99], v[94:95], v[52:53], v[98:99]
	v_and_b32_e32 v111, 0xffff0000, v108
	v_pk_add_f32 v[98:99], v[40:41], v[98:99]
	v_add_f32_e32 v35, 1.0, v35
	v_pk_mul_f32 v[90:91], v[98:99], v[90:91]
	v_pk_mul_f32 v[98:99], v[106:107], v[102:103]
	v_lshlrev_b32_e32 v102, 16, v92
	v_pk_mul_f32 v[90:91], v[98:99], v[90:91]
	v_pk_mul_f32 v[98:99], v[122:123], v[126:127] op_sel_hi:[0,1]
	v_rcp_f32_e32 v126, v35
	v_mul_f32_e32 v35, 0xbfb8aa3b, v111
	v_exp_f32_e32 v35, v35
	v_cvt_pk_bf16_f32 v87, v90, v91
	v_lshlrev_b32_e32 v90, 16, v100
	v_and_b32_e32 v91, 0xffff0000, v100
	v_pk_mul_f32 v[90:91], v[98:99], v[90:91]
	v_lshlrev_b32_e32 v98, 16, v88
	v_and_b32_e32 v99, 0xffff0000, v88
	v_and_b32_e32 v103, 0xffff0000, v92
	v_pk_mul_f32 v[102:103], v[98:99], v[102:103]
	v_add_f32_e32 v35, 1.0, v35
	v_lshlrev_b32_e32 v98, 16, v104
	v_and_b32_e32 v99, 0xffff0000, v104
	v_lshlrev_b32_e32 v106, 16, v96
	v_and_b32_e32 v107, 0xffff0000, v96
	v_pk_mul_f32 v[128:129], v[102:103], v[16:17]
	v_rcp_f32_e32 v127, v35
	v_pk_mul_f32 v[98:99], v[98:99], v[106:107]
	v_pk_fma_f32 v[90:91], v[90:91], v[12:13], v[128:129]
	v_lshlrev_b32_e32 v104, 16, v109
	v_pk_fma_f32 v[90:91], v[98:99], v[20:21], v[90:91]
	v_lshlrev_b32_e32 v106, 16, v112
	v_and_b32_e32 v107, 0xffff0000, v112
	v_pk_add_f32 v[90:91], v[8:9], v[90:91]
	v_mul_f32_e32 v35, 0xbfb8aa3b, v104
	v_pk_mul_f32 v[90:91], v[90:91], v[106:107]
	v_pk_mul_f32 v[106:107], v[126:127], v[110:111]
	v_exp_f32_e32 v35, v35
	v_pk_mul_f32 v[90:91], v[106:107], v[90:91]
	v_lshlrev_b32_e32 v92, 16, v93
	v_cvt_pk_bf16_f32 v88, v90, v91
	v_lshlrev_b32_e32 v90, 16, v101
	v_and_b32_e32 v91, 0xffff0000, v101
	v_pk_mul_f32 v[100:101], v[122:123], v[124:125] op_sel_hi:[0,1]
	v_pk_mul_f32 v[90:91], v[100:101], v[90:91]
	v_lshlrev_b32_e32 v100, 16, v89
	v_and_b32_e32 v101, 0xffff0000, v89
	v_and_b32_e32 v93, 0xffff0000, v93
	v_pk_mul_f32 v[100:101], v[100:101], v[92:93]
	v_lshlrev_b32_e32 v92, 16, v105
	v_and_b32_e32 v93, 0xffff0000, v105
	v_and_b32_e32 v105, 0xffff0000, v109
	v_add_f32_e32 v35, 1.0, v35
	v_rcp_f32_e32 v106, v35
	v_mul_f32_e32 v35, 0xbfb8aa3b, v105
	v_exp_f32_e32 v35, v35
	v_lshlrev_b32_e32 v96, 16, v97
	v_and_b32_e32 v97, 0xffff0000, v97
	v_pk_mul_f32 v[108:109], v[100:101], v[18:19]
	v_add_f32_e32 v35, 1.0, v35
	v_rcp_f32_e32 v107, v35
	v_pk_mul_f32 v[92:93], v[92:93], v[96:97]
	v_pk_fma_f32 v[90:91], v[90:91], v[14:15], v[108:109]
	v_lshlrev_b32_e32 v96, 16, v113
	v_pk_fma_f32 v[90:91], v[92:93], v[22:23], v[90:91]
	v_and_b32_e32 v97, 0xffff0000, v113
	v_pk_add_f32 v[90:91], v[10:11], v[90:91]
	s_mov_b32 s0, 0x18c00000
	v_pk_mul_f32 v[90:91], v[90:91], v[96:97]
	v_pk_mul_f32 v[96:97], v[106:107], v[104:105]
	v_pk_mul_f32 v[106:107], v[116:117], v[46:47]
	v_pk_mul_f32 v[90:91], v[96:97], v[90:91]
	v_pk_fma_f32 v[106:107], v[118:119], v[42:43], v[106:107]
	v_cvt_pk_bf16_f32 v89, v90, v91
	v_mov_b64_e32 v[90:91], s[48:49]
	v_mad_i64_i32 v[96:97], s[6:7], v34, s44, v[90:91]
	v_lshl_add_u64 v[96:97], v[96:97], 0, v[32:33]
	v_add_co_u32_e32 v96, vcc, s0, v96
	s_mov_b64 s[76:77], 0
	s_nop 0
	v_addc_co_u32_e32 v97, vcc, 0, v97, vcc
	global_store_dwordx4 v[96:97], v[86:89], off offset:1024
	v_lshlrev_b32_e32 v96, 16, v78
	v_mul_f32_e32 v35, 0xbfb8aa3b, v96
	v_exp_f32_e32 v35, v35
	v_and_b32_e32 v97, 0xffff0000, v78
	v_lshlrev_b32_e32 v78, 16, v79
	v_lshlrev_b32_e32 v86, 16, v74
	v_add_f32_e32 v35, 1.0, v35
	v_rcp_f32_e32 v104, v35
	v_mul_f32_e32 v35, 0xbfb8aa3b, v97
	v_exp_f32_e32 v35, v35
	v_and_b32_e32 v87, 0xffff0000, v74
	v_lshlrev_b32_e32 v88, 16, v70
	v_and_b32_e32 v89, 0xffff0000, v70
	v_add_f32_e32 v35, 1.0, v35
	v_rcp_f32_e32 v105, v35
	v_mul_f32_e32 v35, 0xbfb8aa3b, v78
	v_exp_f32_e32 v35, v35
	v_and_b32_e32 v79, 0xffff0000, v79
	v_pk_mul_f32 v[88:89], v[86:87], v[88:89]
	v_lshlrev_b32_e32 v86, 16, v82
	v_add_f32_e32 v35, 1.0, v35
	v_and_b32_e32 v87, 0xffff0000, v82
	v_rcp_f32_e32 v82, v35
	v_mul_f32_e32 v35, 0xbfb8aa3b, v79
	v_pk_fma_f32 v[106:107], v[88:89], v[50:51], v[106:107]
	v_exp_f32_e32 v35, v35
	v_pk_add_f32 v[106:107], v[38:39], v[106:107]
	v_pk_mul_f32 v[96:97], v[104:105], v[96:97]
	v_pk_mul_f32 v[86:87], v[106:107], v[86:87]
	v_lshlrev_b32_e32 v74, 16, v75
	v_pk_mul_f32 v[86:87], v[96:97], v[86:87]
	v_and_b32_e32 v75, 0xffff0000, v75
	v_cvt_pk_bf16_f32 v70, v86, v87
	v_lshlrev_b32_e32 v86, 16, v71
	v_and_b32_e32 v87, 0xffff0000, v71
	v_add_f32_e32 v35, 1.0, v35
	v_pk_mul_f32 v[86:87], v[74:75], v[86:87]
	v_lshlrev_b32_e32 v74, 16, v83
	v_and_b32_e32 v75, 0xffff0000, v83
	v_rcp_f32_e32 v83, v35
	v_pk_mul_f32 v[96:97], v[94:95], v[48:49]
	v_pk_mul_f32 v[104:105], v[98:99], v[16:17]
	v_pk_fma_f32 v[96:97], v[120:121], v[44:45], v[96:97]
	v_pk_mul_f32 v[78:79], v[82:83], v[78:79]
	v_lshlrev_b32_e32 v82, 16, v80
	v_mul_f32_e32 v35, 0xbfb8aa3b, v82
	v_exp_f32_e32 v35, v35
	v_pk_fma_f32 v[96:97], v[86:87], v[52:53], v[96:97]
	v_and_b32_e32 v83, 0xffff0000, v80
	v_pk_add_f32 v[96:97], v[40:41], v[96:97]
	v_add_f32_e32 v35, 1.0, v35
	v_pk_mul_f32 v[74:75], v[96:97], v[74:75]
	v_rcp_f32_e32 v96, v35
	v_mul_f32_e32 v35, 0xbfb8aa3b, v83
	v_exp_f32_e32 v35, v35
	v_lshlrev_b32_e32 v80, 16, v81
	v_pk_mul_f32 v[74:75], v[78:79], v[74:75]
	v_lshlrev_b32_e32 v78, 16, v72
	v_add_f32_e32 v35, 1.0, v35
	v_rcp_f32_e32 v97, v35
	v_mul_f32_e32 v35, 0xbfb8aa3b, v80
	v_cvt_pk_bf16_f32 v71, v74, v75
	v_lshlrev_b32_e32 v74, 16, v76
	v_and_b32_e32 v75, 0xffff0000, v76
	v_and_b32_e32 v79, 0xffff0000, v72
	v_exp_f32_e32 v35, v35
	v_pk_mul_f32 v[78:79], v[74:75], v[78:79]
	v_pk_fma_f32 v[102:103], v[102:103], v[12:13], v[104:105]
	v_lshlrev_b32_e32 v74, 16, v84
	v_pk_fma_f32 v[102:103], v[78:79], v[20:21], v[102:103]
	v_and_b32_e32 v75, 0xffff0000, v84
	v_pk_add_f32 v[102:103], v[8:9], v[102:103]
	v_pk_mul_f32 v[82:83], v[96:97], v[82:83]
	v_pk_mul_f32 v[74:75], v[102:103], v[74:75]
	v_and_b32_e32 v81, 0xffff0000, v81
	v_add_f32_e32 v35, 1.0, v35
	v_pk_mul_f32 v[74:75], v[82:83], v[74:75]
	v_rcp_f32_e32 v82, v35
	v_mul_f32_e32 v35, 0xbfb8aa3b, v81
	v_exp_f32_e32 v35, v35
	v_cvt_pk_bf16_f32 v72, v74, v75
	v_lshlrev_b32_e32 v74, 16, v77
	v_and_b32_e32 v75, 0xffff0000, v77
	v_lshlrev_b32_e32 v76, 16, v73
	v_and_b32_e32 v77, 0xffff0000, v73
	v_add_f32_e32 v35, 1.0, v35
	v_pk_mul_f32 v[74:75], v[74:75], v[76:77]
	v_lshlrev_b32_e32 v76, 16, v85
	v_and_b32_e32 v77, 0xffff0000, v85
	v_pk_mul_f32 v[84:85], v[92:93], v[18:19]
	v_rcp_f32_e32 v83, v35
	v_pk_fma_f32 v[84:85], v[100:101], v[14:15], v[84:85]
	v_or_b32_e32 v35, 1, v34
	v_pk_fma_f32 v[84:85], v[74:75], v[22:23], v[84:85]
	v_pk_mul_f32 v[80:81], v[82:83], v[80:81]
	v_pk_add_f32 v[84:85], v[10:11], v[84:85]
	v_pk_mul_f32 v[82:83], v[88:89], v[46:47]
	v_pk_mul_f32 v[76:77], v[84:85], v[76:77]
	v_pk_fma_f32 v[82:83], v[116:117], v[42:43], v[82:83]
	v_pk_mul_f32 v[76:77], v[80:81], v[76:77]
	s_mov_b32 s94, s18
	v_cvt_pk_bf16_f32 v73, v76, v77
	v_mad_i64_i32 v[76:77], s[6:7], v35, s44, v[90:91]
	v_lshl_add_u64 v[76:77], v[76:77], 0, v[32:33]
	v_add_co_u32_e32 v76, vcc, s0, v76
	s_nop 1
	v_addc_co_u32_e32 v77, vcc, 0, v77, vcc
	global_store_dwordx4 v[76:77], v[70:73], off offset:1024
	v_lshlrev_b32_e32 v76, 16, v62
	v_mul_f32_e32 v35, 0xbfb8aa3b, v76
	v_exp_f32_e32 v35, v35
	v_and_b32_e32 v77, 0xffff0000, v62
	v_lshlrev_b32_e32 v62, 16, v63
	v_lshlrev_b32_e32 v70, 16, v58
	v_add_f32_e32 v35, 1.0, v35
	v_rcp_f32_e32 v80, v35
	v_mul_f32_e32 v35, 0xbfb8aa3b, v77
	v_exp_f32_e32 v35, v35
	v_and_b32_e32 v71, 0xffff0000, v58
	v_lshlrev_b32_e32 v72, 16, v54
	v_and_b32_e32 v73, 0xffff0000, v54
	v_add_f32_e32 v35, 1.0, v35
	v_rcp_f32_e32 v81, v35
	v_mul_f32_e32 v35, 0xbfb8aa3b, v62
	v_exp_f32_e32 v35, v35
	v_and_b32_e32 v63, 0xffff0000, v63
	v_pk_mul_f32 v[72:73], v[70:71], v[72:73]
	v_lshlrev_b32_e32 v70, 16, v66
	v_add_f32_e32 v35, 1.0, v35
	v_and_b32_e32 v71, 0xffff0000, v66
	v_rcp_f32_e32 v66, v35
	v_mul_f32_e32 v35, 0xbfb8aa3b, v63
	v_pk_fma_f32 v[82:83], v[72:73], v[50:51], v[82:83]
	v_exp_f32_e32 v35, v35
	v_pk_add_f32 v[82:83], v[38:39], v[82:83]
	v_pk_mul_f32 v[76:77], v[80:81], v[76:77]
	v_pk_mul_f32 v[70:71], v[82:83], v[70:71]
	v_lshlrev_b32_e32 v58, 16, v59
	v_pk_mul_f32 v[70:71], v[76:77], v[70:71]
	v_and_b32_e32 v59, 0xffff0000, v59
	v_cvt_pk_bf16_f32 v54, v70, v71
	v_lshlrev_b32_e32 v70, 16, v55
	v_and_b32_e32 v71, 0xffff0000, v55
	v_add_f32_e32 v35, 1.0, v35
	v_pk_mul_f32 v[70:71], v[58:59], v[70:71]
	v_lshlrev_b32_e32 v58, 16, v67
	v_and_b32_e32 v59, 0xffff0000, v67
	v_rcp_f32_e32 v67, v35
	v_pk_mul_f32 v[76:77], v[86:87], v[48:49]
	v_pk_mul_f32 v[80:81], v[78:79], v[16:17]
	v_pk_fma_f32 v[76:77], v[94:95], v[44:45], v[76:77]
	v_pk_mul_f32 v[62:63], v[66:67], v[62:63]
	v_lshlrev_b32_e32 v66, 16, v64
	v_mul_f32_e32 v35, 0xbfb8aa3b, v66
	v_exp_f32_e32 v35, v35
	v_pk_fma_f32 v[76:77], v[70:71], v[52:53], v[76:77]
	v_and_b32_e32 v67, 0xffff0000, v64
	v_pk_add_f32 v[76:77], v[40:41], v[76:77]
	v_add_f32_e32 v35, 1.0, v35
	v_pk_mul_f32 v[58:59], v[76:77], v[58:59]
	v_rcp_f32_e32 v76, v35
	v_mul_f32_e32 v35, 0xbfb8aa3b, v67
	v_exp_f32_e32 v35, v35
	v_lshlrev_b32_e32 v64, 16, v65
	v_pk_mul_f32 v[58:59], v[62:63], v[58:59]
	v_lshlrev_b32_e32 v62, 16, v56
	v_add_f32_e32 v35, 1.0, v35
	v_rcp_f32_e32 v77, v35
	v_mul_f32_e32 v35, 0xbfb8aa3b, v64
	v_cvt_pk_bf16_f32 v55, v58, v59
	v_lshlrev_b32_e32 v58, 16, v60
	v_and_b32_e32 v59, 0xffff0000, v60
	v_and_b32_e32 v63, 0xffff0000, v56
	v_exp_f32_e32 v35, v35
	v_pk_mul_f32 v[62:63], v[58:59], v[62:63]
	v_pk_fma_f32 v[80:81], v[98:99], v[12:13], v[80:81]
	v_lshlrev_b32_e32 v58, 16, v68
	v_pk_fma_f32 v[80:81], v[62:63], v[20:21], v[80:81]
	v_and_b32_e32 v59, 0xffff0000, v68
	v_pk_add_f32 v[80:81], v[8:9], v[80:81]
	v_pk_mul_f32 v[66:67], v[76:77], v[66:67]
	v_pk_mul_f32 v[58:59], v[80:81], v[58:59]
	v_and_b32_e32 v65, 0xffff0000, v65
	v_add_f32_e32 v35, 1.0, v35
	v_pk_mul_f32 v[58:59], v[66:67], v[58:59]
	v_rcp_f32_e32 v66, v35
	v_mul_f32_e32 v35, 0xbfb8aa3b, v65
	v_exp_f32_e32 v35, v35
	v_cvt_pk_bf16_f32 v56, v58, v59
	v_lshlrev_b32_e32 v58, 16, v61
	v_and_b32_e32 v59, 0xffff0000, v61
	v_lshlrev_b32_e32 v60, 16, v57
	v_and_b32_e32 v61, 0xffff0000, v57
	v_add_f32_e32 v35, 1.0, v35
	v_pk_mul_f32 v[58:59], v[58:59], v[60:61]
	v_lshlrev_b32_e32 v60, 16, v69
	v_and_b32_e32 v61, 0xffff0000, v69
	v_pk_mul_f32 v[68:69], v[74:75], v[18:19]
	v_rcp_f32_e32 v67, v35
	v_pk_fma_f32 v[68:69], v[92:93], v[14:15], v[68:69]
	v_or_b32_e32 v35, 2, v34
	v_pk_fma_f32 v[68:69], v[58:59], v[22:23], v[68:69]
	v_pk_mul_f32 v[64:65], v[66:67], v[64:65]
	v_pk_add_f32 v[68:69], v[10:11], v[68:69]
	v_pk_mul_f32 v[46:47], v[72:73], v[46:47]
	v_pk_mul_f32 v[60:61], v[68:69], v[60:61]
	v_pk_fma_f32 v[42:43], v[88:89], v[42:43], v[46:47]
	v_pk_mul_f32 v[60:61], v[64:65], v[60:61]
	v_pk_mul_f32 v[16:17], v[62:63], v[16:17]
	v_cvt_pk_bf16_f32 v57, v60, v61
	v_mad_i64_i32 v[60:61], s[6:7], v35, s44, v[90:91]
	v_lshl_add_u64 v[60:61], v[60:61], 0, v[32:33]
	v_add_co_u32_e32 v60, vcc, s0, v60
	v_pk_fma_f32 v[12:13], v[78:79], v[12:13], v[16:17]
	s_nop 0
	v_addc_co_u32_e32 v61, vcc, 0, v61, vcc
	global_store_dwordx4 v[60:61], v[54:57], off offset:1024
	v_lshlrev_b32_e32 v60, 16, v24
	v_and_b32_e32 v61, 0xffff0000, v24
	v_lshlrev_b32_e32 v56, 16, v0
	v_and_b32_e32 v57, 0xffff0000, v0
	v_mul_f32_e32 v0, 0xbfb8aa3b, v60
	v_exp_f32_e32 v0, v0
	v_lshlrev_b32_e32 v54, 16, v4
	v_and_b32_e32 v55, 0xffff0000, v4
	v_pk_mul_f32 v[54:55], v[114:115], v[54:55] op_sel_hi:[0,1]
	v_add_f32_e32 v0, 1.0, v0
	v_rcp_f32_e32 v64, v0
	v_mul_f32_e32 v0, 0xbfb8aa3b, v61
	v_exp_f32_e32 v0, v0
	v_pk_mul_f32 v[54:55], v[54:55], v[56:57]
	v_lshlrev_b32_e32 v56, 16, v28
	v_pk_fma_f32 v[42:43], v[54:55], v[50:51], v[42:43]
	v_add_f32_e32 v0, 1.0, v0
	v_rcp_f32_e32 v65, v0
	v_and_b32_e32 v57, 0xffff0000, v28
	v_pk_add_f32 v[38:39], v[38:39], v[42:43]
	v_lshlrev_b32_e32 v24, 16, v25
	v_pk_mul_f32 v[38:39], v[38:39], v[56:57]
	v_pk_mul_f32 v[42:43], v[64:65], v[60:61]
	v_lshlrev_b32_e32 v4, 16, v5
	v_pk_mul_f32 v[38:39], v[42:43], v[38:39]
	v_and_b32_e32 v5, 0xffff0000, v5
	v_cvt_pk_bf16_f32 v0, v38, v39
	v_lshlrev_b32_e32 v38, 16, v1
	v_and_b32_e32 v39, 0xffff0000, v1
	v_mul_f32_e32 v1, 0xbfb8aa3b, v24
	v_exp_f32_e32 v1, v1
	v_pk_mul_f32 v[4:5], v[114:115], v[4:5] op_sel_hi:[0,1]
	v_and_b32_e32 v25, 0xffff0000, v25
	v_pk_mul_f32 v[4:5], v[4:5], v[38:39]
	v_add_f32_e32 v1, 1.0, v1
	v_rcp_f32_e32 v38, v1
	v_mul_f32_e32 v1, 0xbfb8aa3b, v25
	v_exp_f32_e32 v1, v1
	v_pk_mul_f32 v[42:43], v[70:71], v[48:49]
	v_lshlrev_b32_e32 v28, 16, v29
	v_pk_fma_f32 v[42:43], v[86:87], v[44:45], v[42:43]
	v_add_f32_e32 v1, 1.0, v1
	v_rcp_f32_e32 v39, v1
	v_pk_fma_f32 v[4:5], v[4:5], v[52:53], v[42:43]
	v_and_b32_e32 v29, 0xffff0000, v29
	v_pk_add_f32 v[4:5], v[40:41], v[4:5]
	v_pk_mul_f32 v[24:25], v[38:39], v[24:25]
	v_pk_mul_f32 v[4:5], v[4:5], v[28:29]
	v_lshlrev_b32_e32 v28, 16, v26
	v_pk_mul_f32 v[4:5], v[24:25], v[4:5]
	v_lshlrev_b32_e32 v24, 16, v2
	v_and_b32_e32 v25, 0xffff0000, v2
	v_mul_f32_e32 v2, 0xbfb8aa3b, v28
	v_exp_f32_e32 v2, v2
	v_and_b32_e32 v29, 0xffff0000, v26
	v_cvt_pk_bf16_f32 v1, v4, v5
	v_lshlrev_b32_e32 v4, 16, v6
	v_add_f32_e32 v2, 1.0, v2
	v_rcp_f32_e32 v38, v2
	v_mul_f32_e32 v2, 0xbfb8aa3b, v29
	v_exp_f32_e32 v2, v2
	v_and_b32_e32 v5, 0xffff0000, v6
	v_pk_mul_f32 v[4:5], v[114:115], v[4:5] op_sel_hi:[0,1]
	v_pk_mul_f32 v[4:5], v[4:5], v[24:25]
	v_add_f32_e32 v2, 1.0, v2
	v_rcp_f32_e32 v39, v2
	v_pk_fma_f32 v[4:5], v[4:5], v[20:21], v[12:13]
	v_lshlrev_b32_e32 v24, 16, v30
	v_and_b32_e32 v25, 0xffff0000, v30
	v_pk_add_f32 v[4:5], v[8:9], v[4:5]
	v_pk_mul_f32 v[8:9], v[38:39], v[28:29]
	v_pk_mul_f32 v[4:5], v[4:5], v[24:25]
	v_lshlrev_b32_e32 v6, 16, v3
	v_pk_mul_f32 v[4:5], v[8:9], v[4:5]
	v_lshlrev_b32_e32 v8, 16, v27
	v_cvt_pk_bf16_f32 v2, v4, v5
	v_lshlrev_b32_e32 v4, 16, v7
	v_and_b32_e32 v5, 0xffff0000, v7
	v_and_b32_e32 v7, 0xffff0000, v3
	v_mul_f32_e32 v3, 0xbfb8aa3b, v8
	v_exp_f32_e32 v3, v3
	v_and_b32_e32 v9, 0xffff0000, v27
	v_pk_mul_f32 v[4:5], v[114:115], v[4:5] op_sel_hi:[0,1]
	v_pk_mul_f32 v[16:17], v[58:59], v[18:19]
	v_add_f32_e32 v3, 1.0, v3
	v_rcp_f32_e32 v12, v3
	v_mul_f32_e32 v3, 0xbfb8aa3b, v9
	v_exp_f32_e32 v3, v3
	v_pk_mul_f32 v[4:5], v[4:5], v[6:7]
	v_pk_fma_f32 v[14:15], v[74:75], v[14:15], v[16:17]
	v_lshlrev_b32_e32 v6, 16, v31
	v_add_f32_e32 v3, 1.0, v3
	v_rcp_f32_e32 v13, v3
	v_pk_fma_f32 v[4:5], v[4:5], v[22:23], v[14:15]
	v_and_b32_e32 v7, 0xffff0000, v31
	v_pk_add_f32 v[4:5], v[10:11], v[4:5]
	s_nop 0
	v_pk_mul_f32 v[4:5], v[4:5], v[6:7]
	v_pk_mul_f32 v[6:7], v[12:13], v[8:9]
	s_nop 0
	v_pk_mul_f32 v[4:5], v[6:7], v[4:5]
	s_nop 0
	v_cvt_pk_bf16_f32 v3, v4, v5
	v_or_b32_e32 v4, 3, v34
	v_mad_i64_i32 v[4:5], s[6:7], v4, s44, v[90:91]
	v_lshl_add_u64 v[4:5], v[4:5], 0, v[32:33]
	v_add_co_u32_e32 v4, vcc, 0x18c00000, v4
	s_nop 1
	v_addc_co_u32_e32 v5, vcc, 0, v5, vcc
	global_store_dwordx4 v[4:5], v[0:3], off offset:1024

.LBB0_653:
	s_mul_hi_u32 s0, s12, 0xaaaaaaab
	s_lshr_b32 s13, s0, 1
	s_mul_i32 s16, s13, -3
	s_add_i32 s16, s16, s12
	s_cmp_lt_i32 s16, 2
	s_mov_b64 s[6:7], -1
	s_cbranch_scc1 .LBB0_656
	s_mov_b64 s[6:7], 0
	s_mov_b64 s[10:11], -1
	s_cmp_eq_u32 s16, 2
	s_mov_b32 s95, s13
	s_mov_b64 s[76:77], 0
	s_mov_b32 s94, s18
	s_cbranch_scc0 .LBB0_656
	s_lshl_b32 s8, s13, 1
	s_mul_hi_u32 s0, s8, 0x78787879
	s_lshr_b32 s0, s0, 4
	s_mul_i32 s0, s0, 34
	s_sub_i32 s0, s8, s0
	s_mul_hi_u32 s9, s12, 0xa0a0a0a1
	s_lshr_b32 s10, s9, 5
	s_lshr_b32 s19, s9, 7
	s_bfe_u32 s11, s9, 0x20005
	s_lshl_b32 s9, s0, 7
	s_cmp_eq_u32 s0, 0
	s_movk_i32 s21, 0xff00
	s_cselect_b32 s17, 8, 12
	s_cselect_b32 s20, 0x4000, s21
	s_or_b32 s8, s8, 1
	s_add_i32 s20, s20, s9
	s_mul_hi_u32 s9, s8, 0x78787879
	s_lshr_b32 s9, s9, 4
	s_lshl_b32 s17, s19, s17
	s_mul_i32 s9, s9, 34
	s_add_i32 s20, s20, s17
	s_sub_i32 s17, s8, s9
	s_lshl_b32 s8, s17, 7
	s_cmp_eq_u32 s17, 1
	s_cselect_b32 s9, 8, 12
	s_cselect_b32 s21, 0x4000, s21
	s_lshl_b32 s9, s19, s9
	s_add_i32 s19, s21, s8
	s_lshl_b32 s8, s5, 3
	s_or_b32 s8, s8, s11
	s_add_i32 s19, s19, s9
	s_ashr_i32 s9, s8, 31
	s_lshl_b64 s[8:9], s[8:9], 2
	s_add_u32 s8, s42, s8
	s_addc_u32 s9, s43, s9
	global_load_dword v0, v33, s[8:9]
	global_load_dword v1, v33, s[8:9] offset:16
	s_mov_b32 s8, 0xbfb8aa3b
	s_mov_b32 s9, 0x3f317218
	s_mov_b32 s21, 0x7f800000
	s_mov_b32 s22, 0x33800000
	v_ashrrev_i32_e32 v31, 3, v206
	v_and_b32_e32 v16, 15, v206
	v_lshlrev_b32_e32 v102, 2, v16
	v_and_b32_e32 v86, 12, v102
	v_mov_b32_e32 v62, 0x1400
	v_mov_b32_e32 v80, 0x1e00
	s_mov_b32 s94, 2
	s_waitcnt vmcnt(1)
	v_mul_f32_e32 v2, 0xbfb8aa3b, v0
	s_waitcnt vmcnt(0)
	v_mul_f32_e32 v3, 0xbfb8aa3b, v1
	v_fma_f32 v4, v0, s8, -v2
	v_rndne_f32_e32 v5, v2
	v_fma_f32 v6, v1, s8, -v3
	v_rndne_f32_e32 v7, v3
	v_fmac_f32_e32 v4, 0xb2a5705f, v0
	v_sub_f32_e32 v2, v2, v5
	v_fmac_f32_e32 v6, 0xb2a5705f, v1
	v_sub_f32_e32 v3, v3, v7
	v_add_f32_e32 v2, v2, v4
	v_cvt_i32_f32_e32 v5, v5
	v_add_f32_e32 v3, v3, v6
	v_exp_f32_e32 v2, v2
	v_cvt_i32_f32_e32 v7, v7
	v_exp_f32_e32 v3, v3
	s_mov_b32 s8, 0x42ce8ed0
	v_ldexp_f32 v2, v2, v5
	v_cmp_nlt_f32_e32 vcc, s8, v0
	v_ldexp_f32 v3, v3, v7
	s_nop 0
	v_cndmask_b32_e32 v2, 0, v2, vcc
	v_cmp_nlt_f32_e32 vcc, s8, v1
	s_mov_b32 s8, 0xc2b17218
	s_nop 0
	v_cndmask_b32_e32 v3, 0, v3, vcc
	v_cmp_ngt_f32_e32 vcc, s8, v0
	s_nop 1
	v_cndmask_b32_e32 v17, v227, v2, vcc
	v_cmp_ngt_f32_e32 vcc, s8, v1
	v_add_f32_e32 v1, 1.0, v17
	v_add_f32_e32 v4, -1.0, v1
	v_cndmask_b32_e32 v0, v227, v3, vcc
	v_add_f32_e32 v20, 1.0, v0
	v_frexp_mant_f32_e32 v5, v1
	v_cvt_f64_f32_e32 v[2:3], v1
	s_mov_b32 s8, 0x3f2aaaab
	v_add_f32_e32 v21, -1.0, v20
	v_sub_f32_e32 v6, v4, v1
	v_frexp_exp_i32_f64_e32 v2, v[2:3]
	v_cmp_gt_f32_e32 vcc, s8, v5
	v_sub_f32_e32 v4, v17, v4
	v_sub_f32_e32 v3, v21, v20
	v_add_f32_e32 v6, 1.0, v6
	v_subbrev_co_u32_e32 v2, vcc, 0, v2, vcc
	v_add_f32_e32 v22, 1.0, v3
	v_add_f32_e32 v3, v4, v6
	v_sub_u32_e32 v4, 0, v2
	v_ldexp_f32 v1, v1, v4
	v_ldexp_f32 v3, v3, v4
	v_add_f32_e32 v4, -1.0, v1
	v_add_f32_e32 v6, 1.0, v1
	v_add_f32_e32 v5, 1.0, v4
	v_add_f32_e32 v7, -1.0, v6
	v_sub_f32_e32 v5, v1, v5
	v_sub_f32_e32 v1, v1, v7
	v_add_f32_e32 v1, v3, v1
	v_add_f32_e32 v7, v3, v5
	v_add_f32_e32 v3, v6, v1
	v_rcp_f32_e32 v10, v3
	v_add_f32_e32 v5, v4, v7
	v_sub_f32_e32 v6, v6, v3
	v_add_f32_e32 v1, v1, v6
	v_mul_f32_e32 v12, v5, v10
	v_mul_f32_e32 v6, v3, v12
	v_fma_f32 v8, v12, v3, -v6
	v_sub_f32_e32 v4, v4, v5
	v_fmac_f32_e32 v8, v12, v1
	v_add_f32_e32 v11, v7, v4
	v_add_f32_e32 v4, v6, v8
	v_sub_f32_e32 v7, v5, v4
	v_mov_b32_e32 v9, v4
	v_pk_add_f32 v[4:5], v[4:5], v[6:7] neg_lo:[0,1] neg_hi:[0,1]
	v_cvt_f32_i32_e32 v2, v2
	v_pk_add_f32 v[4:5], v[4:5], v[8:9] neg_lo:[0,1] neg_hi:[0,1]
	v_cmp_neq_f32_e32 vcc, s21, v17
	v_add_f32_e32 v5, v11, v5
	v_add_f32_e32 v4, v4, v5
	v_add_f32_e32 v5, v7, v4
	v_mul_f32_e32 v9, v10, v5
	v_mul_f32_e32 v6, v3, v9
	v_fma_f32 v8, v9, v3, -v6
	v_sub_f32_e32 v7, v7, v5
	v_fmac_f32_e32 v8, v9, v1
	v_add_f32_e32 v11, v4, v7
	v_add_f32_e32 v13, v12, v9
	v_add_f32_e32 v4, v6, v8
	v_sub_f32_e32 v3, v13, v12
	v_sub_f32_e32 v7, v5, v4
	v_sub_f32_e32 v1, v9, v3
	v_mov_b32_e32 v9, v4
	v_pk_add_f32 v[4:5], v[4:5], v[6:7] neg_lo:[0,1] neg_hi:[0,1]
	s_nop 0
	v_pk_add_f32 v[4:5], v[4:5], v[8:9] neg_lo:[0,1] neg_hi:[0,1]
	s_nop 0
	v_add_f32_e32 v3, v11, v5
	v_add_f32_e32 v3, v4, v3
	v_add_f32_e32 v3, v7, v3
	v_mul_f32_e32 v3, v10, v3
	v_add_f32_e32 v1, v1, v3
	v_add_f32_e32 v3, v13, v1
	v_mul_f32_e32 v4, v3, v3
	v_fmamk_f32 v7, v4, 0x3e9b6dac, v252
	v_sub_f32_e32 v6, v3, v13
	v_ldexp_f32 v5, v3, 1
	v_mul_f32_e32 v3, v3, v4
	v_fmaak_f32 v201, v4, v7, 0x3f2aaada
	v_sub_f32_e32 v1, v1, v6
	v_pk_mul_f32 v[6:7], v[2:3], v[200:201]
	v_ldexp_f32 v1, v1, 1
	v_fma_f32 v4, v2, s9, -v6
	v_fmac_f32_e32 v4, 0xb102e308, v2
	v_pk_add_f32 v[2:3], v[6:7], v[4:5]
	v_mov_b32_e32 v8, v6
	v_sub_f32_e32 v9, v3, v5
	v_pk_add_f32 v[10:11], v[2:3], v[6:7] neg_lo:[0,1] neg_hi:[0,1]
	v_sub_f32_e32 v7, v7, v9
	v_add_f32_e32 v9, v1, v7
	v_pk_add_f32 v[14:15], v[2:3], v[8:9]
	v_mov_b32_e32 v5, v2
	v_mov_b32_e32 v11, v15
	v_pk_add_f32 v[18:19], v[4:5], v[10:11] neg_lo:[0,1] neg_hi:[0,1]
	v_pk_add_f32 v[4:5], v[4:5], v[10:11]
	v_mov_b32_e32 v6, v3
	v_mov_b32_e32 v13, v2
	v_pk_add_f32 v[2:3], v[4:5], v[2:3] op_sel:[1,0] op_sel_hi:[0,1] neg_lo:[0,1] neg_hi:[0,1]
	v_mov_b32_e32 v12, v9
	v_mov_b32_e32 v8, v15
	v_mov_b32_e32 v9, v5
	v_mov_b32_e32 v7, v2
	v_pk_add_f32 v[10:11], v[14:15], v[2:3] op_sel_hi:[1,0] neg_lo:[0,1] neg_hi:[0,1]
	v_pk_add_f32 v[2:3], v[8:9], v[6:7] neg_lo:[0,1] neg_hi:[0,1]
	v_mov_b32_e32 v10, v18
	v_pk_add_f32 v[2:3], v[12:13], v[2:3] neg_lo:[0,1] neg_hi:[0,1]
	v_mov_b32_e32 v19, v5
	v_pk_add_f32 v[6:7], v[10:11], v[2:3]
	s_nop 0
	v_pk_add_f32 v[8:9], v[6:7], v[6:7] op_sel:[0,1] op_sel_hi:[1,0]
	s_nop 0
	v_pk_add_f32 v[4:5], v[4:5], v[8:9] op_sel:[1,0] op_sel_hi:[0,1]
	v_mov_b32_e32 v7, v4
	v_mov_b32_e32 v3, v8
	v_pk_add_f32 v[8:9], v[6:7], v[18:19] neg_lo:[0,1] neg_hi:[0,1]
	s_nop 0
	v_sub_f32_e32 v1, v6, v8
	v_pk_add_f32 v[2:3], v[2:3], v[8:9] neg_lo:[0,1] neg_hi:[0,1]
	v_sub_f32_e32 v1, v18, v1
	v_add_f32_e32 v1, v2, v1
	v_add_f32_e32 v1, v1, v3
	v_add_f32_e32 v1, v4, v1
	v_cndmask_b32_e32 v1, v227, v1, vcc
	v_cmp_lt_f32_e64 vcc, |v17|, s22
	v_frexp_mant_f32_e32 v4, v20
	v_cvt_f64_f32_e32 v[2:3], v20
	v_cndmask_b32_e32 v17, v1, v17, vcc
	v_frexp_exp_i32_f64_e32 v2, v[2:3]
	v_cmp_gt_f32_e32 vcc, s8, v4
	v_sub_f32_e32 v1, v0, v21
	v_add_f32_e32 v1, v1, v22
	v_subbrev_co_u32_e32 v10, vcc, 0, v2, vcc
	v_sub_u32_e32 v2, 0, v10
	v_ldexp_f32 v3, v20, v2
	v_ldexp_f32 v1, v1, v2
	v_add_f32_e32 v2, -1.0, v3
	v_add_f32_e32 v5, 1.0, v3
	v_add_f32_e32 v4, 1.0, v2
	v_add_f32_e32 v6, -1.0, v5
	v_sub_f32_e32 v4, v3, v4
	v_sub_f32_e32 v3, v3, v6
	v_add_f32_e32 v4, v1, v4
	v_add_f32_e32 v1, v1, v3
	v_add_f32_e32 v11, v5, v1
	v_rcp_f32_e32 v12, v11
	v_sub_f32_e32 v3, v5, v11
	v_add_f32_e32 v1, v1, v3
	v_add_f32_e32 v3, v2, v4
	v_sub_f32_e32 v2, v2, v3
	v_mul_f32_e32 v14, v3, v12
	v_add_f32_e32 v13, v4, v2
	v_mul_f32_e32 v4, v11, v14
	v_fma_f32 v6, v14, v11, -v4
	v_fmac_f32_e32 v6, v14, v1
	v_add_f32_e32 v2, v4, v6
	v_sub_f32_e32 v5, v3, v2
	v_pk_add_f32 v[8:9], v[2:3], v[4:5] neg_lo:[0,1] neg_hi:[0,1]
	v_mov_b32_e32 v7, v2
	v_pk_add_f32 v[2:3], v[8:9], v[6:7] neg_lo:[0,1] neg_hi:[0,1]
	s_lshl_b32 s8, s11, 7
	v_add_f32_e32 v3, v13, v3
	v_add_f32_e32 v2, v2, v3
	v_add_f32_e32 v3, v5, v2
	v_mul_f32_e32 v13, v12, v3
	v_mul_f32_e32 v4, v11, v13
	v_fma_f32 v6, v13, v11, -v4
	v_fmac_f32_e32 v6, v13, v1
	v_sub_f32_e32 v1, v5, v3
	v_add_f32_e32 v1, v2, v1
	v_add_f32_e32 v2, v4, v6
	v_sub_f32_e32 v5, v3, v2
	v_pk_add_f32 v[8:9], v[2:3], v[4:5] neg_lo:[0,1] neg_hi:[0,1]
	v_mov_b32_e32 v7, v2
	v_pk_add_f32 v[2:3], v[8:9], v[6:7] neg_lo:[0,1] neg_hi:[0,1]
	s_add_u32 s8, s70, s8
	v_add_f32_e32 v1, v1, v3
	v_add_f32_e32 v1, v2, v1
	v_add_f32_e32 v3, v14, v13
	v_add_f32_e32 v1, v5, v1
	v_sub_f32_e32 v2, v3, v14
	v_mul_f32_e32 v1, v12, v1
	v_sub_f32_e32 v2, v13, v2
	v_add_f32_e32 v1, v2, v1
	v_add_f32_e32 v4, v3, v1
	v_mul_f32_e32 v6, v4, v4
	v_fmamk_f32 v2, v6, 0x3e9b6dac, v252
	v_fmaak_f32 v201, v6, v2, 0x3f2aaada
	v_cvt_f32_i32_e32 v2, v10
	v_sub_f32_e32 v3, v4, v3
	v_sub_f32_e32 v1, v1, v3
	v_mul_f32_e32 v3, v4, v6
	v_pk_mul_f32 v[6:7], v[2:3], v[200:201]
	v_ldexp_f32 v5, v4, 1
	v_fma_f32 v4, v2, s9, -v6
	v_fmac_f32_e32 v4, 0xb102e308, v2
	v_pk_add_f32 v[2:3], v[6:7], v[4:5]
	v_ldexp_f32 v1, v1, 1
	v_sub_f32_e32 v5, v3, v5
	v_sub_f32_e32 v5, v7, v5
	v_add_f32_e32 v9, v1, v5
	v_lshlrev_b32_e32 v1, 3, v206
	v_and_b32_e32 v30, 56, v1
	v_add_u32_e32 v12, s20, v31
	v_mov_b32_e32 v8, v6
	s_addc_u32 s9, s71, 0
	v_lshlrev_b32_e32 v32, 1, v30
	v_ashrrev_i32_e32 v13, 31, v12
	v_pk_add_f32 v[6:7], v[2:3], v[6:7] neg_lo:[0,1] neg_hi:[0,1]
	v_pk_add_f32 v[10:11], v[2:3], v[8:9]
	v_lshl_add_u64 v[34:35], s[8:9], 0, v[32:33]
	v_lshlrev_b64 v[12:13], 13, v[12:13]
	v_lshl_add_u64 v[12:13], v[34:35], 0, v[12:13]
	s_movk_i32 s8, 0x1000
	v_mov_b32_e32 v7, v11
	v_mov_b32_e32 v5, v2
	v_add_co_u32_e32 v12, vcc, s8, v12
	v_pk_add_f32 v[14:15], v[4:5], v[6:7] neg_lo:[0,1] neg_hi:[0,1]
	v_pk_add_f32 v[4:5], v[4:5], v[6:7]
	v_addc_co_u32_e32 v13, vcc, 0, v13, vcc
	v_pk_add_f32 v[6:7], v[4:5], v[2:3] op_sel:[1,0] op_sel_hi:[0,1] neg_lo:[0,1] neg_hi:[0,1]
	global_load_dwordx4 v[18:21], v[12:13], off offset:1024 nt
	v_pk_add_f32 v[22:23], v[10:11], v[6:7] op_sel_hi:[1,0] neg_lo:[0,1] neg_hi:[0,1]
	v_mov_b32_e32 v10, v11
	v_mov_b32_e32 v11, v5
	v_mov_b32_e32 v24, v3
	v_mov_b32_e32 v25, v6
	v_pk_add_f32 v[6:7], v[10:11], v[24:25] neg_lo:[0,1] neg_hi:[0,1]
	v_mov_b32_e32 v8, v9
	v_mov_b32_e32 v9, v2
	v_pk_add_f32 v[2:3], v[8:9], v[6:7] neg_lo:[0,1] neg_hi:[0,1]
	v_mov_b32_e32 v22, v14
	v_pk_add_f32 v[6:7], v[22:23], v[2:3]
	v_mov_b32_e32 v15, v5
	v_pk_add_f32 v[8:9], v[6:7], v[6:7] op_sel:[0,1] op_sel_hi:[1,0]
	v_cmp_neq_f32_e32 vcc, s21, v0
	v_pk_add_f32 v[4:5], v[4:5], v[8:9] op_sel:[1,0] op_sel_hi:[0,1]
	v_mov_b32_e32 v7, v4
	v_pk_add_f32 v[10:11], v[6:7], v[14:15] neg_lo:[0,1] neg_hi:[0,1]
	v_mov_b32_e32 v3, v8
	v_sub_f32_e32 v1, v6, v10
	v_pk_add_f32 v[2:3], v[2:3], v[10:11] neg_lo:[0,1] neg_hi:[0,1]
	v_sub_f32_e32 v1, v14, v1
	v_add_f32_e32 v1, v2, v1
	v_add_f32_e32 v1, v1, v3
	v_add_f32_e32 v1, v4, v1
	v_cndmask_b32_e32 v1, v227, v1, vcc
	v_cmp_lt_f32_e64 vcc, |v0|, s22
	global_load_dwordx4 v[22:25], v[12:13], off offset:1536 nt
	v_cndmask_b32_e32 v32, v1, v0, vcc
	v_add_u32_e32 v0, 0x200, v206
	v_ashrrev_i32_e32 v37, 3, v0
	v_add_u32_e32 v0, s20, v37
	v_ashrrev_i32_e32 v1, 31, v0
	v_lshlrev_b64 v[0:1], 13, v[0:1]
	v_lshl_add_u64 v[0:1], v[34:35], 0, v[0:1]
	v_add_co_u32_e32 v0, vcc, s8, v0
	s_nop 0
	v_addc_co_u32_e32 v1, vcc, 0, v1, vcc
	global_load_dwordx4 v[26:29], v[0:1], off offset:1024 nt
	global_load_dwordx4 v[38:41], v[0:1], off offset:1536 nt
	v_add_u32_e32 v0, s19, v31
	v_ashrrev_i32_e32 v1, 31, v0
	v_lshlrev_b64 v[0:1], 13, v[0:1]
	v_lshl_add_u64 v[0:1], v[34:35], 0, v[0:1]
	v_add_co_u32_e32 v0, vcc, s8, v0
	s_nop 0
	v_addc_co_u32_e32 v1, vcc, 0, v1, vcc
	global_load_dwordx4 v[12:15], v[0:1], off offset:1024 nt
	global_load_dwordx4 v[8:11], v[0:1], off offset:1536 nt
	v_add_u32_e32 v0, s19, v37
	v_ashrrev_i32_e32 v1, 31, v0
	v_lshlrev_b64 v[0:1], 13, v[0:1]
	v_lshl_add_u64 v[0:1], v[34:35], 0, v[0:1]
	v_add_co_u32_e32 v0, vcc, s8, v0
	v_lshrrev_b32_e32 v34, 4, v207
	s_nop 0
	v_addc_co_u32_e32 v1, vcc, 0, v1, vcc
	global_load_dwordx4 v[4:7], v[0:1], off offset:1024 nt
	s_nop 0
	global_load_dwordx4 v[0:3], v[0:1], off offset:1536 nt
	s_waitcnt vmcnt(7)
	v_lshlrev_b32_e32 v46, 16, v20
	v_and_b32_e32 v47, 0xffff0000, v20
	v_cvt_f32_i32_e32 v20, v31
	v_mul_f32_e32 v35, 0xbfb8aa3b, v17
	v_bfe_u32 v17, v206, 2, 2
	v_lshl_or_b32 v76, v34, 3, v17
	v_sub_u32_e32 v17, 0x7f, v31
	v_cvt_f32_i32_e32 v17, v17
	v_lshlrev_b32_e32 v42, 16, v18
	v_and_b32_e32 v43, 0xffff0000, v18
	v_mul_f32_e32 v32, 0xbfb8aa3b, v32
	v_mul_f32_e32 v16, v35, v17
	v_exp_f32_e32 v103, v16
	v_lshlrev_b32_e32 v44, 16, v19
	v_and_b32_e32 v45, 0xffff0000, v19
	v_mul_f32_e32 v20, v32, v20
	v_mul_f32_e32 v16, v103, v42
	v_mul_f32_e32 v17, v103, v43
	v_cvt_pk_bf16_f32 v16, v16, v17
	v_mul_f32_e32 v17, v103, v44
	v_mul_f32_e32 v18, v103, v45
	v_cvt_pk_bf16_f32 v17, v17, v18
	v_mul_f32_e32 v18, v103, v46
	v_mul_f32_e32 v19, v103, v47
	v_lshlrev_b32_e32 v48, 16, v21
	v_and_b32_e32 v49, 0xffff0000, v21
	v_exp_f32_e32 v104, v20
	v_cvt_pk_bf16_f32 v18, v18, v19
	v_mul_f32_e32 v19, v103, v48
	v_mul_f32_e32 v21, v103, v49
	s_movk_i32 s19, 0x50
	v_cvt_pk_bf16_f32 v19, v19, v21
	v_mad_u64_u32 v[20:21], s[8:9], v31, s19, v[30:31]
	v_lshl_add_u32 v105, v20, 1, 0
	s_barrier
	ds_write_b128 v105, v[16:19]
	v_mul_f32_e32 v16, v104, v42
	v_mul_f32_e32 v17, v104, v43
	v_cvt_pk_bf16_f32 v16, v16, v17
	v_mul_f32_e32 v17, v104, v44
	v_mul_f32_e32 v18, v104, v45
	v_cvt_pk_bf16_f32 v17, v17, v18
	v_mul_f32_e32 v18, v104, v46
	v_mul_f32_e32 v19, v104, v47
	v_cvt_pk_bf16_f32 v18, v18, v19
	v_sub_u32_e32 v19, 0x7f, v37
	v_cvt_f32_i32_e32 v20, v19
	v_mul_f32_e32 v19, v104, v48
	v_mul_f32_e32 v21, v104, v49
	v_cvt_pk_bf16_f32 v19, v19, v21
	v_mul_f32_e32 v20, v35, v20
	v_exp_f32_e32 v35, v20
	v_cvt_f32_i32_e32 v20, v37
	ds_write_b128 v105, v[16:19] offset:20480
	s_waitcnt vmcnt(6)
	ds_write_b128 v105, v[22:25] offset:40960
	v_mad_u32_u24 v62, v76, s19, v62
	v_mad_u32_u24 v87, v76, s19, v80
	v_mul_f32_e32 v20, v32, v20
	v_exp_f32_e32 v32, v20
	s_waitcnt vmcnt(5)
	v_lshlrev_b32_e32 v22, 16, v26
	v_and_b32_e32 v23, 0xffff0000, v26
	v_mul_f32_e32 v16, v35, v22
	v_mul_f32_e32 v17, v35, v23
	v_lshlrev_b32_e32 v24, 16, v27
	v_and_b32_e32 v25, 0xffff0000, v27
	v_cvt_pk_bf16_f32 v16, v16, v17
	v_mul_f32_e32 v17, v35, v24
	v_mul_f32_e32 v18, v35, v25
	v_lshlrev_b32_e32 v26, 16, v28
	v_and_b32_e32 v27, 0xffff0000, v28
	v_cvt_pk_bf16_f32 v17, v17, v18
	v_mul_f32_e32 v18, v35, v26
	v_mul_f32_e32 v19, v35, v27
	v_lshlrev_b32_e32 v28, 16, v29
	v_and_b32_e32 v29, 0xffff0000, v29
	v_cvt_pk_bf16_f32 v18, v18, v19
	v_mul_f32_e32 v19, v35, v28
	v_mul_f32_e32 v21, v35, v29
	v_cvt_pk_bf16_f32 v19, v19, v21
	v_mad_u64_u32 v[20:21], s[8:9], v37, s19, v[30:31]
	v_lshl_add_u32 v37, v20, 1, 0
	ds_write_b128 v37, v[16:19]
	v_mul_f32_e32 v16, v32, v22
	v_mul_f32_e32 v17, v32, v23
	v_cvt_pk_bf16_f32 v16, v16, v17
	v_mul_f32_e32 v17, v32, v24
	v_mul_f32_e32 v18, v32, v25
	v_cvt_pk_bf16_f32 v17, v17, v18
	v_mul_f32_e32 v18, v32, v26
	v_mul_f32_e32 v19, v32, v27
	v_cvt_pk_bf16_f32 v18, v18, v19
	v_mul_f32_e32 v19, v32, v28
	v_mul_f32_e32 v20, v32, v29
	v_cvt_pk_bf16_f32 v19, v19, v20
	v_readlane_b32 s8, v254, 42
	v_mov_b32_e32 v30, 0xa00
	ds_write_b128 v37, v[16:19] offset:20480
	s_waitcnt vmcnt(4)
	ds_write_b128 v37, v[38:41] offset:40960
	v_or_b32_e32 v77, s8, v86
	v_mul_u32_u24_e32 v16, 0x50, v76
	v_mad_u32_u24 v46, v76, s19, v30
	v_mad_u32_u24 v17, v76, s19, v77
	v_or_b32_e32 v16, v16, v86
	v_add_u32_e32 v30, v46, v77
	v_or_b32_e32 v46, v46, v86
	v_add_u32_e32 v63, v62, v77
	v_or_b32_e32 v62, v62, v86
	v_or_b32_e32 v86, v87, v86
	v_lshl_add_u32 v106, v17, 1, 0
	v_lshl_add_u32 v107, v16, 1, s72
	v_lshl_add_u32 v109, v46, 1, s72
	v_lshl_add_u32 v110, v63, 1, 0
	v_lshl_add_u32 v111, v62, 1, s72
	v_add_u32_e32 v76, v87, v77
	v_lshl_add_u32 v113, v86, 1, s72
	s_waitcnt lgkmcnt(0)
	s_barrier
	ds_read_b64_tr_b16 v[16:17], v106 offset:40960
	ds_read_b64_tr_b16 v[18:19], v106 offset:41600
	ds_read_b64_tr_b16 v[20:21], v107
	ds_read_b64_tr_b16 v[24:25], v107 offset:32
	ds_read_b64_tr_b16 v[22:23], v107 offset:640
	ds_read_b64_tr_b16 v[26:27], v107 offset:672
	ds_read_b64_tr_b16 v[28:29], v107 offset:64
	ds_read_b64_tr_b16 v[38:39], v107 offset:96
	v_lshl_add_u32 v108, v30, 1, 0
	ds_read_b64_tr_b16 v[30:31], v107 offset:704
	ds_read_b64_tr_b16 v[40:41], v107 offset:736
	ds_read_b64_tr_b16 v[42:43], v108 offset:40960
	ds_read_b64_tr_b16 v[44:45], v108 offset:41600
	ds_read_b64_tr_b16 v[46:47], v109
	ds_read_b64_tr_b16 v[50:51], v109 offset:32
	ds_read_b64_tr_b16 v[54:55], v109 offset:64
	ds_read_b64_tr_b16 v[58:59], v109 offset:96
	ds_read_b64_tr_b16 v[48:49], v109 offset:640
	ds_read_b64_tr_b16 v[52:53], v109 offset:672
	ds_read_b64_tr_b16 v[56:57], v109 offset:704
	ds_read_b64_tr_b16 v[60:61], v109 offset:736
	ds_read_b64_tr_b16 v[62:63], v110 offset:40960
	ds_read_b64_tr_b16 v[64:65], v110 offset:41600
	ds_read_b64_tr_b16 v[66:67], v111
	ds_read_b64_tr_b16 v[70:71], v111 offset:32
	ds_read_b64_tr_b16 v[68:69], v111 offset:640
	ds_read_b64_tr_b16 v[72:73], v111 offset:672
	ds_read_b64_tr_b16 v[74:75], v111 offset:64
	ds_read_b64_tr_b16 v[78:79], v111 offset:96
	v_lshl_add_u32 v112, v76, 1, 0
	ds_read_b64_tr_b16 v[76:77], v111 offset:704
	ds_read_b64_tr_b16 v[80:81], v111 offset:736
	ds_read_b64_tr_b16 v[82:83], v112 offset:40960
	ds_read_b64_tr_b16 v[84:85], v112 offset:41600
	ds_read_b64_tr_b16 v[86:87], v113
	ds_read_b64_tr_b16 v[90:91], v113 offset:32
	ds_read_b64_tr_b16 v[94:95], v113 offset:64
	ds_read_b64_tr_b16 v[98:99], v113 offset:96
	ds_read_b64_tr_b16 v[88:89], v113 offset:640
	ds_read_b64_tr_b16 v[92:93], v113 offset:672
	ds_read_b64_tr_b16 v[96:97], v113 offset:704
	ds_read_b64_tr_b16 v[100:101], v113 offset:736
	s_mul_i32 s8, s10, 34
	v_lshlrev_b32_e32 v34, 10, v34
	s_waitcnt lgkmcnt(14)
	v_mfma_f32_16x16x32_bf16 v[20:23], v[16:19], v[20:23], 0
	v_readlane_b32 s9, v254, 40
	s_add_i32 s0, s0, s8
	s_lshl_b32 s0, s0, 13
	v_mfma_f32_16x16x32_bf16 v[24:27], v[16:19], v[24:27], 0
	v_add3_u32 v34, s9, v34, v102
	v_add_u32_e32 v34, 0xf000, v34
	v_readlane_b32 s19, v254, 54
	v_mfma_f32_16x16x32_bf16 v[28:31], v[16:19], v[28:31], 0
	s_add_i32 s0, s0, s19
	v_readlane_b32 s20, v254, 19
	v_readlane_b32 s21, v254, 20
	v_mfma_f32_16x16x32_bf16 v[16:19], v[16:19], v[38:41], 0
	v_readlane_b32 s22, v254, 21
	v_readlane_b32 s23, v254, 22
	v_mfma_f32_16x16x32_bf16 v[20:23], v[42:45], v[46:49], v[20:23]
	v_mfma_f32_16x16x32_bf16 v[24:27], v[42:45], v[50:53], v[24:27]
	v_mfma_f32_16x16x32_bf16 v[28:31], v[42:45], v[54:57], v[28:31]
	v_mfma_f32_16x16x32_bf16 v[16:19], v[42:45], v[58:61], v[16:19]
	v_mfma_f32_16x16x32_bf16 v[20:23], v[62:65], v[66:69], v[20:23]
	v_mfma_f32_16x16x32_bf16 v[24:27], v[62:65], v[70:73], v[24:27]
	s_waitcnt lgkmcnt(11)
	v_mfma_f32_16x16x32_bf16 v[28:31], v[62:65], v[74:77], v[28:31]
	s_waitcnt lgkmcnt(10)
	v_mfma_f32_16x16x32_bf16 v[16:19], v[62:65], v[78:81], v[16:19]
	s_waitcnt lgkmcnt(3)
	v_mfma_f32_16x16x32_bf16 v[20:23], v[82:85], v[86:89], v[20:23]
	v_lshl_add_u32 v87, v207, 4, s9
	v_lshlrev_b32_e32 v86, 2, v207
	v_or_b32_e32 v38, s0, v86
	s_waitcnt lgkmcnt(2)
	v_mfma_f32_16x16x32_bf16 v[24:27], v[82:85], v[90:93], v[24:27]
	v_lshlrev_b32_e32 v38, 2, v38
	s_waitcnt lgkmcnt(1)
	v_mfma_f32_16x16x32_bf16 v[28:31], v[82:85], v[94:97], v[28:31]
	s_waitcnt lgkmcnt(0)
	v_mfma_f32_16x16x32_bf16 v[16:19], v[82:85], v[98:101], v[16:19]
	s_nop 2
	ds_write2_b32 v34, v20, v24 offset1:16
	ds_write2_b32 v34, v21, v25 offset0:64 offset1:80
	ds_write2_b32 v34, v22, v26 offset0:128 offset1:144
	ds_write2_b32 v34, v23, v27 offset0:192 offset1:208
	s_nop 0
	ds_write2_b32 v34, v28, v16 offset0:32 offset1:48
	ds_write2_b32 v34, v29, v17 offset0:96 offset1:112
	ds_write2_b32 v34, v30, v18 offset0:160 offset1:176
	ds_write2_b32 v34, v31, v19 offset0:224 offset1:240
	s_waitcnt lgkmcnt(0)
	ds_read_b128 v[16:19], v87 offset:61440
	ds_read_b128 v[20:23], v87 offset:62464
	ds_read_b128 v[24:27], v87 offset:63488
	ds_read_b128 v[28:31], v87 offset:64512
	s_waitcnt lgkmcnt(3)
	buffer_store_dwordx4 v[16:19], v38, s[20:23], 0 offen sc1
	s_waitcnt lgkmcnt(2)
	buffer_store_dwordx4 v[20:23], v38, s[20:23], 0 offen offset:1024 sc1
	s_waitcnt lgkmcnt(1)
	buffer_store_dwordx4 v[24:27], v38, s[20:23], 0 offen offset:2048 sc1
	s_waitcnt lgkmcnt(0)
	buffer_store_dwordx4 v[28:31], v38, s[20:23], 0 offen offset:3072 sc1
	s_waitcnt vmcnt(7)
	v_lshlrev_b32_e32 v16, 16, v12
	v_and_b32_e32 v18, 0xffff0000, v12
	v_mul_f32_e32 v17, v103, v16
	v_mul_f32_e32 v12, v103, v18
	v_cvt_pk_bf16_f32 v12, v17, v12
	v_lshlrev_b32_e32 v17, 16, v13
	v_and_b32_e32 v20, 0xffff0000, v13
	v_mul_f32_e32 v19, v103, v17
	v_mul_f32_e32 v13, v103, v20
	v_cvt_pk_bf16_f32 v13, v19, v13
	v_lshlrev_b32_e32 v19, 16, v14
	v_and_b32_e32 v22, 0xffff0000, v14
	v_mul_f32_e32 v21, v103, v19
	v_mul_f32_e32 v14, v103, v22
	v_cvt_pk_bf16_f32 v14, v21, v14
	v_lshlrev_b32_e32 v21, 16, v15
	v_and_b32_e32 v24, 0xffff0000, v15
	v_mul_f32_e32 v23, v103, v21
	v_mul_f32_e32 v15, v103, v24
	v_cvt_pk_bf16_f32 v15, v23, v15
	s_waitcnt lgkmcnt(0)
	s_barrier
	ds_write_b128 v105, v[12:15]
	v_mul_f32_e32 v12, v104, v16
	v_mul_f32_e32 v13, v104, v18
	v_cvt_pk_bf16_f32 v12, v12, v13
	v_mul_f32_e32 v13, v104, v17
	v_mul_f32_e32 v14, v104, v20
	v_cvt_pk_bf16_f32 v13, v13, v14
	v_mul_f32_e32 v14, v104, v19
	v_mul_f32_e32 v15, v104, v22
	v_cvt_pk_bf16_f32 v14, v14, v15
	v_mul_f32_e32 v15, v104, v21
	v_mul_f32_e32 v16, v104, v24
	v_cvt_pk_bf16_f32 v15, v15, v16
	ds_write_b128 v105, v[12:15] offset:20480
	s_waitcnt vmcnt(6)
	ds_write_b128 v105, v[8:11] offset:40960
	s_waitcnt vmcnt(5)
	v_lshlrev_b32_e32 v8, 16, v4
	v_and_b32_e32 v10, 0xffff0000, v4
	v_mul_f32_e32 v9, v35, v8
	v_mul_f32_e32 v4, v35, v10
	v_cvt_pk_bf16_f32 v4, v9, v4
	v_lshlrev_b32_e32 v9, 16, v5
	v_and_b32_e32 v12, 0xffff0000, v5
	v_mul_f32_e32 v11, v35, v9
	v_mul_f32_e32 v5, v35, v12
	v_cvt_pk_bf16_f32 v5, v11, v5
	v_lshlrev_b32_e32 v11, 16, v6
	v_and_b32_e32 v14, 0xffff0000, v6
	v_mul_f32_e32 v13, v35, v11
	v_mul_f32_e32 v6, v35, v14
	v_cvt_pk_bf16_f32 v6, v13, v6
	v_lshlrev_b32_e32 v13, 16, v7
	v_and_b32_e32 v16, 0xffff0000, v7
	v_mul_f32_e32 v15, v35, v13
	v_mul_f32_e32 v7, v35, v16
	v_cvt_pk_bf16_f32 v7, v15, v7
	ds_write_b128 v37, v[4:7]
	v_mul_f32_e32 v4, v32, v8
	v_mul_f32_e32 v5, v32, v10
	v_cvt_pk_bf16_f32 v4, v4, v5
	v_mul_f32_e32 v5, v32, v9
	v_mul_f32_e32 v6, v32, v12
	v_cvt_pk_bf16_f32 v5, v5, v6
	v_mul_f32_e32 v6, v32, v11
	v_mul_f32_e32 v7, v32, v14
	v_cvt_pk_bf16_f32 v6, v6, v7
	v_mul_f32_e32 v7, v32, v13
	v_mul_f32_e32 v8, v32, v16
	v_cvt_pk_bf16_f32 v7, v7, v8
	ds_write_b128 v37, v[4:7] offset:20480
	s_waitcnt vmcnt(4)
	ds_write_b128 v37, v[0:3] offset:40960
	s_waitcnt lgkmcnt(0)
	s_barrier
	ds_read_b64_tr_b16 v[0:1], v106 offset:40960
	ds_read_b64_tr_b16 v[2:3], v106 offset:41600
	ds_read_b64_tr_b16 v[4:5], v107
	ds_read_b64_tr_b16 v[8:9], v107 offset:32
	ds_read_b64_tr_b16 v[6:7], v107 offset:640
	ds_read_b64_tr_b16 v[10:11], v107 offset:672
	ds_read_b64_tr_b16 v[12:13], v107 offset:64
	ds_read_b64_tr_b16 v[16:17], v107 offset:96
	ds_read_b64_tr_b16 v[14:15], v107 offset:704
	ds_read_b64_tr_b16 v[18:19], v107 offset:736
	ds_read_b64_tr_b16 v[20:21], v108 offset:40960
	ds_read_b64_tr_b16 v[22:23], v108 offset:41600
	ds_read_b64_tr_b16 v[24:25], v109
	ds_read_b64_tr_b16 v[28:29], v109 offset:32
	ds_read_b64_tr_b16 v[38:39], v109 offset:64
	ds_read_b64_tr_b16 v[42:43], v109 offset:96
	ds_read_b64_tr_b16 v[26:27], v109 offset:640
	ds_read_b64_tr_b16 v[30:31], v109 offset:672
	ds_read_b64_tr_b16 v[40:41], v109 offset:704
	ds_read_b64_tr_b16 v[44:45], v109 offset:736
	ds_read_b64_tr_b16 v[46:47], v110 offset:40960
	ds_read_b64_tr_b16 v[48:49], v110 offset:41600
	ds_read_b64_tr_b16 v[50:51], v111
	ds_read_b64_tr_b16 v[54:55], v111 offset:32
	ds_read_b64_tr_b16 v[52:53], v111 offset:640
	ds_read_b64_tr_b16 v[56:57], v111 offset:672
	ds_read_b64_tr_b16 v[58:59], v111 offset:64
	ds_read_b64_tr_b16 v[62:63], v111 offset:96
	ds_read_b64_tr_b16 v[60:61], v111 offset:704
	ds_read_b64_tr_b16 v[64:65], v111 offset:736
	ds_read_b64_tr_b16 v[66:67], v112 offset:40960
	ds_read_b64_tr_b16 v[68:69], v112 offset:41600
	ds_read_b64_tr_b16 v[70:71], v113
	ds_read_b64_tr_b16 v[74:75], v113 offset:32
	ds_read_b64_tr_b16 v[78:79], v113 offset:64
	ds_read_b64_tr_b16 v[82:83], v113 offset:96
	ds_read_b64_tr_b16 v[72:73], v113 offset:640
	ds_read_b64_tr_b16 v[76:77], v113 offset:672
	ds_read_b64_tr_b16 v[80:81], v113 offset:704
	ds_read_b64_tr_b16 v[84:85], v113 offset:736
	s_waitcnt lgkmcnt(14)
	v_mfma_f32_16x16x32_bf16 v[4:7], v[0:3], v[4:7], 0
	s_add_i32 s17, s17, s8
	s_lshl_b32 s0, s17, 13
	s_add_i32 s0, s0, s19
	v_mfma_f32_16x16x32_bf16 v[8:11], v[0:3], v[8:11], 0
	s_and_b32 s8, s10, 0x7fffffc
	s_mov_b32 s95, s12
	v_mfma_f32_16x16x32_bf16 v[12:15], v[0:3], v[12:15], 0
	v_mfma_f32_16x16x32_bf16 v[0:3], v[0:3], v[16:19], 0
	v_or_b32_e32 v16, s0, v86
	s_lshl_b32 s0, s5, 4
	s_add_i32 s0, s0, s8
	v_mfma_f32_16x16x32_bf16 v[4:7], v[20:23], v[24:27], v[4:7]
	s_or_b32 s0, s0, s11
	v_lshlrev_b32_e32 v16, 2, v16
	s_lshl_b32 s8, s0, 4
	v_mfma_f32_16x16x32_bf16 v[8:11], v[20:23], v[28:31], v[8:11]
	s_ashr_i32 s9, s8, 31
	s_lshl_b64 s[8:9], s[8:9], 2
	v_readlane_b32 s0, v254, 59
	v_mfma_f32_16x16x32_bf16 v[12:15], v[20:23], v[38:41], v[12:15]
	s_add_u32 s76, s0, s8
	v_readlane_b32 s0, v254, 60
	s_addc_u32 s77, s0, s9
	v_mfma_f32_16x16x32_bf16 v[0:3], v[20:23], v[42:45], v[0:3]
	s_mov_b64 s[10:11], 0
	v_mfma_f32_16x16x32_bf16 v[4:7], v[46:49], v[50:53], v[4:7]
	v_mfma_f32_16x16x32_bf16 v[8:11], v[46:49], v[54:57], v[8:11]
	s_waitcnt lgkmcnt(11)
	v_mfma_f32_16x16x32_bf16 v[12:15], v[46:49], v[58:61], v[12:15]
	s_waitcnt lgkmcnt(10)
	v_mfma_f32_16x16x32_bf16 v[0:3], v[46:49], v[62:65], v[0:3]
	s_waitcnt lgkmcnt(3)
	v_mfma_f32_16x16x32_bf16 v[4:7], v[66:69], v[70:73], v[4:7]
	s_waitcnt lgkmcnt(2)
	v_mfma_f32_16x16x32_bf16 v[8:11], v[66:69], v[74:77], v[8:11]
	s_waitcnt lgkmcnt(1)
	v_mfma_f32_16x16x32_bf16 v[12:15], v[66:69], v[78:81], v[12:15]
	s_waitcnt lgkmcnt(0)
	v_mfma_f32_16x16x32_bf16 v[0:3], v[66:69], v[82:85], v[0:3]
	s_nop 3
	ds_write2_b32 v34, v4, v8 offset1:16
	ds_write2_b32 v34, v5, v9 offset0:64 offset1:80
	ds_write2_b32 v34, v6, v10 offset0:128 offset1:144
	ds_write2_b32 v34, v7, v11 offset0:192 offset1:208
	ds_write2_b32 v34, v12, v0 offset0:32 offset1:48
	ds_write2_b32 v34, v13, v1 offset0:96 offset1:112
	ds_write2_b32 v34, v14, v2 offset0:160 offset1:176
	ds_write2_b32 v34, v15, v3 offset0:224 offset1:240
	s_waitcnt lgkmcnt(0)
	ds_read_b128 v[0:3], v87 offset:61440
	ds_read_b128 v[4:7], v87 offset:62464
	ds_read_b128 v[8:11], v87 offset:63488
	ds_read_b128 v[12:15], v87 offset:64512
	s_waitcnt lgkmcnt(3)
	buffer_store_dwordx4 v[0:3], v16, s[20:23], 0 offen sc1
	s_waitcnt lgkmcnt(2)
	buffer_store_dwordx4 v[4:7], v16, s[20:23], 0 offen offset:1024 sc1
	s_waitcnt lgkmcnt(1)
	buffer_store_dwordx4 v[8:11], v16, s[20:23], 0 offen offset:2048 sc1
	s_waitcnt lgkmcnt(0)
	buffer_store_dwordx4 v[12:15], v16, s[20:23], 0 offen offset:3072 sc1
	s_waitcnt lgkmcnt(0)
.LBB0_656:
	s_andn2_b64 vcc, exec, s[6:7]
	s_cbranch_vccnz .LBB0_661
	s_cmp_lg_u32 s16, 1
	s_mov_b64 s[10:11], -1
	s_cbranch_scc1 .LBB0_659
	v_ashrrev_i32_e32 v0, 3, v206
	v_and_b32_e32 v0, -4, v0
	v_lshl_add_u32 v34, s13, 6, v0
	v_lshlrev_b32_e32 v0, 3, v206
	s_movk_i32 s10, 0x4000
	v_and_b32_e32 v18, 0xf8, v0
	v_cmp_gt_i32_e32 vcc, s10, v34
	v_bfrev_b32_e32 v0, 0.5
	v_mov_b32_e32 v1, 0xffc
	v_cndmask_b32_e32 v0, v0, v1, vcc
	v_ashrrev_i32_e32 v35, 31, v34
	v_and_b32_e32 v2, v0, v34
	v_lshlrev_b64 v[0:1], 13, v[34:35]
	v_lshl_add_u64 v[0:1], s[70:71], 0, v[0:1]
	v_lshlrev_b32_e32 v32, 1, v18
	v_lshl_add_u64 v[8:9], v[0:1], 0, v[32:33]
	s_movk_i32 s0, 0x2000
	v_add_co_u32_e64 v10, s[8:9], s0, v8
	v_cmp_ne_u32_e64 s[6:7], 0, v2
	s_nop 0
	v_addc_co_u32_e64 v11, s[8:9], 0, v9, s[8:9]
	v_cndmask_b32_e64 v0, 0, -1, s[6:7]
	v_add_co_u32_e64 v12, s[8:9], s10, v8
	v_mov_b32_e32 v1, v0
	s_nop 0
	v_addc_co_u32_e64 v13, s[8:9], 0, v9, s[8:9]
	s_movk_i32 s0, 0x6000
	v_lshlrev_b64 v[0:1], 13, v[0:1]
	v_add_co_u32_e64 v14, s[8:9], s0, v8
	v_lshl_add_u64 v[0:1], v[8:9], 0, v[0:1]
	s_nop 0
	v_addc_co_u32_e64 v15, s[8:9], 0, v9, s[8:9]
	v_cndmask_b32_e64 v122, 0, 1.0, s[6:7]
	s_lshl_b32 s6, s5, 8
	global_load_dwordx4 v[116:119], v[0:1], off offset:2560 nt
	global_load_dwordx4 v[98:101], v[0:1], off offset:3584 nt
	global_load_dwordx4 v[86:89], v[8:9], off offset:2560 nt
	global_load_dwordx4 v[90:93], v[8:9], off offset:3584 nt
	v_or_b32_e32 v0, 3, v2
	v_mov_b32_e32 v1, 0xff
	v_mov_b32_e32 v2, 0xfff
	s_ashr_i32 s7, s6, 31
	s_mul_i32 s8, s5, 0x300
	v_cndmask_b32_e32 v1, v1, v2, vcc
	s_ashr_i32 s9, s8, 31
	s_lshl_b64 s[6:7], s[6:7], 2
	v_cmp_lt_u32_e32 vcc, v0, v1
	v_mov_b32_e32 v0, 0x6000
	v_mov_b32_e32 v1, 0x8000
	s_add_u32 s10, s40, s6
	s_movk_i32 s0, 0x1000
	v_cndmask_b32_e32 v0, v0, v1, vcc
	v_mov_b32_e32 v1, v33
	s_addc_u32 s11, s41, s7
	v_add_co_u32_e64 v16, s[6:7], s0, v8
	v_lshl_add_u64 v[0:1], v[8:9], 0, v[0:1]
	s_nop 0
	v_addc_co_u32_e64 v17, s[6:7], 0, v9, s[6:7]
	s_movk_i32 s0, 0x3000
	global_load_dwordx4 v[102:105], v[10:11], off offset:2560 nt
	global_load_dwordx4 v[94:97], v[10:11], off offset:3584 nt
	global_load_dwordx4 v[74:77], v[12:13], off offset:2560 nt
	global_load_dwordx4 v[70:73], v[12:13], off offset:3584 nt
	global_load_dwordx4 v[58:61], v[14:15], off offset:2560 nt
	global_load_dwordx4 v[54:57], v[14:15], off offset:3584 nt
	global_load_dwordx4 v[4:7], v[0:1], off offset:2560 nt
	s_nop 0
	global_load_dwordx4 v[0:3], v[0:1], off offset:3584 nt
	v_lshlrev_b32_e32 v35, 2, v18
	global_load_dwordx4 v[110:113], v[8:9], off offset:3072 nt
	global_load_dwordx4 v[106:109], v[16:17], off nt
	global_load_dwordx4 v[82:85], v[10:11], off offset:3072 nt
	v_add_co_u32_e64 v10, s[6:7], s0, v8
	s_movk_i32 s0, 0x5000
	s_nop 0
	v_addc_co_u32_e64 v11, s[6:7], 0, v9, s[6:7]
	global_load_dwordx4 v[78:81], v[10:11], off nt
	global_load_dwordx4 v[66:69], v[12:13], off offset:3072 nt
	v_add_co_u32_e64 v10, s[6:7], s0, v8
	s_movk_i32 s0, 0x7000
	s_nop 0
	v_addc_co_u32_e64 v11, s[6:7], 0, v9, s[6:7]
	v_add_co_u32_e64 v8, s[6:7], s0, v8
	global_load_dwordx4 v[62:65], v[10:11], off nt
	global_load_dwordx4 v[28:31], v[14:15], off offset:3072 nt
	v_addc_co_u32_e64 v9, s[6:7], 0, v9, s[6:7]
	s_lshl_b64 s[6:7], s[8:9], 2
	s_add_u32 s6, s38, s6
	global_load_dwordx4 v[24:27], v[8:9], off nt
	s_addc_u32 s7, s39, s7
	global_load_dwordx4 v[8:11], v35, s[10:11] offset:16 nt
	global_load_dwordx4 v[38:41], v35, s[10:11] nt
	global_load_dwordx4 v[12:15], v35, s[6:7] offset:16 nt
	global_load_dwordx4 v[42:45], v35, s[6:7] nt
	global_load_dwordx4 v[16:19], v35, s[6:7] offset:1040 nt
	global_load_dwordx4 v[46:49], v35, s[6:7] offset:1024 nt
	global_load_dwordx4 v[20:23], v35, s[6:7] offset:2064 nt
	global_load_dwordx4 v[50:53], v35, s[6:7] offset:2048 nt
	v_cndmask_b32_e64 v114, 0, 1.0, vcc
	s_waitcnt vmcnt(14)
	v_lshlrev_b32_e32 v132, 16, v106
	v_mul_f32_e32 v35, 0xbfb8aa3b, v132
	v_exp_f32_e32 v35, v35
	v_and_b32_e32 v133, 0xffff0000, v106
	v_lshlrev_b32_e32 v120, 16, v116
	v_and_b32_e32 v121, 0xffff0000, v116
	v_add_f32_e32 v35, 1.0, v35
	v_rcp_f32_e32 v134, v35
	v_mul_f32_e32 v35, 0xbfb8aa3b, v133
	v_exp_f32_e32 v35, v35
	v_lshlrev_b32_e32 v128, 16, v117
	v_and_b32_e32 v129, 0xffff0000, v117
	v_lshlrev_b32_e32 v126, 16, v118
	v_and_b32_e32 v127, 0xffff0000, v118
	v_lshlrev_b32_e32 v124, 16, v119
	v_and_b32_e32 v125, 0xffff0000, v119
	v_lshlrev_b32_e32 v116, 16, v98
	v_and_b32_e32 v117, 0xffff0000, v98
	v_pk_mul_f32 v[118:119], v[122:123], v[120:121] op_sel_hi:[0,1]
	v_pk_mul_f32 v[120:121], v[118:119], v[116:117]
	v_lshlrev_b32_e32 v116, 16, v86
	v_and_b32_e32 v117, 0xffff0000, v86
	v_lshlrev_b32_e32 v118, 16, v90
	v_and_b32_e32 v119, 0xffff0000, v90
	v_pk_mul_f32 v[118:119], v[116:117], v[118:119]
	v_add_f32_e32 v35, 1.0, v35
	v_lshlrev_b32_e32 v116, 16, v102
	v_and_b32_e32 v117, 0xffff0000, v102
	v_lshlrev_b32_e32 v130, 16, v94
	v_and_b32_e32 v131, 0xffff0000, v94
	s_waitcnt vmcnt(2)
	v_pk_mul_f32 v[136:137], v[118:119], v[46:47]
	v_rcp_f32_e32 v135, v35
	v_pk_mul_f32 v[116:117], v[116:117], v[130:131]
	v_pk_fma_f32 v[120:121], v[120:121], v[42:43], v[136:137]
	v_lshlrev_b32_e32 v102, 16, v107
	s_waitcnt vmcnt(0)
	v_pk_fma_f32 v[120:121], v[116:117], v[50:51], v[120:121]
	v_lshlrev_b32_e32 v130, 16, v110
	v_and_b32_e32 v131, 0xffff0000, v110
	v_pk_add_f32 v[120:121], v[38:39], v[120:121]
	v_mul_f32_e32 v35, 0xbfb8aa3b, v102
	v_pk_mul_f32 v[120:121], v[120:121], v[130:131]
	v_pk_mul_f32 v[130:131], v[134:135], v[132:133]
	v_exp_f32_e32 v35, v35
	v_pk_mul_f32 v[120:121], v[130:131], v[120:121]
	v_lshlrev_b32_e32 v98, 16, v99
	v_cvt_pk_bf16_f32 v86, v120, v121
	v_and_b32_e32 v99, 0xffff0000, v99
	v_pk_mul_f32 v[120:121], v[122:123], v[128:129] op_sel_hi:[0,1]
	v_pk_mul_f32 v[98:99], v[120:121], v[98:99]
	v_lshlrev_b32_e32 v120, 16, v87
	v_and_b32_e32 v121, 0xffff0000, v87
	v_lshlrev_b32_e32 v90, 16, v91
	v_and_b32_e32 v91, 0xffff0000, v91
	v_pk_mul_f32 v[120:121], v[120:121], v[90:91]
	v_lshlrev_b32_e32 v90, 16, v103
	v_and_b32_e32 v91, 0xffff0000, v103
	v_and_b32_e32 v103, 0xffff0000, v107
	v_add_f32_e32 v35, 1.0, v35
	v_rcp_f32_e32 v106, v35
	v_mul_f32_e32 v35, 0xbfb8aa3b, v103
	v_exp_f32_e32 v35, v35
	v_lshlrev_b32_e32 v94, 16, v95
	v_and_b32_e32 v95, 0xffff0000, v95
	v_pk_mul_f32 v[94:95], v[90:91], v[94:95]
	v_lshlrev_b32_e32 v90, 16, v111
	v_and_b32_e32 v91, 0xffff0000, v111
	v_pk_mul_f32 v[110:111], v[120:121], v[48:49]
	v_add_f32_e32 v35, 1.0, v35
	v_pk_fma_f32 v[98:99], v[98:99], v[44:45], v[110:111]
	v_lshlrev_b32_e32 v110, 16, v108
	v_rcp_f32_e32 v107, v35
	v_mul_f32_e32 v35, 0xbfb8aa3b, v110
	v_exp_f32_e32 v35, v35
	v_pk_fma_f32 v[98:99], v[94:95], v[52:53], v[98:99]
	v_and_b32_e32 v111, 0xffff0000, v108
	v_pk_add_f32 v[98:99], v[40:41], v[98:99]
	v_add_f32_e32 v35, 1.0, v35
	v_pk_mul_f32 v[90:91], v[98:99], v[90:91]
	v_pk_mul_f32 v[98:99], v[106:107], v[102:103]
	v_lshlrev_b32_e32 v102, 16, v92
	v_pk_mul_f32 v[90:91], v[98:99], v[90:91]
	v_pk_mul_f32 v[98:99], v[122:123], v[126:127] op_sel_hi:[0,1]
	v_rcp_f32_e32 v126, v35
	v_mul_f32_e32 v35, 0xbfb8aa3b, v111
	v_exp_f32_e32 v35, v35
	v_cvt_pk_bf16_f32 v87, v90, v91
	v_lshlrev_b32_e32 v90, 16, v100
	v_and_b32_e32 v91, 0xffff0000, v100
	v_pk_mul_f32 v[90:91], v[98:99], v[90:91]
	v_lshlrev_b32_e32 v98, 16, v88
	v_and_b32_e32 v99, 0xffff0000, v88
	v_and_b32_e32 v103, 0xffff0000, v92
	v_pk_mul_f32 v[102:103], v[98:99], v[102:103]
	v_add_f32_e32 v35, 1.0, v35
	v_lshlrev_b32_e32 v98, 16, v104
	v_and_b32_e32 v99, 0xffff0000, v104
	v_lshlrev_b32_e32 v106, 16, v96
	v_and_b32_e32 v107, 0xffff0000, v96
	v_pk_mul_f32 v[128:129], v[102:103], v[16:17]
	v_rcp_f32_e32 v127, v35
	v_pk_mul_f32 v[98:99], v[98:99], v[106:107]
	v_pk_fma_f32 v[90:91], v[90:91], v[12:13], v[128:129]
	v_lshlrev_b32_e32 v104, 16, v109
	v_pk_fma_f32 v[90:91], v[98:99], v[20:21], v[90:91]
	v_lshlrev_b32_e32 v106, 16, v112
	v_and_b32_e32 v107, 0xffff0000, v112
	v_pk_add_f32 v[90:91], v[8:9], v[90:91]
	v_mul_f32_e32 v35, 0xbfb8aa3b, v104
	v_pk_mul_f32 v[90:91], v[90:91], v[106:107]
	v_pk_mul_f32 v[106:107], v[126:127], v[110:111]
	v_exp_f32_e32 v35, v35
	v_pk_mul_f32 v[90:91], v[106:107], v[90:91]
	v_lshlrev_b32_e32 v92, 16, v93
	v_cvt_pk_bf16_f32 v88, v90, v91
	v_lshlrev_b32_e32 v90, 16, v101
	v_and_b32_e32 v91, 0xffff0000, v101
	v_pk_mul_f32 v[100:101], v[122:123], v[124:125] op_sel_hi:[0,1]
	v_pk_mul_f32 v[90:91], v[100:101], v[90:91]
	v_lshlrev_b32_e32 v100, 16, v89
	v_and_b32_e32 v101, 0xffff0000, v89
	v_and_b32_e32 v93, 0xffff0000, v93
	v_pk_mul_f32 v[100:101], v[100:101], v[92:93]
	v_lshlrev_b32_e32 v92, 16, v105
	v_and_b32_e32 v93, 0xffff0000, v105
	v_and_b32_e32 v105, 0xffff0000, v109
	v_add_f32_e32 v35, 1.0, v35
	v_rcp_f32_e32 v106, v35
	v_mul_f32_e32 v35, 0xbfb8aa3b, v105
	v_exp_f32_e32 v35, v35
	v_lshlrev_b32_e32 v96, 16, v97
	v_and_b32_e32 v97, 0xffff0000, v97
	v_pk_mul_f32 v[108:109], v[100:101], v[18:19]
	v_add_f32_e32 v35, 1.0, v35
	v_rcp_f32_e32 v107, v35
	v_pk_mul_f32 v[92:93], v[92:93], v[96:97]
	v_pk_fma_f32 v[90:91], v[90:91], v[14:15], v[108:109]
	v_lshlrev_b32_e32 v96, 16, v113
	v_pk_fma_f32 v[90:91], v[92:93], v[22:23], v[90:91]
	v_and_b32_e32 v97, 0xffff0000, v113
	v_pk_add_f32 v[90:91], v[10:11], v[90:91]
	s_mov_b32 s0, 0x18c00000
	v_pk_mul_f32 v[90:91], v[90:91], v[96:97]
	v_pk_mul_f32 v[96:97], v[106:107], v[104:105]
	v_pk_mul_f32 v[106:107], v[116:117], v[46:47]
	v_pk_mul_f32 v[90:91], v[96:97], v[90:91]
	v_pk_fma_f32 v[106:107], v[118:119], v[42:43], v[106:107]
	v_cvt_pk_bf16_f32 v89, v90, v91
	v_mov_b64_e32 v[90:91], s[48:49]
	v_mad_i64_i32 v[96:97], s[6:7], v34, s44, v[90:91]
	v_lshl_add_u64 v[96:97], v[96:97], 0, v[32:33]
	v_add_co_u32_e32 v96, vcc, s0, v96
	s_mov_b64 s[10:11], 0
	s_nop 0
	v_addc_co_u32_e32 v97, vcc, 0, v97, vcc
	global_store_dwordx4 v[96:97], v[86:89], off offset:1024
	v_lshlrev_b32_e32 v96, 16, v78
	v_mul_f32_e32 v35, 0xbfb8aa3b, v96
	v_exp_f32_e32 v35, v35
	v_and_b32_e32 v97, 0xffff0000, v78
	v_lshlrev_b32_e32 v78, 16, v79
	v_lshlrev_b32_e32 v86, 16, v74
	v_add_f32_e32 v35, 1.0, v35
	v_rcp_f32_e32 v104, v35
	v_mul_f32_e32 v35, 0xbfb8aa3b, v97
	v_exp_f32_e32 v35, v35
	v_and_b32_e32 v87, 0xffff0000, v74
	v_lshlrev_b32_e32 v88, 16, v70
	v_and_b32_e32 v89, 0xffff0000, v70
	v_add_f32_e32 v35, 1.0, v35
	v_rcp_f32_e32 v105, v35
	v_mul_f32_e32 v35, 0xbfb8aa3b, v78
	v_exp_f32_e32 v35, v35
	v_and_b32_e32 v79, 0xffff0000, v79
	v_pk_mul_f32 v[88:89], v[86:87], v[88:89]
	v_lshlrev_b32_e32 v86, 16, v82
	v_add_f32_e32 v35, 1.0, v35
	v_and_b32_e32 v87, 0xffff0000, v82
	v_rcp_f32_e32 v82, v35
	v_mul_f32_e32 v35, 0xbfb8aa3b, v79
	v_pk_fma_f32 v[106:107], v[88:89], v[50:51], v[106:107]
	v_exp_f32_e32 v35, v35
	v_pk_add_f32 v[106:107], v[38:39], v[106:107]
	v_pk_mul_f32 v[96:97], v[104:105], v[96:97]
	v_pk_mul_f32 v[86:87], v[106:107], v[86:87]
	v_lshlrev_b32_e32 v74, 16, v75
	v_pk_mul_f32 v[86:87], v[96:97], v[86:87]
	v_and_b32_e32 v75, 0xffff0000, v75
	v_cvt_pk_bf16_f32 v70, v86, v87
	v_lshlrev_b32_e32 v86, 16, v71
	v_and_b32_e32 v87, 0xffff0000, v71
	v_add_f32_e32 v35, 1.0, v35
	v_pk_mul_f32 v[86:87], v[74:75], v[86:87]
	v_lshlrev_b32_e32 v74, 16, v83
	v_and_b32_e32 v75, 0xffff0000, v83
	v_rcp_f32_e32 v83, v35
	v_pk_mul_f32 v[96:97], v[94:95], v[48:49]
	v_pk_mul_f32 v[104:105], v[98:99], v[16:17]
	v_pk_fma_f32 v[96:97], v[120:121], v[44:45], v[96:97]
	v_pk_mul_f32 v[78:79], v[82:83], v[78:79]
	v_lshlrev_b32_e32 v82, 16, v80
	v_mul_f32_e32 v35, 0xbfb8aa3b, v82
	v_exp_f32_e32 v35, v35
	v_pk_fma_f32 v[96:97], v[86:87], v[52:53], v[96:97]
	v_and_b32_e32 v83, 0xffff0000, v80
	v_pk_add_f32 v[96:97], v[40:41], v[96:97]
	v_add_f32_e32 v35, 1.0, v35
	v_pk_mul_f32 v[74:75], v[96:97], v[74:75]
	v_rcp_f32_e32 v96, v35
	v_mul_f32_e32 v35, 0xbfb8aa3b, v83
	v_exp_f32_e32 v35, v35
	v_lshlrev_b32_e32 v80, 16, v81
	v_pk_mul_f32 v[74:75], v[78:79], v[74:75]
	v_lshlrev_b32_e32 v78, 16, v72
	v_add_f32_e32 v35, 1.0, v35
	v_rcp_f32_e32 v97, v35
	v_mul_f32_e32 v35, 0xbfb8aa3b, v80
	v_cvt_pk_bf16_f32 v71, v74, v75
	v_lshlrev_b32_e32 v74, 16, v76
	v_and_b32_e32 v75, 0xffff0000, v76
	v_and_b32_e32 v79, 0xffff0000, v72
	v_exp_f32_e32 v35, v35
	v_pk_mul_f32 v[78:79], v[74:75], v[78:79]
	v_pk_fma_f32 v[102:103], v[102:103], v[12:13], v[104:105]
	v_lshlrev_b32_e32 v74, 16, v84
	v_pk_fma_f32 v[102:103], v[78:79], v[20:21], v[102:103]
	v_and_b32_e32 v75, 0xffff0000, v84
	v_pk_add_f32 v[102:103], v[8:9], v[102:103]
	v_pk_mul_f32 v[82:83], v[96:97], v[82:83]
	v_pk_mul_f32 v[74:75], v[102:103], v[74:75]
	v_and_b32_e32 v81, 0xffff0000, v81
	v_add_f32_e32 v35, 1.0, v35
	v_pk_mul_f32 v[74:75], v[82:83], v[74:75]
	v_rcp_f32_e32 v82, v35
	v_mul_f32_e32 v35, 0xbfb8aa3b, v81
	v_exp_f32_e32 v35, v35
	v_cvt_pk_bf16_f32 v72, v74, v75
	v_lshlrev_b32_e32 v74, 16, v77
	v_and_b32_e32 v75, 0xffff0000, v77
	v_lshlrev_b32_e32 v76, 16, v73
	v_and_b32_e32 v77, 0xffff0000, v73
	v_add_f32_e32 v35, 1.0, v35
	v_pk_mul_f32 v[74:75], v[74:75], v[76:77]
	v_lshlrev_b32_e32 v76, 16, v85
	v_and_b32_e32 v77, 0xffff0000, v85
	v_pk_mul_f32 v[84:85], v[92:93], v[18:19]
	v_rcp_f32_e32 v83, v35
	v_pk_fma_f32 v[84:85], v[100:101], v[14:15], v[84:85]
	v_or_b32_e32 v35, 1, v34
	v_pk_fma_f32 v[84:85], v[74:75], v[22:23], v[84:85]
	v_pk_mul_f32 v[80:81], v[82:83], v[80:81]
	v_pk_add_f32 v[84:85], v[10:11], v[84:85]
	v_pk_mul_f32 v[82:83], v[88:89], v[46:47]
	v_pk_mul_f32 v[76:77], v[84:85], v[76:77]
	v_pk_fma_f32 v[82:83], v[116:117], v[42:43], v[82:83]
	v_pk_mul_f32 v[76:77], v[80:81], v[76:77]
	s_nop 0
	v_cvt_pk_bf16_f32 v73, v76, v77
	v_mad_i64_i32 v[76:77], s[6:7], v35, s44, v[90:91]
	v_lshl_add_u64 v[76:77], v[76:77], 0, v[32:33]
	v_add_co_u32_e32 v76, vcc, s0, v76
	s_nop 1
	v_addc_co_u32_e32 v77, vcc, 0, v77, vcc
	global_store_dwordx4 v[76:77], v[70:73], off offset:1024
	v_lshlrev_b32_e32 v76, 16, v62
	v_mul_f32_e32 v35, 0xbfb8aa3b, v76
	v_exp_f32_e32 v35, v35
	v_and_b32_e32 v77, 0xffff0000, v62
	v_lshlrev_b32_e32 v62, 16, v63
	v_lshlrev_b32_e32 v70, 16, v58
	v_add_f32_e32 v35, 1.0, v35
	v_rcp_f32_e32 v80, v35
	v_mul_f32_e32 v35, 0xbfb8aa3b, v77
	v_exp_f32_e32 v35, v35
	v_and_b32_e32 v71, 0xffff0000, v58
	v_lshlrev_b32_e32 v72, 16, v54
	v_and_b32_e32 v73, 0xffff0000, v54
	v_add_f32_e32 v35, 1.0, v35
	v_rcp_f32_e32 v81, v35
	v_mul_f32_e32 v35, 0xbfb8aa3b, v62
	v_exp_f32_e32 v35, v35
	v_and_b32_e32 v63, 0xffff0000, v63
	v_pk_mul_f32 v[72:73], v[70:71], v[72:73]
	v_lshlrev_b32_e32 v70, 16, v66
	v_add_f32_e32 v35, 1.0, v35
	v_and_b32_e32 v71, 0xffff0000, v66
	v_rcp_f32_e32 v66, v35
	v_mul_f32_e32 v35, 0xbfb8aa3b, v63
	v_pk_fma_f32 v[82:83], v[72:73], v[50:51], v[82:83]
	v_exp_f32_e32 v35, v35
	v_pk_add_f32 v[82:83], v[38:39], v[82:83]
	v_pk_mul_f32 v[76:77], v[80:81], v[76:77]
	v_pk_mul_f32 v[70:71], v[82:83], v[70:71]
	v_lshlrev_b32_e32 v58, 16, v59
	v_pk_mul_f32 v[70:71], v[76:77], v[70:71]
	v_and_b32_e32 v59, 0xffff0000, v59
	v_cvt_pk_bf16_f32 v54, v70, v71
	v_lshlrev_b32_e32 v70, 16, v55
	v_and_b32_e32 v71, 0xffff0000, v55
	v_add_f32_e32 v35, 1.0, v35
	v_pk_mul_f32 v[70:71], v[58:59], v[70:71]
	v_lshlrev_b32_e32 v58, 16, v67
	v_and_b32_e32 v59, 0xffff0000, v67
	v_rcp_f32_e32 v67, v35
	v_pk_mul_f32 v[76:77], v[86:87], v[48:49]
	v_pk_mul_f32 v[80:81], v[78:79], v[16:17]
	v_pk_fma_f32 v[76:77], v[94:95], v[44:45], v[76:77]
	v_pk_mul_f32 v[62:63], v[66:67], v[62:63]
	v_lshlrev_b32_e32 v66, 16, v64
	v_mul_f32_e32 v35, 0xbfb8aa3b, v66
	v_exp_f32_e32 v35, v35
	v_pk_fma_f32 v[76:77], v[70:71], v[52:53], v[76:77]
	v_and_b32_e32 v67, 0xffff0000, v64
	v_pk_add_f32 v[76:77], v[40:41], v[76:77]
	v_add_f32_e32 v35, 1.0, v35
	v_pk_mul_f32 v[58:59], v[76:77], v[58:59]
	v_rcp_f32_e32 v76, v35
	v_mul_f32_e32 v35, 0xbfb8aa3b, v67
	v_exp_f32_e32 v35, v35
	v_lshlrev_b32_e32 v64, 16, v65
	v_pk_mul_f32 v[58:59], v[62:63], v[58:59]
	v_lshlrev_b32_e32 v62, 16, v56
	v_add_f32_e32 v35, 1.0, v35
	v_rcp_f32_e32 v77, v35
	v_mul_f32_e32 v35, 0xbfb8aa3b, v64
	v_cvt_pk_bf16_f32 v55, v58, v59
	v_lshlrev_b32_e32 v58, 16, v60
	v_and_b32_e32 v59, 0xffff0000, v60
	v_and_b32_e32 v63, 0xffff0000, v56
	v_exp_f32_e32 v35, v35
	v_pk_mul_f32 v[62:63], v[58:59], v[62:63]
	v_pk_fma_f32 v[80:81], v[98:99], v[12:13], v[80:81]
	v_lshlrev_b32_e32 v58, 16, v68
	v_pk_fma_f32 v[80:81], v[62:63], v[20:21], v[80:81]
	v_and_b32_e32 v59, 0xffff0000, v68
	v_pk_add_f32 v[80:81], v[8:9], v[80:81]
	v_pk_mul_f32 v[66:67], v[76:77], v[66:67]
	v_pk_mul_f32 v[58:59], v[80:81], v[58:59]
	v_and_b32_e32 v65, 0xffff0000, v65
	v_add_f32_e32 v35, 1.0, v35
	v_pk_mul_f32 v[58:59], v[66:67], v[58:59]
	v_rcp_f32_e32 v66, v35
	v_mul_f32_e32 v35, 0xbfb8aa3b, v65
	v_exp_f32_e32 v35, v35
	v_cvt_pk_bf16_f32 v56, v58, v59
	v_lshlrev_b32_e32 v58, 16, v61
	v_and_b32_e32 v59, 0xffff0000, v61
	v_lshlrev_b32_e32 v60, 16, v57
	v_and_b32_e32 v61, 0xffff0000, v57
	v_add_f32_e32 v35, 1.0, v35
	v_pk_mul_f32 v[58:59], v[58:59], v[60:61]
	v_lshlrev_b32_e32 v60, 16, v69
	v_and_b32_e32 v61, 0xffff0000, v69
	v_pk_mul_f32 v[68:69], v[74:75], v[18:19]
	v_rcp_f32_e32 v67, v35
	v_pk_fma_f32 v[68:69], v[92:93], v[14:15], v[68:69]
	v_or_b32_e32 v35, 2, v34
	v_pk_fma_f32 v[68:69], v[58:59], v[22:23], v[68:69]
	v_pk_mul_f32 v[64:65], v[66:67], v[64:65]
	v_pk_add_f32 v[68:69], v[10:11], v[68:69]
	v_pk_mul_f32 v[46:47], v[72:73], v[46:47]
	v_pk_mul_f32 v[60:61], v[68:69], v[60:61]
	v_pk_fma_f32 v[42:43], v[88:89], v[42:43], v[46:47]
	v_pk_mul_f32 v[60:61], v[64:65], v[60:61]
	v_pk_mul_f32 v[16:17], v[62:63], v[16:17]
	v_cvt_pk_bf16_f32 v57, v60, v61
	v_mad_i64_i32 v[60:61], s[6:7], v35, s44, v[90:91]
	v_lshl_add_u64 v[60:61], v[60:61], 0, v[32:33]
	v_add_co_u32_e32 v60, vcc, s0, v60
	v_pk_fma_f32 v[12:13], v[78:79], v[12:13], v[16:17]
	s_nop 0
	v_addc_co_u32_e32 v61, vcc, 0, v61, vcc
	global_store_dwordx4 v[60:61], v[54:57], off offset:1024
	v_lshlrev_b32_e32 v60, 16, v24
	v_and_b32_e32 v61, 0xffff0000, v24
	v_lshlrev_b32_e32 v56, 16, v0
	v_and_b32_e32 v57, 0xffff0000, v0
	v_mul_f32_e32 v0, 0xbfb8aa3b, v60
	v_exp_f32_e32 v0, v0
	v_lshlrev_b32_e32 v54, 16, v4
	v_and_b32_e32 v55, 0xffff0000, v4
	v_pk_mul_f32 v[54:55], v[114:115], v[54:55] op_sel_hi:[0,1]
	v_add_f32_e32 v0, 1.0, v0
	v_rcp_f32_e32 v64, v0
	v_mul_f32_e32 v0, 0xbfb8aa3b, v61
	v_exp_f32_e32 v0, v0
	v_pk_mul_f32 v[54:55], v[54:55], v[56:57]
	v_lshlrev_b32_e32 v56, 16, v28
	v_pk_fma_f32 v[42:43], v[54:55], v[50:51], v[42:43]
	v_add_f32_e32 v0, 1.0, v0
	v_rcp_f32_e32 v65, v0
	v_and_b32_e32 v57, 0xffff0000, v28
	v_pk_add_f32 v[38:39], v[38:39], v[42:43]
	v_lshlrev_b32_e32 v24, 16, v25
	v_pk_mul_f32 v[38:39], v[38:39], v[56:57]
	v_pk_mul_f32 v[42:43], v[64:65], v[60:61]
	v_lshlrev_b32_e32 v4, 16, v5
	v_pk_mul_f32 v[38:39], v[42:43], v[38:39]
	v_and_b32_e32 v5, 0xffff0000, v5
	v_cvt_pk_bf16_f32 v0, v38, v39
	v_lshlrev_b32_e32 v38, 16, v1
	v_and_b32_e32 v39, 0xffff0000, v1
	v_mul_f32_e32 v1, 0xbfb8aa3b, v24
	v_exp_f32_e32 v1, v1
	v_pk_mul_f32 v[4:5], v[114:115], v[4:5] op_sel_hi:[0,1]
	v_and_b32_e32 v25, 0xffff0000, v25
	v_pk_mul_f32 v[4:5], v[4:5], v[38:39]
	v_add_f32_e32 v1, 1.0, v1
	v_rcp_f32_e32 v38, v1
	v_mul_f32_e32 v1, 0xbfb8aa3b, v25
	v_exp_f32_e32 v1, v1
	v_pk_mul_f32 v[42:43], v[70:71], v[48:49]
	v_lshlrev_b32_e32 v28, 16, v29
	v_pk_fma_f32 v[42:43], v[86:87], v[44:45], v[42:43]
	v_add_f32_e32 v1, 1.0, v1
	v_rcp_f32_e32 v39, v1
	v_pk_fma_f32 v[4:5], v[4:5], v[52:53], v[42:43]
	v_and_b32_e32 v29, 0xffff0000, v29
	v_pk_add_f32 v[4:5], v[40:41], v[4:5]
	v_pk_mul_f32 v[24:25], v[38:39], v[24:25]
	v_pk_mul_f32 v[4:5], v[4:5], v[28:29]
	v_lshlrev_b32_e32 v28, 16, v26
	v_pk_mul_f32 v[4:5], v[24:25], v[4:5]
	v_lshlrev_b32_e32 v24, 16, v2
	v_and_b32_e32 v25, 0xffff0000, v2
	v_mul_f32_e32 v2, 0xbfb8aa3b, v28
	v_exp_f32_e32 v2, v2
	v_and_b32_e32 v29, 0xffff0000, v26
	v_cvt_pk_bf16_f32 v1, v4, v5
	v_lshlrev_b32_e32 v4, 16, v6
	v_add_f32_e32 v2, 1.0, v2
	v_rcp_f32_e32 v38, v2
	v_mul_f32_e32 v2, 0xbfb8aa3b, v29
	v_exp_f32_e32 v2, v2
	v_and_b32_e32 v5, 0xffff0000, v6
	v_pk_mul_f32 v[4:5], v[114:115], v[4:5] op_sel_hi:[0,1]
	v_pk_mul_f32 v[4:5], v[4:5], v[24:25]
	v_add_f32_e32 v2, 1.0, v2
	v_rcp_f32_e32 v39, v2
	v_pk_fma_f32 v[4:5], v[4:5], v[20:21], v[12:13]
	v_lshlrev_b32_e32 v24, 16, v30
	v_and_b32_e32 v25, 0xffff0000, v30
	v_pk_add_f32 v[4:5], v[8:9], v[4:5]
	v_pk_mul_f32 v[8:9], v[38:39], v[28:29]
	v_pk_mul_f32 v[4:5], v[4:5], v[24:25]
	v_lshlrev_b32_e32 v6, 16, v3
	v_pk_mul_f32 v[4:5], v[8:9], v[4:5]
	v_lshlrev_b32_e32 v8, 16, v27
	v_cvt_pk_bf16_f32 v2, v4, v5
	v_lshlrev_b32_e32 v4, 16, v7
	v_and_b32_e32 v5, 0xffff0000, v7
	v_and_b32_e32 v7, 0xffff0000, v3
	v_mul_f32_e32 v3, 0xbfb8aa3b, v8
	v_exp_f32_e32 v3, v3
	v_and_b32_e32 v9, 0xffff0000, v27
	v_pk_mul_f32 v[4:5], v[114:115], v[4:5] op_sel_hi:[0,1]
	v_pk_mul_f32 v[16:17], v[58:59], v[18:19]
	v_add_f32_e32 v3, 1.0, v3
	v_rcp_f32_e32 v12, v3
	v_mul_f32_e32 v3, 0xbfb8aa3b, v9
	v_exp_f32_e32 v3, v3
	v_pk_mul_f32 v[4:5], v[4:5], v[6:7]
	v_pk_fma_f32 v[14:15], v[74:75], v[14:15], v[16:17]
	v_lshlrev_b32_e32 v6, 16, v31
	v_add_f32_e32 v3, 1.0, v3
	v_rcp_f32_e32 v13, v3
	v_pk_fma_f32 v[4:5], v[4:5], v[22:23], v[14:15]
	v_and_b32_e32 v7, 0xffff0000, v31
	v_pk_add_f32 v[4:5], v[10:11], v[4:5]
	s_nop 0
	v_pk_mul_f32 v[4:5], v[4:5], v[6:7]
	v_pk_mul_f32 v[6:7], v[12:13], v[8:9]
	s_nop 0
	v_pk_mul_f32 v[4:5], v[6:7], v[4:5]
	s_nop 0
	v_cvt_pk_bf16_f32 v3, v4, v5
	v_or_b32_e32 v4, 3, v34
	v_mad_i64_i32 v[4:5], s[6:7], v4, s44, v[90:91]
	v_lshl_add_u64 v[4:5], v[4:5], 0, v[32:33]
	v_add_co_u32_e32 v4, vcc, 0x18c00000, v4
	s_nop 1
	v_addc_co_u32_e32 v5, vcc, 0, v5, vcc
	global_store_dwordx4 v[4:5], v[0:3], off offset:1024
	s_branch .LBB0_660

.LBB0_680:
	s_or_b64 exec, exec, s[18:19]
	s_lshr_b32 s8, s8, 2
	s_lshl_b32 s18, s21, 7
	s_cmp_lt_u32 s21, 2
	s_movk_i32 s21, 0xff00
	s_cselect_b32 s19, 8, 12
	s_cselect_b32 s21, 0x4000, s21
	s_lshl_b32 s8, s8, s19
	s_add_i32 s18, s21, s18
	s_add_i32 s8, s18, s8
	s_lshl_b32 s92, s20, 7
	v_lshlrev_b32_e32 v24, 3, v206
	v_ashrrev_i32_e32 v43, 3, v206
	s_add_u32 s18, s70, s92
	v_and_b32_e32 v40, 56, v24
	v_add_u32_e32 v2, s8, v43
	v_add_u32_e32 v25, 0x200, v206
	s_addc_u32 s19, s71, 0
	v_lshlrev_b32_e32 v32, 1, v40
	v_ashrrev_i32_e32 v3, 31, v2
	v_ashrrev_i32_e32 v42, 3, v25
	v_lshl_add_u64 v[0:1], s[18:19], 0, v[32:33]
	v_lshlrev_b64 v[2:3], 13, v[2:3]
	v_add_u32_e32 v4, s8, v42
	v_lshl_add_u64 v[2:3], v[0:1], 0, v[2:3]
	s_movk_i32 s18, 0x1000
	v_ashrrev_i32_e32 v5, 31, v4
	v_add_co_u32_e32 v2, vcc, s18, v2
	v_lshlrev_b64 v[4:5], 13, v[4:5]
	s_nop 0
	v_addc_co_u32_e32 v3, vcc, 0, v3, vcc
	v_lshl_add_u64 v[0:1], v[0:1], 0, v[4:5]
	v_add_co_u32_e32 v0, vcc, s18, v0
	v_readlane_b32 s18, v254, 52
	v_and_b32_e32 v37, 15, v206
	s_add_i32 s18, s8, s18
	v_or_b32_e32 v28, s18, v37
	v_ashrrev_i32_e32 v29, 31, v28
	v_lshlrev_b64 v[28:29], 13, v[28:29]
	v_lshrrev_b32_e32 v41, 4, v207
	v_lshl_add_u64 v[28:29], s[70:71], 0, v[28:29]
	v_lshl_add_u64 v[28:29], v[28:29], 0, s[92:93]
	v_lshlrev_b32_e32 v38, 3, v41
	v_mov_b32_e32 v39, v33
	v_addc_co_u32_e32 v1, vcc, 0, v1, vcc
	v_lshl_add_u64 v[28:29], v[28:29], 0, v[38:39]
	s_mov_b64 s[18:19], 0x1800
	v_lshl_add_u64 v[30:31], v[28:29], 0, s[18:19]
	v_add_co_u32_e32 v28, vcc, 0x1000, v28
	global_load_dwordx4 v[16:19], v[2:3], off offset:512 nt
	global_load_dwordx4 v[20:23], v[2:3], off offset:1024 nt
	v_addc_co_u32_e32 v29, vcc, 0, v29, vcc
	global_load_dwordx4 v[8:11], v[2:3], off offset:1536 nt
	global_load_dwordx4 v[4:7], v[0:1], off offset:512 nt
	global_load_dwordx4 v[12:15], v[0:1], off offset:1024 nt
	s_nop 0
	global_load_dwordx4 v[0:3], v[0:1], off offset:1536 nt
	s_nop 0
	global_load_dwordx2 v[66:67], v[28:29], off offset:2048 nt
	global_load_dwordx2 v[64:65], v[30:31], off offset:32 nt
	global_load_dwordx2 v[62:63], v[30:31], off offset:64 nt
	global_load_dwordx2 v[34:35], v[30:31], off offset:96 nt
	s_and_saveexec_b64 s[100:101], s[6:7]
	s_cbranch_execz .Lr2p_skip
	s_waitcnt vmcnt(10)
	v_cmp_gt_u32_e32 vcc, 4, v236
	s_orn2_b64 s[16:17], vcc, exec

.LBB0_731:
	s_or_b64 exec, exec, s[12:13]
	s_add_i32 s21, s21, s19
	v_or_b32_e32 v32, s21, v25
	v_lshlrev_b32_e32 v32, 13, v32
	v_lshl_add_u64 v[54:55], v[8:9], 0, v[32:33]
	v_or_b32_e32 v32, s21, v26
	v_lshlrev_b32_e32 v32, 13, v32
	v_lshl_add_u64 v[58:59], v[10:11], 0, v[32:33]
	v_or_b32_e32 v32, s21, v27
	v_lshlrev_b32_e32 v32, 13, v32
	v_lshl_add_u64 v[62:63], v[12:13], 0, v[32:33]
	v_or_b32_e32 v32, s21, v28
	v_lshlrev_b32_e32 v32, 13, v32
	v_lshl_add_u64 v[66:67], v[14:15], 0, v[32:33]
	v_or_b32_e32 v32, s21, v29
	v_lshlrev_b32_e32 v32, 13, v32
	v_lshl_add_u64 v[70:71], v[16:17], 0, v[32:33]
	v_or_b32_e32 v32, s21, v30
	v_lshlrev_b32_e32 v32, 13, v32
	v_lshl_add_u64 v[74:75], v[18:19], 0, v[32:33]
	v_or_b32_e32 v32, s21, v31
	v_lshlrev_b32_e32 v32, 13, v32
	v_lshl_add_u64 v[78:79], v[20:21], 0, v[32:33]
	v_or_b32_e32 v32, s21, v34
	v_lshlrev_b32_e32 v32, 13, v32
	v_lshl_add_u64 v[82:83], v[22:23], 0, v[32:33]
	global_load_dwordx4 v[54:57], v[54:55], off nt
	s_nop 0
	global_load_dwordx4 v[58:61], v[58:59], off nt
	s_nop 0
	global_load_dwordx4 v[62:65], v[62:63], off nt
	s_nop 0
	global_load_dwordx4 v[66:69], v[66:67], off nt
	s_nop 0
	global_load_dwordx4 v[70:73], v[70:71], off nt
	s_nop 0
	global_load_dwordx4 v[74:77], v[74:75], off nt
	s_nop 0
	global_load_dwordx4 v[78:81], v[78:79], off nt
	s_nop 0
	global_load_dwordx4 v[82:85], v[82:83], off nt
	v_add_u32_e32 v32, s65, v37
	s_waitcnt vmcnt(7)
	ds_write_b128 v41, v[54:57]
	s_waitcnt vmcnt(6)
	ds_write_b128 v42, v[58:61]
	s_waitcnt vmcnt(5)
	ds_write_b128 v43, v[62:65]
	s_waitcnt vmcnt(4)
	ds_write_b128 v44, v[66:69]
	s_waitcnt vmcnt(3)
	ds_write_b128 v45, v[70:73]
	s_waitcnt vmcnt(2)
	ds_write_b128 v46, v[74:77]
	s_waitcnt vmcnt(1)
	ds_write_b128 v47, v[78:81]
	s_waitcnt vmcnt(0)
	ds_write_b128 v48, v[82:85]
	s_waitcnt lgkmcnt(0)
	s_barrier
	ds_read_b64_tr_b16 v[56:57], v32 offset:2176
	ds_read_b64_tr_b16 v[60:61], v32 offset:2208
	ds_read_b64_tr_b16 v[62:63], v49
	ds_read_b64_tr_b16 v[58:59], v32 offset:32
	ds_read_b64_tr_b16 v[64:65], v49 offset:2176
	ds_read_b64_tr_b16 v[68:69], v49 offset:2208
	ds_read_b64_tr_b16 v[66:67], v49 offset:32
	ds_read_b64_tr_b16 v[54:55], v32
	ds_read_b128 v[70:73], v38
	ds_read_b128 v[74:77], v50
	s_waitcnt lgkmcnt(0)
	v_mfma_f32_16x16x32_bf16 v[4:7], v[54:57], v[74:77], v[4:7]
	v_mfma_f32_16x16x32_bf16 v[0:3], v[58:61], v[74:77], v[0:3]
	ds_read_b64_tr_b16 v[56:57], v51 offset:2176
	ds_read_b64_tr_b16 v[60:61], v51 offset:2208
	ds_read_b64_tr_b16 v[58:59], v51 offset:32
	ds_read_b64_tr_b16 v[54:55], v51
	ds_read_b128 v[74:77], v39
	v_mfma_f32_16x16x32_bf16 v[4:7], v[62:65], v[70:73], v[4:7]
	v_mfma_f32_16x16x32_bf16 v[0:3], v[66:69], v[70:73], v[0:3]
	ds_read_b64_tr_b16 v[64:65], v52 offset:2176
	ds_read_b64_tr_b16 v[68:69], v52 offset:2208
	ds_read_b64_tr_b16 v[66:67], v52 offset:32
	ds_read_b64_tr_b16 v[62:63], v52
	ds_read_b128 v[70:73], v40
	s_waitcnt lgkmcnt(5)
	v_mfma_f32_16x16x32_bf16 v[4:7], v[54:57], v[74:77], v[4:7]
	v_mfma_f32_16x16x32_bf16 v[0:3], v[58:61], v[74:77], v[0:3]
	s_waitcnt lgkmcnt(0)
	v_mfma_f32_16x16x32_bf16 v[4:7], v[62:65], v[70:73], v[4:7]
	v_mfma_f32_16x16x32_bf16 v[0:3], v[66:69], v[70:73], v[0:3]
	s_add_i32 s20, s20, 1
	s_cmp_eq_u32 s20, 4
	s_cbranch_scc1 .LBB0_739

.LBB0_739:
	s_and_b32 s6, s18, 0xf0
	v_or_b32_e32 v8, s6, v35
	v_or_b32_e32 v8, s0, v8
	v_or_b32_e32 v12, 0x4000, v8
	v_lshrrev_b32_e32 v8, 2, v206
	v_lshlrev_b32_e32 v32, 13, v12
	v_and_b32_e32 v20, 12, v8
	v_lshl_add_u64 v[8:9], s[70:71], 0, v[32:33]
	s_mov_b64 s[6:7], 0x1e00
	v_lshl_add_u64 v[10:11], v[8:9], 0, s[6:7]
	v_mov_b64_e32 v[8:9], s[48:49]
	v_readlane_b32 s0, v254, 50
	v_mad_u64_u32 v[8:9], s[6:7], v12, s44, v[8:9]
	s_nop 0
	v_or_b32_e32 v12, s0, v20
	v_ashrrev_i32_e32 v13, 31, v12
	v_lshlrev_b64 v[12:13], 1, v[12:13]
	v_lshl_add_u64 v[14:15], v[10:11], 0, v[12:13]
	global_load_dwordx2 v[14:15], v[14:15], off nt
	s_brev_b32 s0, 60
	v_pk_mul_f32 v[4:5], v[4:5], s[0:1] op_sel_hi:[1,0]
	s_mov_b64 s[6:7], 0x18c00800
	v_pk_mul_f32 v[6:7], v[6:7], s[0:1] op_sel_hi:[1,0]
	v_lshl_add_u64 v[8:9], v[8:9], 0, s[6:7]
	v_readlane_b32 s6, v254, 51
	v_pk_mul_f32 v[0:1], v[0:1], s[0:1] op_sel_hi:[1,0]
	v_pk_mul_f32 v[2:3], v[2:3], s[0:1] op_sel_hi:[1,0]
	s_mov_b32 s18, s94
	s_waitcnt vmcnt(0)
	v_lshlrev_b32_e32 v16, 16, v14
	v_and_b32_e32 v17, 0xffff0000, v14
	v_mul_f32_e32 v14, 0xbfb8aa3b, v16
	v_exp_f32_e32 v14, v14
	s_nop 0
	v_add_f32_e32 v14, 1.0, v14
	v_rcp_f32_e32 v18, v14
	v_mul_f32_e32 v14, 0xbfb8aa3b, v17
	v_exp_f32_e32 v14, v14
	s_nop 0
	v_add_f32_e32 v14, 1.0, v14
	v_rcp_f32_e32 v19, v14
	v_lshlrev_b32_e32 v14, 16, v15
	v_and_b32_e32 v15, 0xffff0000, v15
	v_pk_mul_f32 v[16:17], v[18:19], v[16:17]
	s_nop 0
	v_pk_mul_f32 v[4:5], v[4:5], v[16:17]
	s_nop 0
	v_cvt_pk_bf16_f32 v4, v4, v5
	v_mul_f32_e32 v5, 0xbfb8aa3b, v14
	v_exp_f32_e32 v5, v5
	s_nop 0
	v_add_f32_e32 v5, 1.0, v5
	v_rcp_f32_e32 v16, v5
	v_mul_f32_e32 v5, 0xbfb8aa3b, v15
	v_exp_f32_e32 v5, v5
	s_nop 0
	v_add_f32_e32 v5, 1.0, v5
	v_rcp_f32_e32 v17, v5
	s_nop 0
	v_pk_mul_f32 v[14:15], v[16:17], v[14:15]
	s_nop 0
	v_pk_mul_f32 v[6:7], v[6:7], v[14:15]
	s_nop 0
	v_cvt_pk_bf16_f32 v5, v6, v7
	v_lshl_add_u64 v[6:7], v[8:9], 0, v[12:13]
	global_store_dwordx2 v[6:7], v[4:5], off
	v_or_b32_e32 v4, s6, v20
	v_ashrrev_i32_e32 v5, 31, v4
	v_lshlrev_b64 v[4:5], 1, v[4:5]
	v_lshl_add_u64 v[6:7], v[10:11], 0, v[4:5]
	global_load_dwordx2 v[6:7], v[6:7], off nt
	s_mov_b64 s[6:7], s[76:77]
	s_waitcnt vmcnt(0)
	v_lshlrev_b32_e32 v10, 16, v6
	v_and_b32_e32 v11, 0xffff0000, v6
	v_mul_f32_e32 v6, 0xbfb8aa3b, v10
	v_exp_f32_e32 v6, v6
	s_nop 0
	v_add_f32_e32 v6, 1.0, v6
	v_rcp_f32_e32 v12, v6
	v_mul_f32_e32 v6, 0xbfb8aa3b, v11
	v_exp_f32_e32 v6, v6
	s_nop 0
	v_add_f32_e32 v6, 1.0, v6
	v_rcp_f32_e32 v13, v6
	v_lshlrev_b32_e32 v6, 16, v7
	v_and_b32_e32 v7, 0xffff0000, v7
	v_pk_mul_f32 v[10:11], v[12:13], v[10:11]
	s_nop 0
	v_pk_mul_f32 v[0:1], v[0:1], v[10:11]
	s_nop 0
	v_cvt_pk_bf16_f32 v0, v0, v1
	v_mul_f32_e32 v1, 0xbfb8aa3b, v6
	v_exp_f32_e32 v1, v1
	s_nop 0
	v_add_f32_e32 v1, 1.0, v1
	v_rcp_f32_e32 v10, v1
	v_mul_f32_e32 v1, 0xbfb8aa3b, v7
	v_exp_f32_e32 v1, v1
	s_nop 0
	v_add_f32_e32 v1, 1.0, v1
	v_rcp_f32_e32 v11, v1
	s_nop 0
	v_pk_mul_f32 v[6:7], v[10:11], v[6:7]
	s_nop 0
	v_pk_mul_f32 v[2:3], v[2:3], v[6:7]
	s_nop 0
	v_cvt_pk_bf16_f32 v1, v2, v3
	v_lshl_add_u64 v[2:3], v[8:9], 0, v[4:5]
	global_store_dwordx2 v[2:3], v[0:1], off

.LBB0_741:
	s_andn2_b64 vcc, exec, s[12:13]
	s_cbranch_vccnz .LBB0_743
	s_lshr_b32 s0, s61, 6
	v_lshlrev_b32_e32 v0, 3, v206
	v_ashrrev_i32_e32 v37, 5, v206
	s_and_b32 s8, s61, 63
	s_lshl_b32 s6, s0, 12
	v_and_b32_e32 v34, 0xf8, v0
	v_lshlrev_b32_e32 v0, 6, v37
	s_or_b32 s6, s6, s8
	v_and_b32_e32 v0, 0xfc0, v0
	v_or_b32_e32 v0, s6, v0
	v_add_u32_e32 v35, 0x200, v206
	v_lshlrev_b32_e32 v32, 13, v0
	v_cmp_gt_u32_e32 vcc, 64, v37
	v_ashrrev_i32_e32 v38, 5, v35
	v_add_u32_e32 v39, 0x400, v206
	v_lshl_add_u64 v[0:1], s[70:71], 0, v[32:33]
	v_cndmask_b32_e32 v32, v240, v238, vcc
	v_cmp_gt_u32_e32 vcc, 64, v38
	v_ashrrev_i32_e32 v40, 5, v39
	v_add_u32_e32 v41, 0x600, v206
	v_add_u32_e32 v43, 0x800, v206
	v_add_u32_e32 v47, 0xc00, v206
	v_cndmask_b32_e32 v4, v240, v238, vcc
	v_cmp_gt_u32_e32 vcc, 64, v40
	v_ashrrev_i32_e32 v42, 5, v41
	v_ashrrev_i32_e32 v44, 5, v43
	v_ashrrev_i32_e32 v48, 5, v47
	v_lshlrev_b32_e32 v8, 6, v40
	v_cndmask_b32_e32 v10, v240, v238, vcc
	v_cmp_gt_u32_e32 vcc, 64, v42
	v_lshlrev_b32_e32 v16, 6, v44
	v_add_u32_e32 v45, 0xa00, v206
	v_lshlrev_b32_e32 v24, 6, v48
	v_and_b32_e32 v8, 0xfc0, v8
	v_cndmask_b32_e32 v12, v240, v238, vcc
	v_and_b32_e32 v16, 0xfc0, v16
	v_cmp_gt_u32_e32 vcc, 64, v44
	v_ashrrev_i32_e32 v46, 5, v45
	v_and_b32_e32 v24, 0xfc0, v24
	v_or_b32_e32 v8, s6, v8
	v_or_b32_e32 v16, s6, v16
	v_cndmask_b32_e32 v18, v240, v238, vcc
	v_cmp_gt_u32_e32 vcc, 64, v46
	v_or_b32_e32 v24, s6, v24
	v_lshlrev_b32_e32 v8, 13, v8
	v_mov_b32_e32 v9, v33
	v_lshlrev_b32_e32 v16, 13, v16
	v_mov_b32_e32 v17, v33
	v_cndmask_b32_e32 v20, v240, v238, vcc
	v_lshlrev_b32_e32 v24, 13, v24
	v_mov_b32_e32 v25, v33
	v_cmp_gt_u32_e32 vcc, 64, v48
	v_add_u32_e32 v49, 0xe00, v206
	v_lshl_add_u64 v[8:9], s[70:71], 0, v[8:9]
	v_mov_b32_e32 v11, v33
	v_lshl_add_u64 v[16:17], s[70:71], 0, v[16:17]
	v_mov_b32_e32 v19, v33
	v_lshl_add_u64 v[24:25], s[70:71], 0, v[24:25]
	v_cndmask_b32_e32 v26, v240, v238, vcc
	v_mov_b32_e32 v27, v33
	v_ashrrev_i32_e32 v50, 5, v49
	v_lshlrev_b32_e32 v2, 6, v38
	v_lshl_add_u64 v[8:9], v[8:9], 0, v[10:11]
	v_lshlrev_b32_e32 v10, 6, v42
	v_lshl_add_u64 v[16:17], v[16:17], 0, v[18:19]
	v_lshlrev_b32_e32 v18, 6, v46
	v_lshl_add_u64 v[24:25], v[24:25], 0, v[26:27]
	v_lshlrev_b32_e32 v26, 6, v50
	v_and_b32_e32 v2, 0xfc0, v2
	v_and_b32_e32 v10, 0xfc0, v10
	v_and_b32_e32 v18, 0xfc0, v18
	v_and_b32_e32 v26, 0xfc0, v26
	v_or_b32_e32 v2, s6, v2
	v_or_b32_e32 v10, s6, v10
	v_or_b32_e32 v18, s6, v18
	v_or_b32_e32 v26, s6, v26
	v_lshlrev_b32_e32 v2, 13, v2
	v_mov_b32_e32 v3, v33
	v_lshlrev_b32_e32 v10, 13, v10
	v_lshlrev_b32_e32 v18, 13, v18
	v_lshlrev_b32_e32 v26, 13, v26
	v_cmp_gt_u32_e32 vcc, 64, v50
	v_lshl_add_u64 v[2:3], s[70:71], 0, v[2:3]
	v_mov_b32_e32 v5, v33
	v_lshl_add_u64 v[10:11], s[70:71], 0, v[10:11]
	v_mov_b32_e32 v13, v33
	v_lshl_add_u64 v[18:19], s[70:71], 0, v[18:19]
	v_mov_b32_e32 v21, v33
	v_lshl_add_u64 v[26:27], s[70:71], 0, v[26:27]
	v_cndmask_b32_e32 v28, v240, v238, vcc
	v_mov_b32_e32 v29, v33
	v_lshl_add_u64 v[0:1], v[0:1], 0, v[32:33]
	v_lshlrev_b32_e32 v32, 1, v34
	v_lshl_add_u64 v[2:3], v[2:3], 0, v[4:5]
	v_lshl_add_u64 v[10:11], v[10:11], 0, v[12:13]
	v_lshl_add_u64 v[18:19], v[18:19], 0, v[20:21]
	v_lshl_add_u64 v[26:27], v[26:27], 0, v[28:29]
	v_lshl_add_u64 v[0:1], v[0:1], 0, v[32:33]
	v_lshl_add_u64 v[4:5], v[2:3], 0, v[32:33]
	v_lshl_add_u64 v[8:9], v[8:9], 0, v[32:33]
	v_lshl_add_u64 v[12:13], v[10:11], 0, v[32:33]
	v_lshl_add_u64 v[16:17], v[16:17], 0, v[32:33]
	v_lshl_add_u64 v[20:21], v[18:19], 0, v[32:33]
	v_lshl_add_u64 v[24:25], v[24:25], 0, v[32:33]
	v_lshl_add_u64 v[28:29], v[26:27], 0, v[32:33]
	s_barrier
	global_load_dwordx4 v[0:3], v[0:1], off nt
	s_nop 0
	global_load_dwordx4 v[4:7], v[4:5], off nt
	s_nop 0
	global_load_dwordx4 v[8:11], v[8:9], off nt
	s_nop 0
	global_load_dwordx4 v[12:15], v[12:13], off nt
	s_nop 0
	global_load_dwordx4 v[16:19], v[16:17], off nt
	s_nop 0
	global_load_dwordx4 v[20:23], v[20:21], off nt
	s_nop 0
	global_load_dwordx4 v[24:27], v[24:25], off nt
	s_nop 0
	global_load_dwordx4 v[28:31], v[28:29], off nt
	s_mov_b32 s18, 1
	v_mad_u64_u32 v[52:53], s[6:7], v37, s33, v[34:35]
	v_lshl_add_u32 v32, v52, 1, 0
	s_waitcnt vmcnt(7)
	ds_write_b128 v32, v[0:3]
	v_mad_u64_u32 v[0:1], s[6:7], v38, s33, v[34:35]
	v_lshl_add_u32 v0, v0, 1, 0
	s_waitcnt vmcnt(6)
	ds_write_b128 v0, v[4:7]
	v_mad_u64_u32 v[0:1], s[6:7], v40, s33, v[34:35]
	v_lshl_add_u32 v0, v0, 1, 0
	s_waitcnt vmcnt(5)
	ds_write_b128 v0, v[8:11]
	v_mad_u64_u32 v[0:1], s[6:7], v42, s33, v[34:35]
	v_lshl_add_u32 v0, v0, 1, 0
	s_waitcnt vmcnt(4)
	ds_write_b128 v0, v[12:15]
	v_mad_u64_u32 v[0:1], s[6:7], v44, s33, v[34:35]
	v_lshl_add_u32 v0, v0, 1, 0
	s_waitcnt vmcnt(3)
	ds_write_b128 v0, v[16:19]
	v_mad_u64_u32 v[0:1], s[6:7], v46, s33, v[34:35]
	v_lshl_add_u32 v0, v0, 1, 0
	s_waitcnt vmcnt(2)
	ds_write_b128 v0, v[20:23]
	v_mad_u64_u32 v[0:1], s[6:7], v48, s33, v[34:35]
	v_lshl_add_u32 v0, v0, 1, 0
	s_waitcnt vmcnt(1)
	ds_write_b128 v0, v[24:27]
	v_mad_u64_u32 v[0:1], s[6:7], v50, s33, v[34:35]
	v_lshl_add_u32 v0, v0, 1, 0
	s_waitcnt vmcnt(0)
	ds_write_b128 v0, v[28:31]
	v_lshrrev_b32_e32 v0, 1, v206
	v_bfe_u32 v1, v206, 2, 2
	v_and_or_b32 v0, v0, 24, v1
	v_mul_u32_u24_e32 v0, 0x110, v0
	v_lshlrev_b32_e32 v1, 2, v206
	v_and_or_b32 v0, v1, 12, v0
	v_and_b32_e32 v51, 15, v206
	v_lshlrev_b32_e32 v0, 1, v0
	v_add_u32_e32 v32, s65, v0
	v_and_b32_e32 v8, 48, v206
	s_add_i32 s6, 0, 0x1edd0
	v_mul_u32_u24_e32 v9, 0x110, v51
	s_waitcnt lgkmcnt(0)
	s_barrier
	ds_read_b64_tr_b16 v[2:3], v32 offset:2176
	ds_read_b64_tr_b16 v[0:1], v32
	ds_read_b64_tr_b16 v[6:7], v32 offset:2208
	ds_read_b64_tr_b16 v[4:5], v32 offset:32
	v_add3_u32 v164, s6, v8, v9
	ds_read_b64_tr_b16 v[10:11], v32 offset:19584
	ds_read_b64_tr_b16 v[8:9], v32 offset:17408
	ds_read_b64_tr_b16 v[14:15], v32 offset:19616
	ds_read_b64_tr_b16 v[12:13], v32 offset:17440
	ds_read_b128 v[16:19], v164
	ds_read_b128 v[20:23], v164 offset:64
	ds_read_b128 v[24:27], v164 offset:4352
	ds_read_b128 v[28:31], v164 offset:4416
	ds_read_b128 v[52:55], v164 offset:8704
	ds_read_b128 v[56:59], v164 offset:8768
	ds_read_b128 v[60:63], v164 offset:13056
	ds_read_b128 v[64:67], v164 offset:13120
	ds_read_b128 v[68:71], v164 offset:17408
	ds_read_b128 v[72:75], v164 offset:17472
	ds_read_b128 v[76:79], v164 offset:21760
	ds_read_b128 v[80:83], v164 offset:21824
	ds_read_b128 v[84:87], v164 offset:26112
	ds_read_b128 v[88:91], v164 offset:26176
	ds_read_b128 v[92:95], v164 offset:30464
	ds_read_b128 v[96:99], v164 offset:30528
	s_waitcnt lgkmcnt(14)
	v_mfma_f32_16x16x32_bf16 v[100:103], v[0:3], v[16:19], 0
	v_mfma_f32_16x16x32_bf16 v[16:19], v[4:7], v[16:19], 0
	s_waitcnt lgkmcnt(13)
	v_mfma_f32_16x16x32_bf16 v[104:107], v[0:3], v[24:27], 0
	v_mfma_f32_16x16x32_bf16 v[24:27], v[4:7], v[24:27], 0
	s_waitcnt lgkmcnt(11)
	v_mfma_f32_16x16x32_bf16 v[108:111], v[0:3], v[52:55], 0
	v_mfma_f32_16x16x32_bf16 v[52:55], v[4:7], v[52:55], 0
	s_waitcnt lgkmcnt(9)
	v_mfma_f32_16x16x32_bf16 v[112:115], v[0:3], v[60:63], 0
	v_mfma_f32_16x16x32_bf16 v[60:63], v[4:7], v[60:63], 0
	s_waitcnt lgkmcnt(7)
	v_mfma_f32_16x16x32_bf16 v[116:119], v[0:3], v[68:71], 0
	v_mfma_f32_16x16x32_bf16 v[68:71], v[4:7], v[68:71], 0
	s_waitcnt lgkmcnt(5)
	v_mfma_f32_16x16x32_bf16 v[120:123], v[0:3], v[76:79], 0
	v_mfma_f32_16x16x32_bf16 v[76:79], v[4:7], v[76:79], 0
	s_waitcnt lgkmcnt(3)
	v_mfma_f32_16x16x32_bf16 v[124:127], v[0:3], v[84:87], 0
	v_mfma_f32_16x16x32_bf16 v[84:87], v[4:7], v[84:87], 0
	s_waitcnt lgkmcnt(1)
	v_mfma_f32_16x16x32_bf16 v[0:3], v[0:3], v[92:95], 0
	v_mfma_f32_16x16x32_bf16 v[4:7], v[4:7], v[92:95], 0
	ds_read_b64_tr_b16 v[94:95], v32 offset:36992
	ds_read_b64_tr_b16 v[92:93], v32 offset:34816
	ds_read_b64_tr_b16 v[130:131], v32 offset:37024
	ds_read_b64_tr_b16 v[128:129], v32 offset:34848
	ds_read_b128 v[132:135], v164 offset:128
	ds_read_b128 v[136:139], v164 offset:4480
	ds_read_b128 v[140:143], v164 offset:8832
	ds_read_b128 v[144:147], v164 offset:13184
	ds_read_b128 v[148:151], v164 offset:17536
	ds_read_b128 v[152:155], v164 offset:21888
	ds_read_b128 v[156:159], v164 offset:26240
	ds_read_b128 v[160:163], v164 offset:30592
	v_mfma_f32_16x16x32_bf16 v[100:103], v[8:11], v[20:23], v[100:103]
	v_mfma_f32_16x16x32_bf16 v[16:19], v[12:15], v[20:23], v[16:19]
	v_mfma_f32_16x16x32_bf16 v[20:23], v[8:11], v[28:31], v[104:107]
	v_mfma_f32_16x16x32_bf16 v[24:27], v[12:15], v[28:31], v[24:27]
	v_mfma_f32_16x16x32_bf16 v[28:31], v[8:11], v[56:59], v[108:111]
	v_mfma_f32_16x16x32_bf16 v[52:55], v[12:15], v[56:59], v[52:55]
	v_mfma_f32_16x16x32_bf16 v[56:59], v[8:11], v[64:67], v[112:115]
	v_mfma_f32_16x16x32_bf16 v[60:63], v[12:15], v[64:67], v[60:63]
	v_mfma_f32_16x16x32_bf16 v[64:67], v[8:11], v[72:75], v[116:119]
	v_mfma_f32_16x16x32_bf16 v[68:71], v[12:15], v[72:75], v[68:71]
	v_mfma_f32_16x16x32_bf16 v[72:75], v[8:11], v[80:83], v[120:123]
	v_mfma_f32_16x16x32_bf16 v[76:79], v[12:15], v[80:83], v[76:79]
	v_mfma_f32_16x16x32_bf16 v[80:83], v[8:11], v[88:91], v[124:127]
	v_mfma_f32_16x16x32_bf16 v[84:87], v[12:15], v[88:91], v[84:87]
	s_waitcnt lgkmcnt(12)
	v_mfma_f32_16x16x32_bf16 v[0:3], v[8:11], v[96:99], v[0:3]
	v_mfma_f32_16x16x32_bf16 v[4:7], v[12:15], v[96:99], v[4:7]
	ds_read_b64_tr_b16 v[14:15], v32 offset:54400
	ds_read_b64_tr_b16 v[12:13], v32 offset:52224
	ds_read_b64_tr_b16 v[90:91], v32 offset:54432
	ds_read_b64_tr_b16 v[88:89], v32 offset:52256
	ds_read_b128 v[8:11], v164 offset:192
	ds_read_b128 v[96:99], v164 offset:4544
	ds_read_b128 v[104:107], v164 offset:8896
	ds_read_b128 v[108:111], v164 offset:13248
	ds_read_b128 v[112:115], v164 offset:17600
	ds_read_b128 v[116:119], v164 offset:21952
	ds_read_b128 v[120:123], v164 offset:26304
	ds_read_b128 v[124:127], v164 offset:30656
	s_waitcnt lgkmcnt(14)
	v_mfma_f32_16x16x32_bf16 v[100:103], v[92:95], v[132:135], v[100:103]
	v_mfma_f32_16x16x32_bf16 v[16:19], v[128:131], v[132:135], v[16:19]
	v_mfma_f32_16x16x32_bf16 v[20:23], v[92:95], v[136:139], v[20:23]
	v_mfma_f32_16x16x32_bf16 v[24:27], v[128:131], v[136:139], v[24:27]
	v_mfma_f32_16x16x32_bf16 v[28:31], v[92:95], v[140:143], v[28:31]
	v_mfma_f32_16x16x32_bf16 v[52:55], v[128:131], v[140:143], v[52:55]
	v_mfma_f32_16x16x32_bf16 v[56:59], v[92:95], v[144:147], v[56:59]
	v_mfma_f32_16x16x32_bf16 v[60:63], v[128:131], v[144:147], v[60:63]
	v_mfma_f32_16x16x32_bf16 v[64:67], v[92:95], v[148:151], v[64:67]
	v_mfma_f32_16x16x32_bf16 v[68:71], v[128:131], v[148:151], v[68:71]
	v_mfma_f32_16x16x32_bf16 v[72:75], v[92:95], v[152:155], v[72:75]
	v_mfma_f32_16x16x32_bf16 v[76:79], v[128:131], v[152:155], v[76:79]
	s_waitcnt lgkmcnt(13)
	v_mfma_f32_16x16x32_bf16 v[80:83], v[92:95], v[156:159], v[80:83]
	v_mfma_f32_16x16x32_bf16 v[84:87], v[128:131], v[156:159], v[84:87]
	s_waitcnt lgkmcnt(12)
	v_mfma_f32_16x16x32_bf16 v[92:95], v[92:95], v[160:163], v[0:3]
	v_mfma_f32_16x16x32_bf16 v[4:7], v[128:131], v[160:163], v[4:7]
	s_waitcnt lgkmcnt(7)
	v_mfma_f32_16x16x32_bf16 v[100:103], v[12:15], v[8:11], v[100:103]
	v_mfma_f32_16x16x32_bf16 v[128:131], v[88:91], v[8:11], v[16:19]
	s_waitcnt lgkmcnt(6)
	v_mfma_f32_16x16x32_bf16 v[132:135], v[12:15], v[96:99], v[20:23]
	v_mfma_f32_16x16x32_bf16 v[96:99], v[88:91], v[96:99], v[24:27]
	s_waitcnt lgkmcnt(5)
	v_mfma_f32_16x16x32_bf16 v[24:27], v[12:15], v[104:107], v[28:31]
	v_mfma_f32_16x16x32_bf16 v[16:19], v[88:91], v[104:107], v[52:55]
	s_waitcnt lgkmcnt(4)
	v_mfma_f32_16x16x32_bf16 v[8:11], v[12:15], v[108:111], v[56:59]
	v_mfma_f32_16x16x32_bf16 v[0:3], v[88:91], v[108:111], v[60:63]
	s_waitcnt lgkmcnt(3)
	v_mfma_f32_16x16x32_bf16 v[52:55], v[12:15], v[112:115], v[64:67]
	v_mfma_f32_16x16x32_bf16 v[56:59], v[88:91], v[112:115], v[68:71]
	s_waitcnt lgkmcnt(2)
	v_mfma_f32_16x16x32_bf16 v[60:63], v[12:15], v[116:119], v[72:75]
	v_mfma_f32_16x16x32_bf16 v[64:67], v[88:91], v[116:119], v[76:79]
	s_waitcnt lgkmcnt(1)
	v_mfma_f32_16x16x32_bf16 v[28:31], v[12:15], v[120:123], v[80:83]
	v_mfma_f32_16x16x32_bf16 v[20:23], v[88:91], v[120:123], v[84:87]
	s_waitcnt lgkmcnt(0)
	v_mfma_f32_16x16x32_bf16 v[12:15], v[12:15], v[124:127], v[92:95]
	v_mfma_f32_16x16x32_bf16 v[4:7], v[88:91], v[124:127], v[4:7]
	v_lshrrev_b32_e32 v32, 2, v206
	v_and_b32_e32 v32, 12, v32
	v_readlane_b32 s6, v254, 50
	s_movk_i32 s12, 0x108
	v_mov_b32_e32 v89, 0x4200
	v_or_b32_e32 v82, s6, v32
	v_mad_u32_u24 v72, v51, s12, v89
	v_mad_u32_u24 v68, v51, s12, v82
	v_lshl_add_u32 v73, v68, 1, 0
	v_add_u32_e32 v68, v82, v72
	v_lshl_add_u32 v83, v68, 1, 0
	v_or_b32_e32 v68, 16, v51
	v_mul_u32_u24_e32 v68, s8, v68
	v_mul_u32_u24_e32 v69, s8, v51
	v_cvt_f32_u32_e32 v69, v69
	v_cvt_f32_u32_e32 v68, v68
	v_readlane_b32 s6, v254, 51
	s_mov_b32 s16, 0x3a000000
	s_mov_b32 s9, 0x7f800000
	v_or_b32_e32 v84, s6, v32
	v_pk_mul_f32 v[68:69], v[68:69], s[16:17] op_sel_hi:[1,0]
	v_mad_u32_u24 v32, v51, s12, v84
	v_pk_mul_f32 v[70:71], v[68:69], 0.5 op_sel_hi:[1,0]
	v_lshl_add_u32 v85, v32, 1, 0
	v_fract_f32_e32 v32, v71
	v_add_f32_e32 v32, v32, v32
	v_cmp_neq_f32_e32 vcc, s9, v71
	v_add_u32_e32 v72, v84, v72
	v_lshl_add_u32 v86, v72, 1, 0
	v_cndmask_b32_e32 v32, 0, v32, vcc
	v_cmp_lt_f32_e32 vcc, 1.0, v69
	v_mov_b32_e32 v87, 0xbf1f24be
	v_mov_b32_e32 v88, 0x3e642e9d
	v_cndmask_b32_e32 v32, v69, v32, vcc
	v_add_f32_e32 v71, v32, v32
	v_rndne_f32_e32 v71, v71
	v_fmac_f32_e32 v32, -0.5, v71
	v_mul_f32_e32 v72, v32, v32
	v_fmamk_f32 v75, v72, 0x3e75aa41, v87
	v_fmaak_f32 v75, v72, v75, 0x40234736
	v_fmaak_f32 v75, v72, v75, 0xc0a55e0e
	v_mul_f32_e32 v76, v32, v72
	v_mul_f32_e32 v75, v76, v75
	v_cvt_i32_f32_e32 v74, v71
	v_fmac_f32_e32 v75, 0x40490fdb, v32
	v_fmamk_f32 v32, v72, 0x3d4be544, v88
	v_fmaak_f32 v32, v72, v32, 0xbfaad1da
	v_fmaak_f32 v32, v72, v32, 0x4081e0d3
	v_fmaak_f32 v32, v72, v32, 0xc09de9e6
	v_fma_f32 v72, v72, v32, 1.0
	v_and_b32_e32 v32, 1, v74
	v_and_b32_e32 v71, 2, v74
	v_cmp_eq_u32_e32 vcc, 0, v32
	v_cmp_eq_u32_e64 s[6:7], 0, v71
	v_lshlrev_b32_e32 v71, 30, v74
	v_cndmask_b32_e64 v32, -v75, v72, vcc
	v_cndmask_b32_e64 v32, -v32, v32, s[6:7]
	v_cmp_lg_f32_e64 s[6:7], s9, v69
	v_cndmask_b32_e32 v69, v72, v75, vcc
	s_brev_b32 s13, 1
	v_bitop3_b32 v69, v71, v69, s13 bitop3:0x6c
	v_cndmask_b32_e64 v72, v226, v69, s[6:7]
	v_cndmask_b32_e64 v32, v226, v32, s[6:7]
	v_pk_mul_f32 v[74:75], v[72:73], v[54:55] op_sel_hi:[0,1]
	v_pk_mul_f32 v[76:77], v[72:73], v[52:53] op_sel_hi:[0,1]
	v_pk_mul_f32 v[78:79], v[72:73], v[102:103] op_sel_hi:[0,1]
	v_pk_mul_f32 v[80:81], v[72:73], v[100:101] op_sel_hi:[0,1]
	v_pk_fma_f32 v[74:75], v[32:33], v[102:103], v[74:75] op_sel_hi:[0,1,1]
	v_pk_fma_f32 v[76:77], v[32:33], v[100:101], v[76:77] op_sel_hi:[0,1,1]
	v_pk_fma_f32 v[54:55], v[32:33], v[54:55], v[78:79] op_sel_hi:[0,1,1] neg_lo:[0,0,1] neg_hi:[0,0,1]
	v_pk_fma_f32 v[52:53], v[32:33], v[52:53], v[80:81] op_sel_hi:[0,1,1] neg_lo:[0,0,1] neg_hi:[0,0,1]
	v_cvt_pk_bf16_f32 v76, v76, v77
	v_cvt_pk_bf16_f32 v77, v74, v75
	v_cvt_pk_bf16_f32 v52, v52, v53
	v_cvt_pk_bf16_f32 v53, v54, v55
	s_barrier
	ds_write_b64 v73, v[76:77]
	ds_write_b64 v83, v[52:53]
	v_pk_mul_f32 v[52:53], v[72:73], v[58:59] op_sel_hi:[0,1]
	v_pk_mul_f32 v[54:55], v[72:73], v[56:57] op_sel_hi:[0,1]
	v_pk_mul_f32 v[74:75], v[72:73], v[130:131] op_sel_hi:[0,1]
	v_pk_mul_f32 v[72:73], v[72:73], v[128:129] op_sel_hi:[0,1]
	v_pk_fma_f32 v[52:53], v[32:33], v[130:131], v[52:53] op_sel_hi:[0,1,1]
	v_pk_fma_f32 v[54:55], v[32:33], v[128:129], v[54:55] op_sel_hi:[0,1,1]
	v_pk_fma_f32 v[58:59], v[32:33], v[58:59], v[74:75] op_sel_hi:[0,1,1] neg_lo:[0,0,1] neg_hi:[0,0,1]
	v_pk_fma_f32 v[56:57], v[32:33], v[56:57], v[72:73] op_sel_hi:[0,1,1] neg_lo:[0,0,1] neg_hi:[0,0,1]
	v_fract_f32_e32 v32, v70
	v_add_f32_e32 v32, v32, v32
	v_cmp_neq_f32_e32 vcc, s9, v70
	v_cvt_pk_bf16_f32 v54, v54, v55
	v_cvt_pk_bf16_f32 v55, v52, v53
	v_cndmask_b32_e32 v32, 0, v32, vcc
	v_cmp_lt_f32_e32 vcc, 1.0, v68
	ds_write_b64 v85, v[54:55]
	v_cvt_pk_bf16_f32 v52, v56, v57
	v_cndmask_b32_e32 v32, v68, v32, vcc
	v_add_f32_e32 v53, v32, v32
	v_rndne_f32_e32 v54, v53
	v_cvt_pk_bf16_f32 v53, v58, v59
	v_fmac_f32_e32 v32, -0.5, v54
	ds_write_b64 v86, v[52:53]
	v_mul_f32_e32 v53, v32, v32
	v_cvt_i32_f32_e32 v55, v54
	v_fmamk_f32 v54, v53, 0x3e75aa41, v87
	v_fmaak_f32 v54, v53, v54, 0x40234736
	v_fmaak_f32 v54, v53, v54, 0xc0a55e0e
	v_mul_f32_e32 v56, v32, v53
	v_mul_f32_e32 v54, v56, v54
	v_fmac_f32_e32 v54, 0x40490fdb, v32
	v_fmamk_f32 v32, v53, 0x3d4be544, v88
	v_fmaak_f32 v32, v53, v32, 0xbfaad1da
	v_fmaak_f32 v32, v53, v32, 0x4081e0d3
	v_fmaak_f32 v32, v53, v32, 0xc09de9e6
	v_fma_f32 v53, v53, v32, 1.0
	v_and_b32_e32 v32, 1, v55
	v_and_b32_e32 v52, 2, v55
	v_cmp_eq_u32_e32 vcc, 0, v32
	v_cmp_eq_u32_e64 s[6:7], 0, v52
	v_readlane_b32 s20, v254, 23
	v_cndmask_b32_e64 v32, -v54, v53, vcc
	v_cndmask_b32_e32 v52, v53, v54, vcc
	v_lshlrev_b32_e32 v53, 30, v55
	v_cndmask_b32_e64 v32, -v32, v32, s[6:7]
	v_cmp_lg_f32_e64 s[6:7], s9, v68
	v_bitop3_b32 v52, v53, v52, s13 bitop3:0x6c
	v_mov_b32_e32 v53, 0x1080
	v_cndmask_b32_e64 v52, v226, v52, s[6:7]
	v_mad_u32_u24 v70, v51, s12, v53
	v_mov_b32_e32 v53, 0x5280
	v_cndmask_b32_e64 v32, v226, v32, s[6:7]
	v_pk_mul_f32 v[54:55], v[52:53], v[62:63] op_sel_hi:[0,1]
	v_pk_mul_f32 v[56:57], v[52:53], v[60:61] op_sel_hi:[0,1]
	v_mad_u32_u24 v71, v51, s12, v53
	v_pk_fma_f32 v[54:55], v[32:33], v[134:135], v[54:55] op_sel_hi:[0,1,1]
	v_pk_fma_f32 v[56:57], v[32:33], v[132:133], v[56:57] op_sel_hi:[0,1,1]
	v_pk_mul_f32 v[58:59], v[52:53], v[134:135] op_sel_hi:[0,1]
	v_pk_mul_f32 v[68:69], v[52:53], v[132:133] op_sel_hi:[0,1]
	v_add_u32_e32 v53, v82, v70
	v_cvt_pk_bf16_f32 v56, v56, v57
	v_cvt_pk_bf16_f32 v57, v54, v55
	v_lshl_add_u32 v53, v53, 1, 0
	v_pk_fma_f32 v[58:59], v[32:33], v[62:63], v[58:59] op_sel_hi:[0,1,1] neg_lo:[0,0,1] neg_hi:[0,0,1]
	v_pk_fma_f32 v[60:61], v[32:33], v[60:61], v[68:69] op_sel_hi:[0,1,1] neg_lo:[0,0,1] neg_hi:[0,0,1]
	ds_write_b64 v53, v[56:57]
	v_add_u32_e32 v53, v71, v82
	v_cvt_pk_bf16_f32 v54, v60, v61
	v_cvt_pk_bf16_f32 v55, v58, v59
	v_lshl_add_u32 v53, v53, 1, 0
	ds_write_b64 v53, v[54:55]
	v_pk_mul_f32 v[54:55], v[52:53], v[66:67] op_sel_hi:[0,1]
	v_pk_mul_f32 v[56:57], v[52:53], v[64:65] op_sel_hi:[0,1]
	v_pk_mul_f32 v[58:59], v[52:53], v[98:99] op_sel_hi:[0,1]
	v_pk_mul_f32 v[52:53], v[52:53], v[96:97] op_sel_hi:[0,1]
	v_pk_fma_f32 v[54:55], v[32:33], v[98:99], v[54:55] op_sel_hi:[0,1,1]
	v_pk_fma_f32 v[56:57], v[32:33], v[96:97], v[56:57] op_sel_hi:[0,1,1]
	v_pk_fma_f32 v[58:59], v[32:33], v[66:67], v[58:59] op_sel_hi:[0,1,1] neg_lo:[0,0,1] neg_hi:[0,0,1]
	v_pk_fma_f32 v[52:53], v[32:33], v[64:65], v[52:53] op_sel_hi:[0,1,1] neg_lo:[0,0,1] neg_hi:[0,0,1]
	v_add_u32_e32 v32, v84, v70
	v_cvt_pk_bf16_f32 v56, v56, v57
	v_cvt_pk_bf16_f32 v57, v54, v55
	v_lshl_add_u32 v32, v32, 1, 0
	v_or_b32_e32 v62, 32, v51
	v_or_b32_e32 v51, 48, v51
	ds_write_b64 v32, v[56:57]
	v_mul_u32_u24_e32 v32, s8, v51
	v_mul_u32_u24_e32 v54, s8, v62
	v_cvt_f32_u32_e32 v55, v54
	v_cvt_f32_u32_e32 v54, v32
	v_cvt_pk_bf16_f32 v52, v52, v53
	v_cvt_pk_bf16_f32 v53, v58, v59
	v_add_u32_e32 v32, v71, v84
	v_pk_mul_f32 v[54:55], v[54:55], s[16:17] op_sel_hi:[1,0]
	v_lshl_add_u32 v32, v32, 1, 0
	v_pk_mul_f32 v[56:57], v[54:55], 0.5 op_sel_hi:[1,0]
	ds_write_b64 v32, v[52:53]
	v_fract_f32_e32 v58, v57
	v_add_f32_e32 v58, v58, v58
	v_cmp_neq_f32_e32 vcc, s9, v57
	s_lshl_b32 s8, s8, 8
	v_readlane_b32 s21, v254, 24
	v_cndmask_b32_e32 v57, 0, v58, vcc
	v_cmp_lt_f32_e32 vcc, 1.0, v55
	v_readlane_b32 s22, v254, 25
	v_readlane_b32 s23, v254, 26
	v_cndmask_b32_e32 v57, v55, v57, vcc
	v_add_f32_e32 v58, v57, v57
	v_rndne_f32_e32 v58, v58
	v_fmac_f32_e32 v57, -0.5, v58
	v_mul_f32_e32 v52, v57, v57
	v_fmamk_f32 v53, v52, 0x3e75aa41, v87
	v_fmaak_f32 v53, v52, v53, 0x40234736
	v_cvt_i32_f32_e32 v59, v58
	v_fmaak_f32 v53, v52, v53, 0xc0a55e0e
	v_mul_f32_e32 v58, v57, v52
	v_mul_f32_e32 v53, v58, v53
	v_fmac_f32_e32 v53, 0x40490fdb, v57
	v_fmamk_f32 v57, v52, 0x3d4be544, v88
	v_fmaak_f32 v57, v52, v57, 0xbfaad1da
	v_fmaak_f32 v57, v52, v57, 0x4081e0d3
	v_fmaak_f32 v57, v52, v57, 0xc09de9e6
	v_fma_f32 v52, v52, v57, 1.0
	v_and_b32_e32 v57, 1, v59
	v_and_b32_e32 v32, 2, v59
	v_cmp_eq_u32_e32 vcc, 0, v57
	v_cmp_eq_u32_e64 s[6:7], 0, v32
	s_nop 0
	v_cndmask_b32_e64 v57, -v53, v52, vcc
	v_cndmask_b32_e32 v52, v52, v53, vcc
	v_lshlrev_b32_e32 v53, 30, v59
	v_cndmask_b32_e64 v32, -v57, v57, s[6:7]
	v_cmp_lg_f32_e64 s[6:7], s9, v55
	v_bitop3_b32 v52, v53, v52, s13 bitop3:0x6c
	v_mad_u32_u24 v53, v62, s12, v89
	v_cndmask_b32_e64 v52, v226, v52, s[6:7]
	v_cndmask_b32_e64 v32, v226, v32, s[6:7]
	v_pk_mul_f32 v[58:59], v[52:53], v[28:29] op_sel_hi:[0,1]
	v_pk_mul_f32 v[60:61], v[52:53], v[30:31] op_sel_hi:[0,1]
	v_pk_fma_f32 v[60:61], v[32:33], v[26:27], v[60:61] op_sel_hi:[0,1,1]
	v_pk_fma_f32 v[58:59], v[32:33], v[24:25], v[58:59] op_sel_hi:[0,1,1]
	v_pk_mul_f32 v[24:25], v[52:53], v[24:25] op_sel_hi:[0,1]
	v_pk_mul_f32 v[26:27], v[52:53], v[26:27] op_sel_hi:[0,1]
	v_pk_fma_f32 v[26:27], v[32:33], v[30:31], v[26:27] op_sel_hi:[0,1,1] neg_lo:[0,0,1] neg_hi:[0,0,1]
	v_pk_fma_f32 v[24:25], v[32:33], v[28:29], v[24:25] op_sel_hi:[0,1,1] neg_lo:[0,0,1] neg_hi:[0,0,1]
	v_mad_u32_u24 v30, v62, s12, v82
	v_cvt_pk_bf16_f32 v24, v24, v25
	v_cvt_pk_bf16_f32 v25, v26, v27
	v_add_u32_e32 v26, v53, v82
	v_cvt_pk_bf16_f32 v28, v58, v59
	v_cvt_pk_bf16_f32 v29, v60, v61
	v_lshl_add_u32 v30, v30, 1, 0
	v_lshl_add_u32 v26, v26, 1, 0
	ds_write_b64 v30, v[28:29]
	ds_write_b64 v26, v[24:25]
	v_pk_mul_f32 v[24:25], v[52:53], v[20:21] op_sel_hi:[0,1]
	v_pk_mul_f32 v[26:27], v[52:53], v[22:23] op_sel_hi:[0,1]
	v_pk_fma_f32 v[26:27], v[32:33], v[18:19], v[26:27] op_sel_hi:[0,1,1]
	v_pk_fma_f32 v[24:25], v[32:33], v[16:17], v[24:25] op_sel_hi:[0,1,1]
	v_pk_mul_f32 v[16:17], v[52:53], v[16:17] op_sel_hi:[0,1]
	v_pk_mul_f32 v[18:19], v[52:53], v[18:19] op_sel_hi:[0,1]
	v_pk_fma_f32 v[18:19], v[32:33], v[22:23], v[18:19] op_sel_hi:[0,1,1] neg_lo:[0,0,1] neg_hi:[0,0,1]
	v_pk_fma_f32 v[16:17], v[32:33], v[20:21], v[16:17] op_sel_hi:[0,1,1] neg_lo:[0,0,1] neg_hi:[0,0,1]
	v_cvt_pk_bf16_f32 v16, v16, v17
	v_cvt_pk_bf16_f32 v17, v18, v19
	v_fract_f32_e32 v19, v56
	v_add_f32_e32 v19, v19, v19
	v_cmp_neq_f32_e32 vcc, s9, v56
	v_mad_u32_u24 v22, v62, s12, v84
	v_cvt_pk_bf16_f32 v20, v24, v25
	v_cndmask_b32_e32 v19, 0, v19, vcc
	v_cmp_lt_f32_e32 vcc, 1.0, v54
	v_cvt_pk_bf16_f32 v21, v26, v27
	v_lshl_add_u32 v22, v22, 1, 0
	v_cndmask_b32_e32 v19, v54, v19, vcc
	ds_write_b64 v22, v[20:21]
	v_add_f32_e32 v20, v19, v19
	v_add_u32_e32 v18, v53, v84
	v_rndne_f32_e32 v20, v20
	v_lshl_add_u32 v18, v18, 1, 0
	v_fmac_f32_e32 v19, -0.5, v20
	ds_write_b64 v18, v[16:17]
	v_mul_f32_e32 v17, v19, v19
	v_fmamk_f32 v18, v17, 0x3e75aa41, v87
	v_fmaak_f32 v18, v17, v18, 0x40234736
	v_cvt_i32_f32_e32 v21, v20
	v_fmaak_f32 v18, v17, v18, 0xc0a55e0e
	v_mul_f32_e32 v20, v19, v17
	v_mul_f32_e32 v18, v20, v18
	v_fmac_f32_e32 v18, 0x40490fdb, v19
	v_fmamk_f32 v19, v17, 0x3d4be544, v88
	v_fmaak_f32 v19, v17, v19, 0xbfaad1da
	v_fmaak_f32 v19, v17, v19, 0x4081e0d3
	v_fmaak_f32 v19, v17, v19, 0xc09de9e6
	v_fma_f32 v17, v17, v19, 1.0
	v_and_b32_e32 v19, 1, v21
	v_and_b32_e32 v16, 2, v21
	v_cmp_eq_u32_e32 vcc, 0, v19
	v_cmp_eq_u32_e64 s[6:7], 0, v16
	s_nop 0
	v_cndmask_b32_e64 v19, -v18, v17, vcc
	v_cndmask_b32_e32 v17, v17, v18, vcc
	v_lshlrev_b32_e32 v18, 30, v21
	v_cndmask_b32_e64 v16, -v19, v19, s[6:7]
	v_cmp_lg_f32_e64 s[6:7], s9, v54
	v_bitop3_b32 v17, v18, v17, s13 bitop3:0x6c
	s_lshl_b32 s9, s0, 7
	v_cndmask_b32_e64 v18, v226, v17, s[6:7]
	v_cndmask_b32_e64 v16, v226, v16, s[6:7]
	v_mad_u32_u24 v17, v51, s12, v89
	v_pk_mul_f32 v[20:21], v[18:19], v[12:13] op_sel_hi:[0,1]
	v_pk_mul_f32 v[22:23], v[18:19], v[14:15] op_sel_hi:[0,1]
	v_pk_fma_f32 v[22:23], v[16:17], v[10:11], v[22:23] op_sel_hi:[0,1,1]
	v_pk_fma_f32 v[20:21], v[16:17], v[8:9], v[20:21] op_sel_hi:[0,1,1]
	v_pk_mul_f32 v[8:9], v[18:19], v[8:9] op_sel_hi:[0,1]
	v_pk_mul_f32 v[10:11], v[18:19], v[10:11] op_sel_hi:[0,1]
	v_pk_fma_f32 v[10:11], v[16:17], v[14:15], v[10:11] op_sel_hi:[0,1,1] neg_lo:[0,0,1] neg_hi:[0,0,1]
	v_pk_fma_f32 v[8:9], v[16:17], v[12:13], v[8:9] op_sel_hi:[0,1,1] neg_lo:[0,0,1] neg_hi:[0,0,1]
	v_mad_u32_u24 v14, v51, s12, v82
	v_cvt_pk_bf16_f32 v8, v8, v9
	v_cvt_pk_bf16_f32 v9, v10, v11
	v_add_u32_e32 v10, v17, v82
	v_cvt_pk_bf16_f32 v12, v20, v21
	v_cvt_pk_bf16_f32 v13, v22, v23
	v_lshl_add_u32 v14, v14, 1, 0
	v_lshl_add_u32 v10, v10, 1, 0
	ds_write_b64 v14, v[12:13]
	ds_write_b64 v10, v[8:9]
	v_pk_mul_f32 v[8:9], v[18:19], v[4:5] op_sel_hi:[0,1]
	v_pk_mul_f32 v[10:11], v[18:19], v[6:7] op_sel_hi:[0,1]
	v_pk_fma_f32 v[10:11], v[16:17], v[2:3], v[10:11] op_sel_hi:[0,1,1]
	v_pk_fma_f32 v[8:9], v[16:17], v[0:1], v[8:9] op_sel_hi:[0,1,1]
	v_pk_mul_f32 v[0:1], v[18:19], v[0:1] op_sel_hi:[0,1]
	v_pk_mul_f32 v[2:3], v[18:19], v[2:3] op_sel_hi:[0,1]
	v_pk_fma_f32 v[2:3], v[16:17], v[6:7], v[2:3] op_sel_hi:[0,1,1] neg_lo:[0,0,1] neg_hi:[0,0,1]
	v_pk_fma_f32 v[0:1], v[16:17], v[4:5], v[0:1] op_sel_hi:[0,1,1] neg_lo:[0,0,1] neg_hi:[0,0,1]
	v_mad_u32_u24 v6, v51, s12, v84
	v_cvt_pk_bf16_f32 v0, v0, v1
	v_cvt_pk_bf16_f32 v1, v2, v3
	v_add_u32_e32 v2, v17, v84
	v_cvt_pk_bf16_f32 v4, v8, v9
	v_cvt_pk_bf16_f32 v5, v10, v11
	v_lshl_add_u32 v6, v6, 1, 0
	v_lshl_add_u32 v2, v2, 1, 0
	ds_write_b64 v6, v[4:5]
	ds_write_b64 v2, v[0:1]
	v_mad_u64_u32 v[0:1], s[6:7], v37, s12, v[34:35]
	v_lshlrev_b32_e32 v4, 1, v37
	v_lshl_add_u32 v0, v0, 1, 0
	v_and_b32_e32 v4, 0x7e, v4
	v_lshrrev_b32_e32 v5, 11, v206
	s_waitcnt lgkmcnt(0)
	s_barrier
	ds_read_b128 v[0:3], v0
	v_add_u32_e32 v4, v4, v5
	v_add_lshl_u32 v4, v4, s9, 14
	v_or3_b32 v4, v4, s8, v34
	v_lshlrev_b32_e32 v8, 1, v4
	v_mad_u64_u32 v[4:5], s[6:7], v38, s12, v[34:35]
	v_lshl_add_u32 v4, v4, 1, 0
	ds_read_b128 v[4:7], v4
	s_waitcnt lgkmcnt(1)
	buffer_store_dwordx4 v[0:3], v8, s[20:23], 0 offen sc1
	s_lshl_b32 s0, s0, 4
	s_nop 0
	v_lshlrev_b32_e32 v0, 1, v38
	v_and_b32_e32 v0, 0x7e, v0
	v_lshrrev_b32_e32 v1, 11, v35
	v_add_u32_e32 v0, v0, v1
	v_add_lshl_u32 v0, v0, s9, 14
	v_or3_b32 v0, v0, s8, v34
	v_lshlrev_b32_e32 v0, 1, v0
	s_waitcnt lgkmcnt(0)
	buffer_store_dwordx4 v[4:7], v0, s[20:23], 0 offen sc1
	v_mad_u64_u32 v[0:1], s[6:7], v40, s12, v[34:35]
	s_nop 0
	v_lshlrev_b32_e32 v4, 1, v40
	v_lshl_add_u32 v0, v0, 1, 0
	v_and_b32_e32 v4, 0x7e, v4
	v_lshrrev_b32_e32 v5, 11, v39
	ds_read_b128 v[0:3], v0
	v_add_u32_e32 v4, v4, v5
	v_add_lshl_u32 v4, v4, s9, 14
	v_or3_b32 v4, v4, s8, v34
	v_lshlrev_b32_e32 v8, 1, v4
	v_mad_u64_u32 v[4:5], s[6:7], v42, s12, v[34:35]
	v_lshl_add_u32 v4, v4, 1, 0
	ds_read_b128 v[4:7], v4
	s_waitcnt lgkmcnt(1)
	buffer_store_dwordx4 v[0:3], v8, s[20:23], 0 offen sc1
	s_nop 1
	v_lshlrev_b32_e32 v0, 1, v42
	v_and_b32_e32 v0, 0x7e, v0
	v_lshrrev_b32_e32 v1, 11, v41
	v_add_u32_e32 v0, v0, v1
	v_add_lshl_u32 v0, v0, s9, 14
	v_or3_b32 v0, v0, s8, v34
	v_lshlrev_b32_e32 v0, 1, v0
	s_waitcnt lgkmcnt(0)
	buffer_store_dwordx4 v[4:7], v0, s[20:23], 0 offen sc1
	v_mad_u64_u32 v[0:1], s[6:7], v44, s12, v[34:35]
	s_nop 0
	v_lshlrev_b32_e32 v4, 1, v44
	v_lshl_add_u32 v0, v0, 1, 0
	v_and_b32_e32 v4, 0x7e, v4
	v_lshrrev_b32_e32 v5, 11, v43
	ds_read_b128 v[0:3], v0
	v_add_u32_e32 v4, v4, v5
	v_add_lshl_u32 v4, v4, s9, 14
	v_or3_b32 v4, v4, s8, v34
	v_lshlrev_b32_e32 v8, 1, v4
	v_mad_u64_u32 v[4:5], s[6:7], v46, s12, v[34:35]
	v_lshl_add_u32 v4, v4, 1, 0
	ds_read_b128 v[4:7], v4
	s_waitcnt lgkmcnt(1)
	buffer_store_dwordx4 v[0:3], v8, s[20:23], 0 offen sc1
	s_nop 1
	v_lshlrev_b32_e32 v0, 1, v46
	v_and_b32_e32 v0, 0x7e, v0
	v_lshrrev_b32_e32 v1, 11, v45
	v_add_u32_e32 v0, v0, v1
	v_add_lshl_u32 v0, v0, s9, 14
	v_or3_b32 v0, v0, s8, v34
	v_lshlrev_b32_e32 v0, 1, v0
	s_waitcnt lgkmcnt(0)
	buffer_store_dwordx4 v[4:7], v0, s[20:23], 0 offen sc1
	v_mad_u64_u32 v[0:1], s[6:7], v48, s12, v[34:35]
	s_nop 0
	v_lshlrev_b32_e32 v4, 1, v48
	v_lshl_add_u32 v0, v0, 1, 0
	v_and_b32_e32 v4, 0x7e, v4
	v_lshrrev_b32_e32 v5, 11, v47
	ds_read_b128 v[0:3], v0
	v_add_u32_e32 v4, v4, v5
	v_add_lshl_u32 v4, v4, s9, 14
	v_or3_b32 v4, v4, s8, v34
	v_lshlrev_b32_e32 v8, 1, v4
	v_mad_u64_u32 v[4:5], s[6:7], v50, s12, v[34:35]
	v_lshl_add_u32 v4, v4, 1, 0
	ds_read_b128 v[4:7], v4
	s_waitcnt lgkmcnt(1)
	buffer_store_dwordx4 v[0:3], v8, s[20:23], 0 offen sc1
	s_lshl_b32 s6, s5, 6
	s_or_b32 s6, s0, s6
	v_lshlrev_b32_e32 v0, 1, v50
	v_and_b32_e32 v0, 0x7e, v0
	v_lshrrev_b32_e32 v1, 11, v49
	v_add_u32_e32 v0, v0, v1
	v_add_lshl_u32 v0, v0, s9, 14
	s_ashr_i32 s7, s6, 31
	v_or3_b32 v0, v0, s8, v34
	s_lshl_b64 s[6:7], s[6:7], 2
	v_readlane_b32 s0, v255, 1
	v_lshlrev_b32_e32 v0, 1, v0
	s_add_u32 s6, s0, s6
	v_readlane_b32 s0, v255, 2
	s_waitcnt lgkmcnt(0)
	buffer_store_dwordx4 v[4:7], v0, s[20:23], 0 offen sc1
	s_addc_u32 s7, s0, s7

.LBB0_760:
	v_lshrrev_b32_e32 v17, 3, v207
	s_waitcnt vmcnt(3)
	v_or_b32_e32 v122, s9, v17
	v_lshlrev_b32_e32 v18, 3, v207
	v_ashrrev_i32_e32 v123, 31, v122
	v_or_b32_e32 v120, 8, v122
	v_and_b32_e32 v37, 56, v18
	v_lshlrev_b64 v[18:19], 13, v[122:123]
	v_ashrrev_i32_e32 v121, 31, v120
	v_lshl_add_u64 v[18:19], s[70:71], 0, v[18:19]
	s_lshl_b32 s92, s8, 1
	v_lshlrev_b64 v[34:35], 13, v[120:121]
	v_lshl_add_u64 v[18:19], v[18:19], 0, s[92:93]
	v_lshlrev_b32_e32 v32, 1, v37
	v_lshl_add_u64 v[34:35], s[70:71], 0, v[34:35]
	v_lshl_add_u64 v[18:19], v[18:19], 0, v[32:33]
	v_lshl_add_u64 v[34:35], v[34:35], 0, s[92:93]
	v_lshl_add_u64 v[34:35], v[34:35], 0, v[32:33]
	global_load_dwordx4 v[114:117], v[18:19], off offset:1536 nt
	global_load_dwordx4 v[110:113], v[34:35], off offset:1536 nt
	v_or_b32_e32 v118, 16, v122
	v_or_b32_e32 v74, 24, v122
	v_ashrrev_i32_e32 v119, 31, v118
	v_ashrrev_i32_e32 v75, 31, v74
	v_lshlrev_b64 v[18:19], 13, v[118:119]
	v_lshlrev_b64 v[34:35], 13, v[74:75]
	v_lshl_add_u64 v[18:19], s[70:71], 0, v[18:19]
	v_lshl_add_u64 v[34:35], s[70:71], 0, v[34:35]
	v_lshl_add_u64 v[18:19], v[18:19], 0, s[92:93]
	v_lshl_add_u64 v[34:35], v[34:35], 0, s[92:93]
	v_or_b32_e32 v46, 32, v122
	v_or_b32_e32 v38, 40, v122
	v_lshl_add_u64 v[18:19], v[18:19], 0, v[32:33]
	v_lshl_add_u64 v[34:35], v[34:35], 0, v[32:33]
	v_ashrrev_i32_e32 v47, 31, v46
	v_ashrrev_i32_e32 v39, 31, v38
	global_load_dwordx4 v[104:107], v[18:19], off offset:1536 nt
	global_load_dwordx4 v[100:103], v[34:35], off offset:1536 nt
	v_lshlrev_b64 v[18:19], 13, v[46:47]
	v_lshlrev_b64 v[34:35], 13, v[38:39]
	v_lshl_add_u64 v[18:19], s[70:71], 0, v[18:19]
	v_lshl_add_u64 v[34:35], s[70:71], 0, v[34:35]
	v_lshl_add_u64 v[18:19], v[18:19], 0, s[92:93]
	v_lshl_add_u64 v[34:35], v[34:35], 0, s[92:93]
	v_lshl_add_u64 v[18:19], v[18:19], 0, v[32:33]
	v_lshl_add_u64 v[34:35], v[34:35], 0, v[32:33]
	global_load_dwordx4 v[96:99], v[18:19], off offset:1536 nt
	global_load_dwordx4 v[92:95], v[34:35], off offset:1536 nt
	v_or_b32_e32 v34, 48, v122
	v_ashrrev_i32_e32 v35, 31, v34
	v_lshlrev_b64 v[18:19], 13, v[34:35]
	v_lshl_add_u64 v[18:19], s[70:71], 0, v[18:19]
	v_lshl_add_u64 v[18:19], v[18:19], 0, s[92:93]
	v_lshl_add_u64 v[66:67], v[18:19], 0, v[32:33]
	v_or_b32_e32 v18, 56, v122
	v_ashrrev_i32_e32 v19, 31, v18
	v_lshlrev_b64 v[68:69], 13, v[18:19]
	v_div_scale_f32 v19, s[6:7], v108, v108, 1.0
	v_rcp_f32_e32 v35, v19
	v_lshl_add_u64 v[68:69], s[70:71], 0, v[68:69]
	v_readlane_b32 s8, v254, 45
	v_lshl_add_u64 v[68:69], v[68:69], 0, s[92:93]
	v_fma_f32 v39, -v19, v35, 1.0
	v_fmac_f32_e32 v35, v39, v35
	v_div_scale_f32 v39, vcc, 1.0, v108, 1.0
	v_mul_f32_e32 v45, v39, v35
	v_fma_f32 v47, -v19, v45, v39
	v_fmac_f32_e32 v45, v47, v35
	v_fma_f32 v19, -v19, v45, v39
	v_div_fmas_f32 v19, v19, v35, v45
	v_div_scale_f32 v35, s[6:7], v64, v64, 1.0
	v_rcp_f32_e32 v39, v35
	v_div_fixup_f32 v108, v19, v108, 1.0
	v_add3_u32 v19, s8, v208, v209
	v_lshl_add_u64 v[68:69], v[68:69], 0, v[32:33]
	v_fma_f32 v45, -v35, v39, 1.0
	v_fmac_f32_e32 v39, v45, v39
	v_div_scale_f32 v45, vcc, 1.0, v64, 1.0
	v_mul_f32_e32 v47, v45, v39
	v_fma_f32 v65, -v35, v47, v45
	v_fmac_f32_e32 v47, v65, v39
	v_fma_f32 v35, -v35, v47, v45
	v_div_fmas_f32 v35, v35, v39, v47
	v_div_fixup_f32 v64, v35, v64, 1.0
	v_pk_mul_f32 v[62:63], v[64:65], v[62:63] op_sel_hi:[0,1]
	v_pk_mul_f32 v[60:61], v[64:65], v[60:61] op_sel_hi:[0,1]
	v_pk_mul_f32 v[50:51], v[64:65], v[50:51] op_sel_hi:[0,1]
	v_pk_mul_f32 v[48:49], v[64:65], v[48:49] op_sel_hi:[0,1]
	v_div_scale_f32 v39, s[6:7], v44, v44, 1.0
	v_cvt_pk_bf16_f32 v60, v60, v61
	v_cvt_pk_bf16_f32 v61, v62, v63
	v_cvt_pk_bf16_f32 v48, v48, v49
	v_cvt_pk_bf16_f32 v49, v50, v51
	v_add_u32_e32 v35, 0x800, v19
	v_rcp_f32_e32 v45, v39
	global_load_dwordx4 v[70:73], v[66:67], off offset:1536 nt
	s_nop 0
	global_load_dwordx4 v[66:69], v[68:69], off offset:1536 nt
	s_barrier
	ds_write2_b64 v35, v[60:61], v[48:49] offset0:32 offset1:36
	v_pk_mul_f32 v[48:49], v[64:65], v[58:59] op_sel_hi:[0,1]
	v_pk_mul_f32 v[50:51], v[64:65], v[56:57] op_sel_hi:[0,1]
	v_cvt_pk_bf16_f32 v50, v50, v51
	v_cvt_pk_bf16_f32 v51, v48, v49
	v_pk_mul_f32 v[48:49], v[64:65], v[54:55] op_sel_hi:[0,1]
	v_pk_mul_f32 v[52:53], v[64:65], v[52:53] op_sel_hi:[0,1]
	v_cvt_pk_bf16_f32 v52, v52, v53
	v_cvt_pk_bf16_f32 v53, v48, v49
	ds_write2_b64 v35, v[50:51], v[52:53] offset0:40 offset1:44
	v_fma_f32 v35, -v39, v45, 1.0
	v_fmac_f32_e32 v45, v35, v45
	v_div_scale_f32 v35, vcc, 1.0, v44, 1.0
	v_mul_f32_e32 v47, v35, v45
	v_fma_f32 v48, -v39, v47, v35
	v_fmac_f32_e32 v47, v48, v45
	v_fma_f32 v35, -v39, v47, v35
	v_div_fmas_f32 v35, v35, v45, v47
	v_div_fixup_f32 v44, v35, v44, 1.0
	v_pk_mul_f32 v[42:43], v[44:45], v[42:43] op_sel_hi:[0,1]
	v_pk_mul_f32 v[40:41], v[44:45], v[40:41] op_sel_hi:[0,1]
	v_pk_mul_f32 v[22:23], v[44:45], v[22:23] op_sel_hi:[0,1]
	v_pk_mul_f32 v[20:21], v[44:45], v[20:21] op_sel_hi:[0,1]
	v_cvt_pk_bf16_f32 v40, v40, v41
	v_cvt_pk_bf16_f32 v41, v42, v43
	v_cvt_pk_bf16_f32 v20, v20, v21
	v_cvt_pk_bf16_f32 v21, v22, v23
	v_add_u32_e32 v35, 0x1000, v19
	ds_write2_b64 v35, v[40:41], v[20:21] offset0:64 offset1:68
	v_pk_mul_f32 v[20:21], v[44:45], v[30:31] op_sel_hi:[0,1]
	v_pk_mul_f32 v[22:23], v[44:45], v[28:29] op_sel_hi:[0,1]
	v_cvt_pk_bf16_f32 v22, v22, v23
	v_cvt_pk_bf16_f32 v23, v20, v21
	v_pk_mul_f32 v[20:21], v[44:45], v[26:27] op_sel_hi:[0,1]
	v_div_scale_f32 v26, s[6:7], v16, v16, 1.0
	v_rcp_f32_e32 v27, v26
	v_pk_mul_f32 v[24:25], v[44:45], v[24:25] op_sel_hi:[0,1]
	v_cvt_pk_bf16_f32 v24, v24, v25
	v_cvt_pk_bf16_f32 v25, v20, v21
	v_fma_f32 v20, -v26, v27, 1.0
	v_fmac_f32_e32 v27, v20, v27
	v_div_scale_f32 v20, vcc, 1.0, v16, 1.0
	v_mul_f32_e32 v21, v20, v27
	ds_write2_b64 v35, v[22:23], v[24:25] offset0:72 offset1:76
	v_fma_f32 v22, -v26, v21, v20
	v_fmac_f32_e32 v21, v22, v27
	v_fma_f32 v20, -v26, v21, v20
	v_div_fmas_f32 v20, v20, v27, v21
	v_div_fixup_f32 v16, v20, v16, 1.0
	v_pk_mul_f32 v[10:11], v[16:17], v[10:11] op_sel_hi:[0,1]
	v_pk_mul_f32 v[8:9], v[16:17], v[8:9] op_sel_hi:[0,1]
	v_pk_mul_f32 v[2:3], v[16:17], v[2:3] op_sel_hi:[0,1]
	v_pk_mul_f32 v[0:1], v[16:17], v[0:1] op_sel_hi:[0,1]
	v_cvt_pk_bf16_f32 v8, v8, v9
	v_cvt_pk_bf16_f32 v9, v10, v11
	v_cvt_pk_bf16_f32 v0, v0, v1
	v_cvt_pk_bf16_f32 v1, v2, v3
	v_add_u32_e32 v10, 0x1800, v19
	v_readlane_b32 s0, v254, 46
	ds_write2_b64 v10, v[8:9], v[0:1] offset0:96 offset1:100
	v_pk_mul_f32 v[0:1], v[16:17], v[14:15] op_sel_hi:[0,1]
	v_pk_mul_f32 v[2:3], v[16:17], v[12:13] op_sel_hi:[0,1]
	s_add_u32 s6, s0, s92
	v_readlane_b32 s0, v254, 47
	v_cvt_pk_bf16_f32 v2, v2, v3
	v_cvt_pk_bf16_f32 v3, v0, v1
	v_pk_mul_f32 v[0:1], v[16:17], v[6:7] op_sel_hi:[0,1]
	v_pk_mul_f32 v[4:5], v[16:17], v[4:5] op_sel_hi:[0,1]
	s_addc_u32 s7, s0, 0
	s_movk_i32 s0, 0x48
	v_cvt_pk_bf16_f32 v4, v4, v5
	v_cvt_pk_bf16_f32 v5, v0, v1
	v_mad_u32_u24 v0, v17, s0, v37
	ds_write2_b64 v10, v[2:3], v[4:5] offset0:104 offset1:108
	v_lshl_add_u32 v2, v0, 1, s8
	s_waitcnt vmcnt(7)
	v_lshlrev_b32_e32 v0, 16, v114
	v_and_b32_e32 v1, 0xffff0000, v114
	v_mul_f32_e32 v3, 0xbfb8aa3b, v0
	v_pk_mul_f32 v[90:91], v[108:109], v[90:91] op_sel_hi:[0,1]
	v_pk_mul_f32 v[88:89], v[108:109], v[88:89] op_sel_hi:[0,1]
	v_pk_mul_f32 v[78:79], v[108:109], v[78:79] op_sel_hi:[0,1]
	v_pk_mul_f32 v[76:77], v[108:109], v[76:77] op_sel_hi:[0,1]
	v_exp_f32_e32 v3, v3
	v_mul_f32_e32 v4, 0xbfb8aa3b, v1
	v_cvt_pk_bf16_f32 v88, v88, v89
	v_cvt_pk_bf16_f32 v89, v90, v91
	v_cvt_pk_bf16_f32 v76, v76, v77
	v_cvt_pk_bf16_f32 v77, v78, v79
	v_exp_f32_e32 v8, v4
	ds_write2_b64 v19, v[88:89], v[76:77] offset1:4
	v_pk_mul_f32 v[76:77], v[108:109], v[86:87] op_sel_hi:[0,1]
	v_pk_mul_f32 v[78:79], v[108:109], v[84:85] op_sel_hi:[0,1]
	v_cvt_pk_bf16_f32 v78, v78, v79
	v_cvt_pk_bf16_f32 v79, v76, v77
	v_pk_mul_f32 v[76:77], v[108:109], v[82:83] op_sel_hi:[0,1]
	v_pk_mul_f32 v[80:81], v[108:109], v[80:81] op_sel_hi:[0,1]
	v_cvt_pk_bf16_f32 v80, v80, v81
	v_cvt_pk_bf16_f32 v81, v76, v77
	v_add_f32_e32 v3, 1.0, v3
	ds_write2_b64 v19, v[78:79], v[80:81] offset0:8 offset1:12
	v_rcp_f32_e32 v12, v3
	v_add_f32_e32 v3, 1.0, v8
	s_waitcnt lgkmcnt(0)
	v_rcp_f32_e32 v13, v3
	ds_read_b128 v[4:7], v2
	ds_read_b128 v[8:11], v2 offset:1152
	s_mov_b32 s18, s94
	v_pk_mul_f32 v[0:1], v[12:13], v[0:1]
	v_lshlrev_b32_e32 v12, 16, v115
	v_and_b32_e32 v13, 0xffff0000, v115
	v_mul_f32_e32 v3, 0xbfb8aa3b, v12
	s_waitcnt lgkmcnt(1)
	v_lshlrev_b32_e32 v14, 16, v4
	v_and_b32_e32 v15, 0xffff0000, v4
	v_exp_f32_e32 v3, v3
	v_mul_f32_e32 v4, 0xbfb8aa3b, v13
	v_exp_f32_e32 v4, v4
	v_pk_mul_f32 v[0:1], v[0:1], v[14:15]
	v_add_f32_e32 v3, 1.0, v3
	v_rcp_f32_e32 v14, v3
	v_add_f32_e32 v3, 1.0, v4
	v_rcp_f32_e32 v15, v3
	v_cvt_pk_bf16_f32 v4, v0, v1
	v_lshlrev_b32_e32 v0, 16, v5
	v_and_b32_e32 v1, 0xffff0000, v5
	v_pk_mul_f32 v[12:13], v[14:15], v[12:13]
	v_lshlrev_b32_e32 v14, 16, v116
	v_and_b32_e32 v15, 0xffff0000, v116
	v_mul_f32_e32 v3, 0xbfb8aa3b, v14
	v_exp_f32_e32 v3, v3
	v_mul_f32_e32 v5, 0xbfb8aa3b, v15
	v_exp_f32_e32 v5, v5
	v_pk_mul_f32 v[0:1], v[12:13], v[0:1]
	v_add_f32_e32 v3, 1.0, v3
	v_rcp_f32_e32 v12, v3
	v_add_f32_e32 v3, 1.0, v5
	v_rcp_f32_e32 v13, v3
	v_cvt_pk_bf16_f32 v5, v0, v1
	v_lshlrev_b32_e32 v0, 16, v6
	v_and_b32_e32 v1, 0xffff0000, v6
	v_pk_mul_f32 v[12:13], v[12:13], v[14:15]
	v_lshlrev_b32_e32 v14, 16, v117
	v_and_b32_e32 v15, 0xffff0000, v117
	v_mul_f32_e32 v3, 0xbfb8aa3b, v14
	v_exp_f32_e32 v3, v3
	v_mul_f32_e32 v6, 0xbfb8aa3b, v15
	v_exp_f32_e32 v6, v6
	v_pk_mul_f32 v[0:1], v[12:13], v[0:1]
	v_add_f32_e32 v3, 1.0, v3
	v_rcp_f32_e32 v12, v3
	v_add_f32_e32 v3, 1.0, v6
	v_rcp_f32_e32 v13, v3
	v_cvt_pk_bf16_f32 v6, v0, v1
	v_lshlrev_b32_e32 v0, 16, v7
	v_and_b32_e32 v1, 0xffff0000, v7
	v_pk_mul_f32 v[12:13], v[12:13], v[14:15]
	s_waitcnt vmcnt(6)
	v_lshlrev_b32_e32 v14, 16, v110
	v_and_b32_e32 v15, 0xffff0000, v110
	v_mul_f32_e32 v3, 0xbfb8aa3b, v14
	v_exp_f32_e32 v3, v3
	v_mul_f32_e32 v16, 0xbfb8aa3b, v15
	v_pk_mul_f32 v[0:1], v[12:13], v[0:1]
	v_exp_f32_e32 v17, v16
	v_cvt_pk_bf16_f32 v7, v0, v1
	v_mov_b64_e32 v[0:1], s[6:7]
	v_mad_i64_i32 v[12:13], s[6:7], v122, s44, v[0:1]
	v_lshl_add_u64 v[12:13], v[12:13], 0, v[32:33]
	v_add_f32_e32 v3, 1.0, v3
	v_rcp_f32_e32 v16, v3
	v_add_f32_e32 v3, 1.0, v17
	global_store_dwordx4 v[12:13], v[4:7], off
	v_lshlrev_b32_e32 v12, 16, v111
	v_rcp_f32_e32 v17, v3
	v_and_b32_e32 v13, 0xffff0000, v111
	v_mul_f32_e32 v3, 0xbfb8aa3b, v12
	s_waitcnt lgkmcnt(0)
	v_lshlrev_b32_e32 v4, 16, v8
	v_and_b32_e32 v5, 0xffff0000, v8
	v_exp_f32_e32 v3, v3
	v_mul_f32_e32 v8, 0xbfb8aa3b, v13
	v_exp_f32_e32 v8, v8
	v_pk_mul_f32 v[6:7], v[16:17], v[14:15]
	v_add_f32_e32 v3, 1.0, v3
	v_pk_mul_f32 v[4:5], v[6:7], v[4:5]
	v_rcp_f32_e32 v6, v3
	v_add_f32_e32 v3, 1.0, v8
	v_rcp_f32_e32 v7, v3
	v_cvt_pk_bf16_f32 v4, v4, v5
	v_lshlrev_b32_e32 v8, 16, v9
	v_and_b32_e32 v9, 0xffff0000, v9
	v_pk_mul_f32 v[6:7], v[6:7], v[12:13]
	v_lshlrev_b32_e32 v12, 16, v112
	v_and_b32_e32 v13, 0xffff0000, v112
	v_mul_f32_e32 v3, 0xbfb8aa3b, v12
	v_exp_f32_e32 v3, v3
	v_mul_f32_e32 v5, 0xbfb8aa3b, v13
	v_exp_f32_e32 v5, v5
	v_pk_mul_f32 v[6:7], v[6:7], v[8:9]
	v_add_f32_e32 v3, 1.0, v3
	v_rcp_f32_e32 v8, v3
	v_add_f32_e32 v3, 1.0, v5
	v_rcp_f32_e32 v9, v3
	v_cvt_pk_bf16_f32 v5, v6, v7
	v_lshlrev_b32_e32 v6, 16, v10
	v_and_b32_e32 v7, 0xffff0000, v10
	v_pk_mul_f32 v[8:9], v[8:9], v[12:13]
	v_lshlrev_b32_e32 v12, 16, v113
	v_and_b32_e32 v13, 0xffff0000, v113
	v_mul_f32_e32 v3, 0xbfb8aa3b, v12
	v_exp_f32_e32 v3, v3
	v_mul_f32_e32 v10, 0xbfb8aa3b, v13
	v_exp_f32_e32 v10, v10
	v_pk_mul_f32 v[6:7], v[8:9], v[6:7]
	v_add_f32_e32 v3, 1.0, v3
	v_rcp_f32_e32 v8, v3
	v_add_f32_e32 v3, 1.0, v10
	v_rcp_f32_e32 v9, v3
	v_lshlrev_b32_e32 v10, 16, v11
	v_and_b32_e32 v11, 0xffff0000, v11
	v_cvt_pk_bf16_f32 v6, v6, v7
	v_pk_mul_f32 v[8:9], v[8:9], v[12:13]
	s_waitcnt vmcnt(6)
	v_lshlrev_b32_e32 v12, 16, v104
	v_pk_mul_f32 v[8:9], v[8:9], v[10:11]
	v_and_b32_e32 v13, 0xffff0000, v104
	v_cvt_pk_bf16_f32 v7, v8, v9
	v_mad_i64_i32 v[8:9], s[6:7], v120, s44, v[0:1]
	v_lshl_add_u64 v[8:9], v[8:9], 0, v[32:33]
	v_mul_f32_e32 v3, 0xbfb8aa3b, v12
	global_store_dwordx4 v[8:9], v[4:7], off
	v_exp_f32_e32 v3, v3
	s_nop 0
	v_mul_f32_e32 v4, 0xbfb8aa3b, v13
	v_exp_f32_e32 v8, v4
	v_add_f32_e32 v3, 1.0, v3
	v_rcp_f32_e32 v14, v3
	ds_read_b128 v[4:7], v2 offset:2304
	v_add_f32_e32 v3, 1.0, v8
	v_rcp_f32_e32 v15, v3
	ds_read_b128 v[8:11], v2 offset:3456
	s_waitcnt lgkmcnt(1)
	v_lshlrev_b32_e32 v16, 16, v4
	v_pk_mul_f32 v[12:13], v[14:15], v[12:13]
	v_lshlrev_b32_e32 v14, 16, v105
	v_and_b32_e32 v15, 0xffff0000, v105
	v_mul_f32_e32 v3, 0xbfb8aa3b, v14
	v_and_b32_e32 v17, 0xffff0000, v4
	v_exp_f32_e32 v3, v3
	v_mul_f32_e32 v4, 0xbfb8aa3b, v15
	v_exp_f32_e32 v4, v4
	v_pk_mul_f32 v[12:13], v[12:13], v[16:17]
	v_add_f32_e32 v3, 1.0, v3
	v_rcp_f32_e32 v16, v3
	v_add_f32_e32 v3, 1.0, v4
	v_rcp_f32_e32 v17, v3
	v_cvt_pk_bf16_f32 v4, v12, v13
	v_lshlrev_b32_e32 v12, 16, v5
	v_and_b32_e32 v13, 0xffff0000, v5
	v_pk_mul_f32 v[14:15], v[16:17], v[14:15]
	v_lshlrev_b32_e32 v16, 16, v106
	v_and_b32_e32 v17, 0xffff0000, v106
	v_mul_f32_e32 v3, 0xbfb8aa3b, v16
	v_exp_f32_e32 v3, v3
	v_mul_f32_e32 v5, 0xbfb8aa3b, v17
	v_exp_f32_e32 v5, v5
	v_pk_mul_f32 v[12:13], v[14:15], v[12:13]
	v_add_f32_e32 v3, 1.0, v3
	v_rcp_f32_e32 v14, v3
	v_add_f32_e32 v3, 1.0, v5
	v_rcp_f32_e32 v15, v3
	v_cvt_pk_bf16_f32 v5, v12, v13
	v_lshlrev_b32_e32 v12, 16, v6
	v_and_b32_e32 v13, 0xffff0000, v6
	v_pk_mul_f32 v[14:15], v[14:15], v[16:17]
	v_lshlrev_b32_e32 v16, 16, v107
	v_and_b32_e32 v17, 0xffff0000, v107
	v_mul_f32_e32 v3, 0xbfb8aa3b, v16
	v_exp_f32_e32 v3, v3
	v_mul_f32_e32 v6, 0xbfb8aa3b, v17
	v_exp_f32_e32 v6, v6
	v_pk_mul_f32 v[12:13], v[14:15], v[12:13]
	v_add_f32_e32 v3, 1.0, v3
	v_rcp_f32_e32 v14, v3
	v_add_f32_e32 v3, 1.0, v6
	v_rcp_f32_e32 v15, v3
	v_cvt_pk_bf16_f32 v6, v12, v13
	v_lshlrev_b32_e32 v12, 16, v7
	v_and_b32_e32 v13, 0xffff0000, v7
	v_pk_mul_f32 v[14:15], v[14:15], v[16:17]
	s_nop 0
	v_pk_mul_f32 v[12:13], v[14:15], v[12:13]
	s_waitcnt vmcnt(6)
	v_lshlrev_b32_e32 v14, 16, v100
	v_and_b32_e32 v15, 0xffff0000, v100
	v_mul_f32_e32 v3, 0xbfb8aa3b, v14
	v_exp_f32_e32 v3, v3
	v_mul_f32_e32 v16, 0xbfb8aa3b, v15
	v_exp_f32_e32 v17, v16
	v_cvt_pk_bf16_f32 v7, v12, v13
	v_mad_i64_i32 v[12:13], s[6:7], v118, s44, v[0:1]
	v_lshl_add_u64 v[12:13], v[12:13], 0, v[32:33]
	v_add_f32_e32 v3, 1.0, v3
	v_rcp_f32_e32 v16, v3
	v_add_f32_e32 v3, 1.0, v17
	global_store_dwordx4 v[12:13], v[4:7], off
	v_lshlrev_b32_e32 v12, 16, v101
	v_rcp_f32_e32 v17, v3
	v_and_b32_e32 v13, 0xffff0000, v101
	v_mul_f32_e32 v3, 0xbfb8aa3b, v12
	s_waitcnt lgkmcnt(0)
	v_lshlrev_b32_e32 v4, 16, v8
	v_and_b32_e32 v5, 0xffff0000, v8
	v_exp_f32_e32 v3, v3
	v_mul_f32_e32 v8, 0xbfb8aa3b, v13
	v_exp_f32_e32 v8, v8
	v_pk_mul_f32 v[6:7], v[16:17], v[14:15]
	v_add_f32_e32 v3, 1.0, v3
	v_pk_mul_f32 v[4:5], v[6:7], v[4:5]
	v_rcp_f32_e32 v6, v3
	v_add_f32_e32 v3, 1.0, v8
	v_rcp_f32_e32 v7, v3
	v_cvt_pk_bf16_f32 v4, v4, v5
	v_lshlrev_b32_e32 v8, 16, v9
	v_and_b32_e32 v9, 0xffff0000, v9
	v_pk_mul_f32 v[6:7], v[6:7], v[12:13]
	v_lshlrev_b32_e32 v12, 16, v102
	v_and_b32_e32 v13, 0xffff0000, v102
	v_mul_f32_e32 v3, 0xbfb8aa3b, v12
	v_exp_f32_e32 v3, v3
	v_mul_f32_e32 v5, 0xbfb8aa3b, v13
	v_exp_f32_e32 v5, v5
	v_pk_mul_f32 v[6:7], v[6:7], v[8:9]
	v_add_f32_e32 v3, 1.0, v3
	v_rcp_f32_e32 v8, v3
	v_add_f32_e32 v3, 1.0, v5
	v_rcp_f32_e32 v9, v3
	v_cvt_pk_bf16_f32 v5, v6, v7
	v_lshlrev_b32_e32 v6, 16, v10
	v_and_b32_e32 v7, 0xffff0000, v10
	v_pk_mul_f32 v[8:9], v[8:9], v[12:13]
	v_lshlrev_b32_e32 v12, 16, v103
	v_and_b32_e32 v13, 0xffff0000, v103
	v_mul_f32_e32 v3, 0xbfb8aa3b, v12
	v_exp_f32_e32 v3, v3
	v_mul_f32_e32 v10, 0xbfb8aa3b, v13
	v_exp_f32_e32 v10, v10
	v_pk_mul_f32 v[6:7], v[8:9], v[6:7]
	v_add_f32_e32 v3, 1.0, v3
	v_rcp_f32_e32 v8, v3
	v_add_f32_e32 v3, 1.0, v10
	v_rcp_f32_e32 v9, v3
	v_lshlrev_b32_e32 v10, 16, v11
	v_and_b32_e32 v11, 0xffff0000, v11
	v_cvt_pk_bf16_f32 v6, v6, v7
	v_pk_mul_f32 v[8:9], v[8:9], v[12:13]
	s_waitcnt vmcnt(6)
	v_lshlrev_b32_e32 v12, 16, v96
	v_pk_mul_f32 v[8:9], v[8:9], v[10:11]
	v_and_b32_e32 v13, 0xffff0000, v96
	v_cvt_pk_bf16_f32 v7, v8, v9
	v_mad_i64_i32 v[8:9], s[6:7], v74, s44, v[0:1]
	v_lshl_add_u64 v[8:9], v[8:9], 0, v[32:33]
	v_mul_f32_e32 v3, 0xbfb8aa3b, v12
	global_store_dwordx4 v[8:9], v[4:7], off
	v_exp_f32_e32 v3, v3
	s_nop 0
	v_mul_f32_e32 v4, 0xbfb8aa3b, v13
	v_exp_f32_e32 v8, v4
	v_add_f32_e32 v3, 1.0, v3
	v_rcp_f32_e32 v14, v3
	ds_read_b128 v[4:7], v2 offset:4608
	v_add_f32_e32 v3, 1.0, v8
	v_rcp_f32_e32 v15, v3
	ds_read_b128 v[8:11], v2 offset:5760
	s_waitcnt lgkmcnt(1)
	v_lshlrev_b32_e32 v16, 16, v4
	v_pk_mul_f32 v[12:13], v[14:15], v[12:13]
	v_lshlrev_b32_e32 v14, 16, v97
	v_and_b32_e32 v15, 0xffff0000, v97
	v_mul_f32_e32 v3, 0xbfb8aa3b, v14
	v_and_b32_e32 v17, 0xffff0000, v4
	v_exp_f32_e32 v3, v3
	v_mul_f32_e32 v4, 0xbfb8aa3b, v15
	v_exp_f32_e32 v4, v4
	v_pk_mul_f32 v[12:13], v[12:13], v[16:17]
	v_add_f32_e32 v3, 1.0, v3
	v_rcp_f32_e32 v16, v3
	v_add_f32_e32 v3, 1.0, v4
	v_rcp_f32_e32 v17, v3
	v_cvt_pk_bf16_f32 v4, v12, v13
	v_lshlrev_b32_e32 v12, 16, v5
	v_and_b32_e32 v13, 0xffff0000, v5
	v_pk_mul_f32 v[14:15], v[16:17], v[14:15]
	v_lshlrev_b32_e32 v16, 16, v98
	v_and_b32_e32 v17, 0xffff0000, v98
	v_mul_f32_e32 v3, 0xbfb8aa3b, v16
	v_exp_f32_e32 v3, v3
	v_mul_f32_e32 v5, 0xbfb8aa3b, v17
	v_exp_f32_e32 v5, v5
	v_pk_mul_f32 v[12:13], v[14:15], v[12:13]
	v_add_f32_e32 v3, 1.0, v3
	v_rcp_f32_e32 v14, v3
	v_add_f32_e32 v3, 1.0, v5
	v_rcp_f32_e32 v15, v3
	v_cvt_pk_bf16_f32 v5, v12, v13
	v_lshlrev_b32_e32 v12, 16, v6
	v_and_b32_e32 v13, 0xffff0000, v6
	v_pk_mul_f32 v[14:15], v[14:15], v[16:17]
	v_lshlrev_b32_e32 v16, 16, v99
	v_and_b32_e32 v17, 0xffff0000, v99
	v_mul_f32_e32 v3, 0xbfb8aa3b, v16
	v_exp_f32_e32 v3, v3
	v_mul_f32_e32 v6, 0xbfb8aa3b, v17
	v_exp_f32_e32 v6, v6
	v_pk_mul_f32 v[12:13], v[14:15], v[12:13]
	v_add_f32_e32 v3, 1.0, v3
	v_rcp_f32_e32 v14, v3
	v_add_f32_e32 v3, 1.0, v6
	v_rcp_f32_e32 v15, v3
	v_cvt_pk_bf16_f32 v6, v12, v13
	v_lshlrev_b32_e32 v12, 16, v7
	v_and_b32_e32 v13, 0xffff0000, v7
	v_pk_mul_f32 v[14:15], v[14:15], v[16:17]
	s_nop 0
	v_pk_mul_f32 v[12:13], v[14:15], v[12:13]
	s_waitcnt vmcnt(6)
	v_lshlrev_b32_e32 v14, 16, v92
	v_and_b32_e32 v15, 0xffff0000, v92
	v_mul_f32_e32 v3, 0xbfb8aa3b, v14
	v_exp_f32_e32 v3, v3
	v_mul_f32_e32 v16, 0xbfb8aa3b, v15
	v_exp_f32_e32 v17, v16
	v_cvt_pk_bf16_f32 v7, v12, v13
	v_mad_i64_i32 v[12:13], s[6:7], v46, s44, v[0:1]
	v_lshl_add_u64 v[12:13], v[12:13], 0, v[32:33]
	v_add_f32_e32 v3, 1.0, v3
	v_rcp_f32_e32 v16, v3
	v_add_f32_e32 v3, 1.0, v17
	global_store_dwordx4 v[12:13], v[4:7], off
	v_lshlrev_b32_e32 v12, 16, v93
	v_rcp_f32_e32 v17, v3
	v_and_b32_e32 v13, 0xffff0000, v93
	v_mul_f32_e32 v3, 0xbfb8aa3b, v12
	s_waitcnt lgkmcnt(0)
	v_lshlrev_b32_e32 v4, 16, v8
	v_and_b32_e32 v5, 0xffff0000, v8
	v_exp_f32_e32 v3, v3
	v_mul_f32_e32 v8, 0xbfb8aa3b, v13
	v_exp_f32_e32 v8, v8
	v_pk_mul_f32 v[6:7], v[16:17], v[14:15]
	v_add_f32_e32 v3, 1.0, v3
	v_pk_mul_f32 v[4:5], v[6:7], v[4:5]
	v_rcp_f32_e32 v6, v3
	v_add_f32_e32 v3, 1.0, v8
	v_rcp_f32_e32 v7, v3
	v_cvt_pk_bf16_f32 v4, v4, v5
	v_lshlrev_b32_e32 v8, 16, v9
	v_and_b32_e32 v9, 0xffff0000, v9
	v_pk_mul_f32 v[6:7], v[6:7], v[12:13]
	v_lshlrev_b32_e32 v12, 16, v94
	v_and_b32_e32 v13, 0xffff0000, v94
	v_mul_f32_e32 v3, 0xbfb8aa3b, v12
	v_exp_f32_e32 v3, v3
	v_mul_f32_e32 v5, 0xbfb8aa3b, v13
	v_exp_f32_e32 v5, v5
	v_pk_mul_f32 v[6:7], v[6:7], v[8:9]
	v_add_f32_e32 v3, 1.0, v3
	v_rcp_f32_e32 v8, v3
	v_add_f32_e32 v3, 1.0, v5
	v_rcp_f32_e32 v9, v3
	v_cvt_pk_bf16_f32 v5, v6, v7
	v_lshlrev_b32_e32 v6, 16, v10
	v_and_b32_e32 v7, 0xffff0000, v10
	v_pk_mul_f32 v[8:9], v[8:9], v[12:13]
	v_lshlrev_b32_e32 v12, 16, v95
	v_and_b32_e32 v13, 0xffff0000, v95
	v_mul_f32_e32 v3, 0xbfb8aa3b, v12
	v_exp_f32_e32 v3, v3
	v_mul_f32_e32 v10, 0xbfb8aa3b, v13
	v_exp_f32_e32 v10, v10
	v_pk_mul_f32 v[6:7], v[8:9], v[6:7]
	v_add_f32_e32 v3, 1.0, v3
	v_rcp_f32_e32 v8, v3
	v_add_f32_e32 v3, 1.0, v10
	v_rcp_f32_e32 v9, v3
	v_lshlrev_b32_e32 v10, 16, v11
	v_and_b32_e32 v11, 0xffff0000, v11
	v_cvt_pk_bf16_f32 v6, v6, v7
	v_pk_mul_f32 v[8:9], v[8:9], v[12:13]
	s_waitcnt vmcnt(6)
	v_lshlrev_b32_e32 v12, 16, v70
	v_pk_mul_f32 v[8:9], v[8:9], v[10:11]
	v_and_b32_e32 v13, 0xffff0000, v70
	v_cvt_pk_bf16_f32 v7, v8, v9
	v_mad_i64_i32 v[8:9], s[6:7], v38, s44, v[0:1]
	v_lshl_add_u64 v[8:9], v[8:9], 0, v[32:33]
	v_mul_f32_e32 v3, 0xbfb8aa3b, v12
	global_store_dwordx4 v[8:9], v[4:7], off
	v_exp_f32_e32 v3, v3
	s_nop 0
	v_mul_f32_e32 v4, 0xbfb8aa3b, v13
	v_exp_f32_e32 v8, v4
	v_add_f32_e32 v3, 1.0, v3
	v_rcp_f32_e32 v14, v3
	ds_read_b128 v[4:7], v2 offset:6912
	v_add_f32_e32 v3, 1.0, v8
	v_rcp_f32_e32 v15, v3
	ds_read_b128 v[8:11], v2 offset:8064
	s_waitcnt lgkmcnt(1)
	v_lshlrev_b32_e32 v2, 16, v4
	v_pk_mul_f32 v[12:13], v[14:15], v[12:13]
	v_lshlrev_b32_e32 v14, 16, v71
	v_and_b32_e32 v3, 0xffff0000, v4
	v_and_b32_e32 v15, 0xffff0000, v71
	v_mul_f32_e32 v4, 0xbfb8aa3b, v14
	v_exp_f32_e32 v4, v4
	v_mul_f32_e32 v16, 0xbfb8aa3b, v15
	v_exp_f32_e32 v16, v16
	v_pk_mul_f32 v[2:3], v[12:13], v[2:3]
	v_add_f32_e32 v4, 1.0, v4
	v_rcp_f32_e32 v12, v4
	v_add_f32_e32 v4, 1.0, v16
	v_rcp_f32_e32 v13, v4
	v_cvt_pk_bf16_f32 v2, v2, v3
	v_lshlrev_b32_e32 v4, 16, v5
	v_and_b32_e32 v5, 0xffff0000, v5
	v_pk_mul_f32 v[12:13], v[12:13], v[14:15]
	v_lshlrev_b32_e32 v14, 16, v72
	v_and_b32_e32 v15, 0xffff0000, v72
	v_mul_f32_e32 v3, 0xbfb8aa3b, v14
	v_exp_f32_e32 v3, v3
	v_mul_f32_e32 v16, 0xbfb8aa3b, v15
	v_exp_f32_e32 v16, v16
	v_pk_mul_f32 v[4:5], v[12:13], v[4:5]
	v_add_f32_e32 v3, 1.0, v3
	v_rcp_f32_e32 v12, v3
	v_add_f32_e32 v3, 1.0, v16
	v_rcp_f32_e32 v13, v3
	v_cvt_pk_bf16_f32 v3, v4, v5
	v_lshlrev_b32_e32 v4, 16, v6
	v_and_b32_e32 v5, 0xffff0000, v6
	v_pk_mul_f32 v[12:13], v[12:13], v[14:15]
	v_lshlrev_b32_e32 v14, 16, v73
	v_and_b32_e32 v15, 0xffff0000, v73
	v_mul_f32_e32 v6, 0xbfb8aa3b, v14
	v_exp_f32_e32 v6, v6
	v_mul_f32_e32 v16, 0xbfb8aa3b, v15
	v_exp_f32_e32 v16, v16
	v_pk_mul_f32 v[4:5], v[12:13], v[4:5]
	v_add_f32_e32 v6, 1.0, v6
	v_rcp_f32_e32 v12, v6
	v_add_f32_e32 v6, 1.0, v16
	v_rcp_f32_e32 v13, v6
	v_lshlrev_b32_e32 v6, 16, v7
	v_and_b32_e32 v7, 0xffff0000, v7
	v_cvt_pk_bf16_f32 v4, v4, v5
	v_pk_mul_f32 v[12:13], v[12:13], v[14:15]
	s_nop 0
	v_pk_mul_f32 v[6:7], v[12:13], v[6:7]
	s_waitcnt vmcnt(6)
	v_lshlrev_b32_e32 v12, 16, v66
	v_and_b32_e32 v13, 0xffff0000, v66
	v_mul_f32_e32 v14, 0xbfb8aa3b, v12
	v_mul_f32_e32 v15, 0xbfb8aa3b, v13
	v_exp_f32_e32 v14, v14
	v_exp_f32_e32 v15, v15
	v_cvt_pk_bf16_f32 v5, v6, v7
	v_mad_i64_i32 v[6:7], s[6:7], v34, s44, v[0:1]
	v_add_f32_e32 v14, 1.0, v14
	v_add_f32_e32 v15, 1.0, v15
	v_rcp_f32_e32 v14, v14
	v_rcp_f32_e32 v15, v15
	v_lshl_add_u64 v[6:7], v[6:7], 0, v[32:33]
	global_store_dwordx4 v[6:7], v[2:5], off
	v_lshlrev_b32_e32 v6, 16, v67
	v_and_b32_e32 v7, 0xffff0000, v67
	s_waitcnt lgkmcnt(0)
	v_lshlrev_b32_e32 v2, 16, v8
	v_and_b32_e32 v3, 0xffff0000, v8
	v_pk_mul_f32 v[4:5], v[14:15], v[12:13]
	v_mul_f32_e32 v8, 0xbfb8aa3b, v6
	v_mul_f32_e32 v12, 0xbfb8aa3b, v7
	v_exp_f32_e32 v8, v8
	v_exp_f32_e32 v12, v12
	v_pk_mul_f32 v[2:3], v[4:5], v[2:3]
	v_mad_i64_i32 v[0:1], s[6:7], v18, s44, v[0:1]
	v_add_f32_e32 v4, 1.0, v8
	v_add_f32_e32 v5, 1.0, v12
	v_rcp_f32_e32 v4, v4
	v_rcp_f32_e32 v5, v5
	v_cvt_pk_bf16_f32 v2, v2, v3
	v_lshlrev_b32_e32 v8, 16, v9
	v_and_b32_e32 v9, 0xffff0000, v9
	v_pk_mul_f32 v[4:5], v[4:5], v[6:7]
	v_lshlrev_b32_e32 v6, 16, v68
	v_and_b32_e32 v7, 0xffff0000, v68
	v_mul_f32_e32 v3, 0xbfb8aa3b, v6
	v_exp_f32_e32 v3, v3
	v_mul_f32_e32 v12, 0xbfb8aa3b, v7
	v_exp_f32_e32 v12, v12
	v_pk_mul_f32 v[4:5], v[4:5], v[8:9]
	v_add_f32_e32 v3, 1.0, v3
	v_rcp_f32_e32 v8, v3
	v_add_f32_e32 v3, 1.0, v12
	v_rcp_f32_e32 v9, v3
	v_cvt_pk_bf16_f32 v3, v4, v5
	v_lshlrev_b32_e32 v4, 16, v10
	v_and_b32_e32 v5, 0xffff0000, v10
	v_pk_mul_f32 v[6:7], v[8:9], v[6:7]
	v_lshlrev_b32_e32 v8, 16, v69
	v_and_b32_e32 v9, 0xffff0000, v69
	v_mul_f32_e32 v10, 0xbfb8aa3b, v8
	v_mul_f32_e32 v12, 0xbfb8aa3b, v9
	v_exp_f32_e32 v10, v10
	v_exp_f32_e32 v12, v12
	v_pk_mul_f32 v[4:5], v[6:7], v[4:5]
	v_lshl_add_u64 v[0:1], v[0:1], 0, v[32:33]
	v_add_f32_e32 v6, 1.0, v10
	v_add_f32_e32 v7, 1.0, v12
	v_rcp_f32_e32 v6, v6
	v_rcp_f32_e32 v7, v7
	v_lshlrev_b32_e32 v10, 16, v11
	v_and_b32_e32 v11, 0xffff0000, v11
	v_cvt_pk_bf16_f32 v4, v4, v5
	v_pk_mul_f32 v[6:7], v[6:7], v[8:9]
	s_mov_b64 s[6:7], s[76:77]
	v_pk_mul_f32 v[6:7], v[6:7], v[10:11]
	s_nop 0
	v_cvt_pk_bf16_f32 v5, v6, v7
	global_store_dwordx4 v[0:1], v[2:5], off

.LBB0_803:
	v_lshrrev_b32_e32 v17, 3, v207
	s_waitcnt vmcnt(3)
	v_or_b32_e32 v122, s82, v17
	v_lshlrev_b32_e32 v18, 3, v207
	v_ashrrev_i32_e32 v123, 31, v122
	v_or_b32_e32 v120, 8, v122
	v_and_b32_e32 v37, 56, v18
	v_lshlrev_b64 v[18:19], 13, v[122:123]
	v_ashrrev_i32_e32 v121, 31, v120
	v_lshl_add_u64 v[18:19], s[70:71], 0, v[18:19]
	s_lshl_b32 s92, s57, 1
	v_lshlrev_b64 v[34:35], 13, v[120:121]
	v_lshl_add_u64 v[18:19], v[18:19], 0, s[92:93]
	v_lshlrev_b32_e32 v32, 1, v37
	v_lshl_add_u64 v[34:35], s[70:71], 0, v[34:35]
	v_lshl_add_u64 v[18:19], v[18:19], 0, v[32:33]
	v_lshl_add_u64 v[34:35], v[34:35], 0, s[92:93]
	v_lshl_add_u64 v[34:35], v[34:35], 0, v[32:33]
	global_load_dwordx4 v[112:115], v[18:19], off offset:1536 nt
	global_load_dwordx4 v[108:111], v[34:35], off offset:1536 nt
	v_or_b32_e32 v118, 16, v122
	v_or_b32_e32 v66, 24, v122
	v_ashrrev_i32_e32 v119, 31, v118
	v_ashrrev_i32_e32 v67, 31, v66
	v_lshlrev_b64 v[18:19], 13, v[118:119]
	v_lshlrev_b64 v[34:35], 13, v[66:67]
	v_lshl_add_u64 v[18:19], s[70:71], 0, v[18:19]
	v_lshl_add_u64 v[34:35], s[70:71], 0, v[34:35]
	v_lshl_add_u64 v[18:19], v[18:19], 0, s[92:93]
	v_lshl_add_u64 v[34:35], v[34:35], 0, s[92:93]
	v_or_b32_e32 v46, 32, v122
	v_or_b32_e32 v38, 40, v122
	v_lshl_add_u64 v[18:19], v[18:19], 0, v[32:33]
	v_lshl_add_u64 v[34:35], v[34:35], 0, v[32:33]
	v_ashrrev_i32_e32 v47, 31, v46
	v_ashrrev_i32_e32 v39, 31, v38
	global_load_dwordx4 v[104:107], v[18:19], off offset:1536 nt
	global_load_dwordx4 v[100:103], v[34:35], off offset:1536 nt
	v_lshlrev_b64 v[18:19], 13, v[46:47]
	v_lshlrev_b64 v[34:35], 13, v[38:39]
	v_lshl_add_u64 v[18:19], s[70:71], 0, v[18:19]
	v_lshl_add_u64 v[34:35], s[70:71], 0, v[34:35]
	v_lshl_add_u64 v[18:19], v[18:19], 0, s[92:93]
	v_lshl_add_u64 v[34:35], v[34:35], 0, s[92:93]
	v_lshl_add_u64 v[18:19], v[18:19], 0, v[32:33]
	v_lshl_add_u64 v[34:35], v[34:35], 0, v[32:33]
	global_load_dwordx4 v[88:91], v[18:19], off offset:1536 nt
	global_load_dwordx4 v[84:87], v[34:35], off offset:1536 nt
	v_or_b32_e32 v34, 48, v122
	v_ashrrev_i32_e32 v35, 31, v34
	v_lshlrev_b64 v[18:19], 13, v[34:35]
	v_lshl_add_u64 v[18:19], s[70:71], 0, v[18:19]
	v_lshl_add_u64 v[18:19], v[18:19], 0, s[92:93]
	v_lshl_add_u64 v[72:73], v[18:19], 0, v[32:33]
	v_or_b32_e32 v18, 56, v122
	v_ashrrev_i32_e32 v19, 31, v18
	v_lshlrev_b64 v[74:75], 13, v[18:19]
	v_div_scale_f32 v19, s[6:7], v116, v116, 1.0
	v_rcp_f32_e32 v35, v19
	v_lshl_add_u64 v[74:75], s[70:71], 0, v[74:75]
	v_readlane_b32 s5, v254, 45
	v_lshl_add_u64 v[74:75], v[74:75], 0, s[92:93]
	v_fma_f32 v39, -v19, v35, 1.0
	v_fmac_f32_e32 v35, v39, v35
	v_div_scale_f32 v39, vcc, 1.0, v116, 1.0
	v_mul_f32_e32 v45, v39, v35
	v_fma_f32 v47, -v19, v45, v39
	v_fmac_f32_e32 v45, v47, v35
	v_fma_f32 v19, -v19, v45, v39
	v_div_fmas_f32 v19, v19, v35, v45
	v_div_scale_f32 v35, s[6:7], v64, v64, 1.0
	v_rcp_f32_e32 v39, v35
	v_div_fixup_f32 v116, v19, v116, 1.0
	v_mul_u32_u24_e32 v19, 0x90, v201
	v_add3_u32 v19, s5, v204, v19
	v_fma_f32 v45, -v35, v39, 1.0
	v_fmac_f32_e32 v39, v45, v39
	v_div_scale_f32 v45, vcc, 1.0, v64, 1.0
	v_mul_f32_e32 v47, v45, v39
	v_fma_f32 v65, -v35, v47, v45
	v_fmac_f32_e32 v47, v65, v39
	v_fma_f32 v35, -v35, v47, v45
	v_div_fmas_f32 v35, v35, v39, v47
	v_div_fixup_f32 v64, v35, v64, 1.0
	v_pk_mul_f32 v[62:63], v[62:63], v[64:65] op_sel_hi:[1,0]
	v_pk_mul_f32 v[60:61], v[60:61], v[64:65] op_sel_hi:[1,0]
	v_pk_mul_f32 v[50:51], v[50:51], v[64:65] op_sel_hi:[1,0]
	v_pk_mul_f32 v[48:49], v[48:49], v[64:65] op_sel_hi:[1,0]
	v_div_scale_f32 v39, s[6:7], v44, v44, 1.0
	v_lshl_add_u64 v[74:75], v[74:75], 0, v[32:33]
	v_cvt_pk_bf16_f32 v60, v60, v61
	v_cvt_pk_bf16_f32 v61, v62, v63
	v_cvt_pk_bf16_f32 v48, v48, v49
	v_cvt_pk_bf16_f32 v49, v50, v51
	v_add_u32_e32 v35, 0x800, v19
	v_rcp_f32_e32 v45, v39
	global_load_dwordx4 v[76:79], v[72:73], off offset:1536 nt
	s_nop 0
	global_load_dwordx4 v[72:75], v[74:75], off offset:1536 nt
	s_barrier
	ds_write2_b64 v35, v[60:61], v[48:49] offset0:32 offset1:36
	v_pk_mul_f32 v[48:49], v[58:59], v[64:65] op_sel_hi:[1,0]
	v_pk_mul_f32 v[50:51], v[56:57], v[64:65] op_sel_hi:[1,0]
	v_pk_mul_f32 v[52:53], v[64:65], v[52:53] op_sel_hi:[0,1]
	v_cvt_pk_bf16_f32 v50, v50, v51
	v_cvt_pk_bf16_f32 v51, v48, v49
	v_pk_mul_f32 v[48:49], v[64:65], v[54:55] op_sel_hi:[0,1]
	v_cvt_pk_bf16_f32 v52, v52, v53
	v_cvt_pk_bf16_f32 v53, v48, v49
	ds_write2_b64 v35, v[50:51], v[52:53] offset0:40 offset1:44
	v_fma_f32 v35, -v39, v45, 1.0
	v_fmac_f32_e32 v45, v35, v45
	v_div_scale_f32 v35, vcc, 1.0, v44, 1.0
	v_mul_f32_e32 v47, v35, v45
	v_fma_f32 v48, -v39, v47, v35
	v_fmac_f32_e32 v47, v48, v45
	v_fma_f32 v35, -v39, v47, v35
	v_div_fmas_f32 v35, v35, v45, v47
	v_div_fixup_f32 v44, v35, v44, 1.0
	v_pk_mul_f32 v[42:43], v[42:43], v[44:45] op_sel_hi:[1,0]
	v_pk_mul_f32 v[40:41], v[40:41], v[44:45] op_sel_hi:[1,0]
	v_pk_mul_f32 v[22:23], v[22:23], v[44:45] op_sel_hi:[1,0]
	v_pk_mul_f32 v[20:21], v[20:21], v[44:45] op_sel_hi:[1,0]
	v_cvt_pk_bf16_f32 v40, v40, v41
	v_cvt_pk_bf16_f32 v41, v42, v43
	v_cvt_pk_bf16_f32 v20, v20, v21
	v_cvt_pk_bf16_f32 v21, v22, v23
	v_add_u32_e32 v35, 0x1000, v19
	ds_write2_b64 v35, v[40:41], v[20:21] offset0:64 offset1:68
	v_pk_mul_f32 v[20:21], v[44:45], v[30:31] op_sel_hi:[0,1]
	v_pk_mul_f32 v[22:23], v[44:45], v[28:29] op_sel_hi:[0,1]
	v_cvt_pk_bf16_f32 v22, v22, v23
	v_cvt_pk_bf16_f32 v23, v20, v21
	v_pk_mul_f32 v[20:21], v[44:45], v[26:27] op_sel_hi:[0,1]
	v_div_scale_f32 v26, s[6:7], v16, v16, 1.0
	v_rcp_f32_e32 v27, v26
	v_pk_mul_f32 v[24:25], v[44:45], v[24:25] op_sel_hi:[0,1]
	v_cvt_pk_bf16_f32 v24, v24, v25
	v_cvt_pk_bf16_f32 v25, v20, v21
	v_fma_f32 v20, -v26, v27, 1.0
	v_fmac_f32_e32 v27, v20, v27
	v_div_scale_f32 v20, vcc, 1.0, v16, 1.0
	v_mul_f32_e32 v21, v20, v27
	ds_write2_b64 v35, v[22:23], v[24:25] offset0:72 offset1:76
	v_fma_f32 v22, -v26, v21, v20
	v_fmac_f32_e32 v21, v22, v27
	v_fma_f32 v20, -v26, v21, v20
	v_div_fmas_f32 v20, v20, v27, v21
	v_div_fixup_f32 v16, v20, v16, 1.0
	v_pk_mul_f32 v[10:11], v[10:11], v[16:17] op_sel_hi:[1,0]
	v_pk_mul_f32 v[8:9], v[8:9], v[16:17] op_sel_hi:[1,0]
	v_pk_mul_f32 v[2:3], v[2:3], v[16:17] op_sel_hi:[1,0]
	v_pk_mul_f32 v[0:1], v[0:1], v[16:17] op_sel_hi:[1,0]
	v_cvt_pk_bf16_f32 v8, v8, v9
	v_cvt_pk_bf16_f32 v9, v10, v11
	v_cvt_pk_bf16_f32 v0, v0, v1
	v_cvt_pk_bf16_f32 v1, v2, v3
	v_add_u32_e32 v10, 0x1800, v19
	v_readlane_b32 s0, v254, 46
	ds_write2_b64 v10, v[8:9], v[0:1] offset0:96 offset1:100
	v_pk_mul_f32 v[0:1], v[16:17], v[14:15] op_sel_hi:[0,1]
	v_pk_mul_f32 v[2:3], v[16:17], v[12:13] op_sel_hi:[0,1]
	s_add_u32 s6, s0, s92
	v_readlane_b32 s0, v254, 47
	v_cvt_pk_bf16_f32 v2, v2, v3
	v_cvt_pk_bf16_f32 v3, v0, v1
	v_pk_mul_f32 v[0:1], v[16:17], v[6:7] op_sel_hi:[0,1]
	v_pk_mul_f32 v[4:5], v[16:17], v[4:5] op_sel_hi:[0,1]
	s_addc_u32 s7, s0, 0
	s_movk_i32 s0, 0x48
	v_cvt_pk_bf16_f32 v4, v4, v5
	v_cvt_pk_bf16_f32 v5, v0, v1
	v_mad_u32_u24 v0, v17, s0, v37
	ds_write2_b64 v10, v[2:3], v[4:5] offset0:104 offset1:108
	v_lshl_add_u32 v2, v0, 1, s5
	s_waitcnt vmcnt(7)
	v_lshlrev_b32_e32 v0, 16, v112
	v_and_b32_e32 v1, 0xffff0000, v112
	v_mul_f32_e32 v3, 0xbfb8aa3b, v0
	v_pk_mul_f32 v[98:99], v[98:99], v[116:117] op_sel_hi:[1,0]
	v_pk_mul_f32 v[96:97], v[96:97], v[116:117] op_sel_hi:[1,0]
	v_pk_mul_f32 v[70:71], v[70:71], v[116:117] op_sel_hi:[1,0]
	v_pk_mul_f32 v[68:69], v[68:69], v[116:117] op_sel_hi:[1,0]
	v_exp_f32_e32 v3, v3
	v_mul_f32_e32 v4, 0xbfb8aa3b, v1
	v_cvt_pk_bf16_f32 v96, v96, v97
	v_cvt_pk_bf16_f32 v97, v98, v99
	v_cvt_pk_bf16_f32 v68, v68, v69
	v_cvt_pk_bf16_f32 v69, v70, v71
	v_exp_f32_e32 v8, v4
	ds_write2_b64 v19, v[96:97], v[68:69] offset1:4
	v_pk_mul_f32 v[68:69], v[94:95], v[116:117] op_sel_hi:[1,0]
	v_pk_mul_f32 v[70:71], v[92:93], v[116:117] op_sel_hi:[1,0]
	v_pk_mul_f32 v[80:81], v[116:117], v[80:81] op_sel_hi:[0,1]
	v_cvt_pk_bf16_f32 v70, v70, v71
	v_cvt_pk_bf16_f32 v71, v68, v69
	v_pk_mul_f32 v[68:69], v[116:117], v[82:83] op_sel_hi:[0,1]
	v_cvt_pk_bf16_f32 v80, v80, v81
	v_cvt_pk_bf16_f32 v81, v68, v69
	v_add_f32_e32 v3, 1.0, v3
	ds_write2_b64 v19, v[70:71], v[80:81] offset0:8 offset1:12
	v_rcp_f32_e32 v12, v3
	v_add_f32_e32 v3, 1.0, v8
	s_waitcnt lgkmcnt(0)
	v_rcp_f32_e32 v13, v3
	ds_read_b128 v[4:7], v2
	ds_read_b128 v[8:11], v2 offset:1152
	s_mov_b32 s18, s94
	v_pk_mul_f32 v[0:1], v[12:13], v[0:1]
	v_lshlrev_b32_e32 v12, 16, v113
	v_and_b32_e32 v13, 0xffff0000, v113
	v_mul_f32_e32 v3, 0xbfb8aa3b, v12
	s_waitcnt lgkmcnt(1)
	v_lshlrev_b32_e32 v14, 16, v4
	v_and_b32_e32 v15, 0xffff0000, v4
	v_exp_f32_e32 v3, v3
	v_mul_f32_e32 v4, 0xbfb8aa3b, v13
	v_exp_f32_e32 v4, v4
	v_pk_mul_f32 v[0:1], v[0:1], v[14:15]
	v_add_f32_e32 v3, 1.0, v3
	v_rcp_f32_e32 v14, v3
	v_add_f32_e32 v3, 1.0, v4
	v_rcp_f32_e32 v15, v3
	v_cvt_pk_bf16_f32 v4, v0, v1
	v_lshlrev_b32_e32 v0, 16, v5
	v_and_b32_e32 v1, 0xffff0000, v5
	v_pk_mul_f32 v[12:13], v[14:15], v[12:13]
	v_lshlrev_b32_e32 v14, 16, v114
	v_and_b32_e32 v15, 0xffff0000, v114
	v_mul_f32_e32 v3, 0xbfb8aa3b, v14
	v_exp_f32_e32 v3, v3
	v_mul_f32_e32 v5, 0xbfb8aa3b, v15
	v_exp_f32_e32 v5, v5
	v_pk_mul_f32 v[0:1], v[12:13], v[0:1]
	v_add_f32_e32 v3, 1.0, v3
	v_rcp_f32_e32 v12, v3
	v_add_f32_e32 v3, 1.0, v5
	v_rcp_f32_e32 v13, v3
	v_cvt_pk_bf16_f32 v5, v0, v1
	v_lshlrev_b32_e32 v0, 16, v6
	v_and_b32_e32 v1, 0xffff0000, v6
	v_pk_mul_f32 v[12:13], v[12:13], v[14:15]
	v_lshlrev_b32_e32 v14, 16, v115
	v_and_b32_e32 v15, 0xffff0000, v115
	v_mul_f32_e32 v3, 0xbfb8aa3b, v14
	v_exp_f32_e32 v3, v3
	v_mul_f32_e32 v6, 0xbfb8aa3b, v15
	v_exp_f32_e32 v6, v6
	v_pk_mul_f32 v[0:1], v[12:13], v[0:1]
	v_add_f32_e32 v3, 1.0, v3
	v_rcp_f32_e32 v12, v3
	v_add_f32_e32 v3, 1.0, v6
	v_rcp_f32_e32 v13, v3
	v_cvt_pk_bf16_f32 v6, v0, v1
	v_lshlrev_b32_e32 v0, 16, v7
	v_and_b32_e32 v1, 0xffff0000, v7
	v_pk_mul_f32 v[12:13], v[12:13], v[14:15]
	s_waitcnt vmcnt(6)
	v_lshlrev_b32_e32 v14, 16, v108
	v_and_b32_e32 v15, 0xffff0000, v108
	v_mul_f32_e32 v3, 0xbfb8aa3b, v14
	v_exp_f32_e32 v3, v3
	v_mul_f32_e32 v16, 0xbfb8aa3b, v15
	v_pk_mul_f32 v[0:1], v[12:13], v[0:1]
	v_exp_f32_e32 v17, v16
	v_cvt_pk_bf16_f32 v7, v0, v1
	v_mov_b64_e32 v[0:1], s[6:7]
	v_mad_i64_i32 v[12:13], s[6:7], v122, s44, v[0:1]
	v_lshl_add_u64 v[12:13], v[12:13], 0, v[32:33]
	v_add_f32_e32 v3, 1.0, v3
	v_rcp_f32_e32 v16, v3
	v_add_f32_e32 v3, 1.0, v17
	global_store_dwordx4 v[12:13], v[4:7], off
	v_lshlrev_b32_e32 v12, 16, v109
	v_rcp_f32_e32 v17, v3
	v_and_b32_e32 v13, 0xffff0000, v109
	v_mul_f32_e32 v3, 0xbfb8aa3b, v12
	s_waitcnt lgkmcnt(0)
	v_lshlrev_b32_e32 v4, 16, v8
	v_and_b32_e32 v5, 0xffff0000, v8
	v_exp_f32_e32 v3, v3
	v_mul_f32_e32 v8, 0xbfb8aa3b, v13
	v_exp_f32_e32 v8, v8
	v_pk_mul_f32 v[6:7], v[16:17], v[14:15]
	v_add_f32_e32 v3, 1.0, v3
	v_pk_mul_f32 v[4:5], v[6:7], v[4:5]
	v_rcp_f32_e32 v6, v3
	v_add_f32_e32 v3, 1.0, v8
	v_rcp_f32_e32 v7, v3
	v_cvt_pk_bf16_f32 v4, v4, v5
	v_lshlrev_b32_e32 v8, 16, v9
	v_and_b32_e32 v9, 0xffff0000, v9
	v_pk_mul_f32 v[6:7], v[6:7], v[12:13]
	v_lshlrev_b32_e32 v12, 16, v110
	v_and_b32_e32 v13, 0xffff0000, v110
	v_mul_f32_e32 v3, 0xbfb8aa3b, v12
	v_exp_f32_e32 v3, v3
	v_mul_f32_e32 v5, 0xbfb8aa3b, v13
	v_exp_f32_e32 v5, v5
	v_pk_mul_f32 v[6:7], v[6:7], v[8:9]
	v_add_f32_e32 v3, 1.0, v3
	v_rcp_f32_e32 v8, v3
	v_add_f32_e32 v3, 1.0, v5
	v_rcp_f32_e32 v9, v3
	v_cvt_pk_bf16_f32 v5, v6, v7
	v_lshlrev_b32_e32 v6, 16, v10
	v_and_b32_e32 v7, 0xffff0000, v10
	v_pk_mul_f32 v[8:9], v[8:9], v[12:13]
	v_lshlrev_b32_e32 v12, 16, v111
	v_and_b32_e32 v13, 0xffff0000, v111
	v_mul_f32_e32 v3, 0xbfb8aa3b, v12
	v_exp_f32_e32 v3, v3
	v_mul_f32_e32 v10, 0xbfb8aa3b, v13
	v_exp_f32_e32 v10, v10
	v_pk_mul_f32 v[6:7], v[8:9], v[6:7]
	v_add_f32_e32 v3, 1.0, v3
	v_rcp_f32_e32 v8, v3
	v_add_f32_e32 v3, 1.0, v10
	v_rcp_f32_e32 v9, v3
	v_lshlrev_b32_e32 v10, 16, v11
	v_and_b32_e32 v11, 0xffff0000, v11
	v_cvt_pk_bf16_f32 v6, v6, v7
	v_pk_mul_f32 v[8:9], v[8:9], v[12:13]
	s_waitcnt vmcnt(6)
	v_lshlrev_b32_e32 v12, 16, v104
	v_pk_mul_f32 v[8:9], v[8:9], v[10:11]
	v_and_b32_e32 v13, 0xffff0000, v104
	v_cvt_pk_bf16_f32 v7, v8, v9
	v_mad_i64_i32 v[8:9], s[6:7], v120, s44, v[0:1]
	v_lshl_add_u64 v[8:9], v[8:9], 0, v[32:33]
	v_mul_f32_e32 v3, 0xbfb8aa3b, v12
	global_store_dwordx4 v[8:9], v[4:7], off
	v_exp_f32_e32 v3, v3
	v_readlane_b32 s96, v254, 31
	v_mul_f32_e32 v4, 0xbfb8aa3b, v13
	v_exp_f32_e32 v8, v4
	v_add_f32_e32 v3, 1.0, v3
	v_rcp_f32_e32 v14, v3
	ds_read_b128 v[4:7], v2 offset:2304
	v_add_f32_e32 v3, 1.0, v8
	v_rcp_f32_e32 v15, v3
	ds_read_b128 v[8:11], v2 offset:3456
	v_readlane_b32 s83, v254, 33
	s_waitcnt lgkmcnt(1)
	v_lshlrev_b32_e32 v16, 16, v4
	v_pk_mul_f32 v[12:13], v[14:15], v[12:13]
	v_lshlrev_b32_e32 v14, 16, v105
	v_and_b32_e32 v15, 0xffff0000, v105
	v_mul_f32_e32 v3, 0xbfb8aa3b, v14
	v_and_b32_e32 v17, 0xffff0000, v4
	v_exp_f32_e32 v3, v3
	v_mul_f32_e32 v4, 0xbfb8aa3b, v15
	v_exp_f32_e32 v4, v4
	v_pk_mul_f32 v[12:13], v[12:13], v[16:17]
	v_add_f32_e32 v3, 1.0, v3
	v_rcp_f32_e32 v16, v3
	v_add_f32_e32 v3, 1.0, v4
	v_rcp_f32_e32 v17, v3
	v_cvt_pk_bf16_f32 v4, v12, v13
	v_lshlrev_b32_e32 v12, 16, v5
	v_and_b32_e32 v13, 0xffff0000, v5
	v_pk_mul_f32 v[14:15], v[16:17], v[14:15]
	v_lshlrev_b32_e32 v16, 16, v106
	v_and_b32_e32 v17, 0xffff0000, v106
	v_mul_f32_e32 v3, 0xbfb8aa3b, v16
	v_exp_f32_e32 v3, v3
	v_mul_f32_e32 v5, 0xbfb8aa3b, v17
	v_exp_f32_e32 v5, v5
	v_pk_mul_f32 v[12:13], v[14:15], v[12:13]
	v_add_f32_e32 v3, 1.0, v3
	v_rcp_f32_e32 v14, v3
	v_add_f32_e32 v3, 1.0, v5
	v_rcp_f32_e32 v15, v3
	v_cvt_pk_bf16_f32 v5, v12, v13
	v_lshlrev_b32_e32 v12, 16, v6
	v_and_b32_e32 v13, 0xffff0000, v6
	v_pk_mul_f32 v[14:15], v[14:15], v[16:17]
	v_lshlrev_b32_e32 v16, 16, v107
	v_and_b32_e32 v17, 0xffff0000, v107
	v_mul_f32_e32 v3, 0xbfb8aa3b, v16
	v_exp_f32_e32 v3, v3
	v_mul_f32_e32 v6, 0xbfb8aa3b, v17
	v_exp_f32_e32 v6, v6
	v_pk_mul_f32 v[12:13], v[14:15], v[12:13]
	v_add_f32_e32 v3, 1.0, v3
	v_rcp_f32_e32 v14, v3
	v_add_f32_e32 v3, 1.0, v6
	v_rcp_f32_e32 v15, v3
	v_cvt_pk_bf16_f32 v6, v12, v13
	v_lshlrev_b32_e32 v12, 16, v7
	v_and_b32_e32 v13, 0xffff0000, v7
	v_pk_mul_f32 v[14:15], v[14:15], v[16:17]
	s_movk_i32 s79, 0x100
	v_pk_mul_f32 v[12:13], v[14:15], v[12:13]
	s_waitcnt vmcnt(6)
	v_lshlrev_b32_e32 v14, 16, v100
	v_and_b32_e32 v15, 0xffff0000, v100
	v_mul_f32_e32 v3, 0xbfb8aa3b, v14
	v_exp_f32_e32 v3, v3
	v_mul_f32_e32 v16, 0xbfb8aa3b, v15
	v_exp_f32_e32 v17, v16
	v_cvt_pk_bf16_f32 v7, v12, v13
	v_mad_i64_i32 v[12:13], s[6:7], v118, s44, v[0:1]
	v_lshl_add_u64 v[12:13], v[12:13], 0, v[32:33]
	v_add_f32_e32 v3, 1.0, v3
	v_rcp_f32_e32 v16, v3
	v_add_f32_e32 v3, 1.0, v17
	global_store_dwordx4 v[12:13], v[4:7], off
	v_lshlrev_b32_e32 v12, 16, v101
	v_rcp_f32_e32 v17, v3
	v_and_b32_e32 v13, 0xffff0000, v101
	v_mul_f32_e32 v3, 0xbfb8aa3b, v12
	s_waitcnt lgkmcnt(0)
	v_lshlrev_b32_e32 v4, 16, v8
	v_and_b32_e32 v5, 0xffff0000, v8
	v_exp_f32_e32 v3, v3
	v_mul_f32_e32 v8, 0xbfb8aa3b, v13
	v_exp_f32_e32 v8, v8
	v_pk_mul_f32 v[6:7], v[16:17], v[14:15]
	v_add_f32_e32 v3, 1.0, v3
	v_pk_mul_f32 v[4:5], v[6:7], v[4:5]
	v_rcp_f32_e32 v6, v3
	v_add_f32_e32 v3, 1.0, v8
	v_rcp_f32_e32 v7, v3
	v_cvt_pk_bf16_f32 v4, v4, v5
	v_lshlrev_b32_e32 v8, 16, v9
	v_and_b32_e32 v9, 0xffff0000, v9
	v_pk_mul_f32 v[6:7], v[6:7], v[12:13]
	v_lshlrev_b32_e32 v12, 16, v102
	v_and_b32_e32 v13, 0xffff0000, v102
	v_mul_f32_e32 v3, 0xbfb8aa3b, v12
	v_exp_f32_e32 v3, v3
	v_mul_f32_e32 v5, 0xbfb8aa3b, v13
	v_exp_f32_e32 v5, v5
	v_pk_mul_f32 v[6:7], v[6:7], v[8:9]
	v_add_f32_e32 v3, 1.0, v3
	v_rcp_f32_e32 v8, v3
	v_add_f32_e32 v3, 1.0, v5
	v_rcp_f32_e32 v9, v3
	v_cvt_pk_bf16_f32 v5, v6, v7
	v_lshlrev_b32_e32 v6, 16, v10
	v_and_b32_e32 v7, 0xffff0000, v10
	v_pk_mul_f32 v[8:9], v[8:9], v[12:13]
	v_lshlrev_b32_e32 v12, 16, v103
	v_and_b32_e32 v13, 0xffff0000, v103
	v_mul_f32_e32 v3, 0xbfb8aa3b, v12
	v_exp_f32_e32 v3, v3
	v_mul_f32_e32 v10, 0xbfb8aa3b, v13
	v_exp_f32_e32 v10, v10
	v_pk_mul_f32 v[6:7], v[8:9], v[6:7]
	v_add_f32_e32 v3, 1.0, v3
	v_rcp_f32_e32 v8, v3
	v_add_f32_e32 v3, 1.0, v10
	v_rcp_f32_e32 v9, v3
	v_lshlrev_b32_e32 v10, 16, v11
	v_and_b32_e32 v11, 0xffff0000, v11
	v_cvt_pk_bf16_f32 v6, v6, v7
	v_pk_mul_f32 v[8:9], v[8:9], v[12:13]
	s_waitcnt vmcnt(6)
	v_lshlrev_b32_e32 v12, 16, v88
	v_pk_mul_f32 v[8:9], v[8:9], v[10:11]
	v_and_b32_e32 v13, 0xffff0000, v88
	v_cvt_pk_bf16_f32 v7, v8, v9
	v_mad_i64_i32 v[8:9], s[6:7], v66, s44, v[0:1]
	v_lshl_add_u64 v[8:9], v[8:9], 0, v[32:33]
	v_mul_f32_e32 v3, 0xbfb8aa3b, v12
	global_store_dwordx4 v[8:9], v[4:7], off
	v_exp_f32_e32 v3, v3
	s_movk_i32 s81, 0xff
	v_mul_f32_e32 v4, 0xbfb8aa3b, v13
	v_exp_f32_e32 v8, v4
	v_add_f32_e32 v3, 1.0, v3
	v_rcp_f32_e32 v14, v3
	ds_read_b128 v[4:7], v2 offset:4608
	v_add_f32_e32 v3, 1.0, v8
	v_rcp_f32_e32 v15, v3
	ds_read_b128 v[8:11], v2 offset:5760
	v_readlane_b32 s97, v254, 32
	s_waitcnt lgkmcnt(1)
	v_lshlrev_b32_e32 v16, 16, v4
	v_pk_mul_f32 v[12:13], v[14:15], v[12:13]
	v_lshlrev_b32_e32 v14, 16, v89
	v_and_b32_e32 v15, 0xffff0000, v89
	v_mul_f32_e32 v3, 0xbfb8aa3b, v14
	v_and_b32_e32 v17, 0xffff0000, v4
	v_exp_f32_e32 v3, v3
	v_mul_f32_e32 v4, 0xbfb8aa3b, v15
	v_exp_f32_e32 v4, v4
	v_pk_mul_f32 v[12:13], v[12:13], v[16:17]
	v_add_f32_e32 v3, 1.0, v3
	v_rcp_f32_e32 v16, v3
	v_add_f32_e32 v3, 1.0, v4
	v_rcp_f32_e32 v17, v3
	v_cvt_pk_bf16_f32 v4, v12, v13
	v_lshlrev_b32_e32 v12, 16, v5
	v_and_b32_e32 v13, 0xffff0000, v5
	v_pk_mul_f32 v[14:15], v[16:17], v[14:15]
	v_lshlrev_b32_e32 v16, 16, v90
	v_and_b32_e32 v17, 0xffff0000, v90
	v_mul_f32_e32 v3, 0xbfb8aa3b, v16
	v_exp_f32_e32 v3, v3
	v_mul_f32_e32 v5, 0xbfb8aa3b, v17
	v_exp_f32_e32 v5, v5
	v_pk_mul_f32 v[12:13], v[14:15], v[12:13]
	v_add_f32_e32 v3, 1.0, v3
	v_rcp_f32_e32 v14, v3
	v_add_f32_e32 v3, 1.0, v5
	v_rcp_f32_e32 v15, v3
	v_cvt_pk_bf16_f32 v5, v12, v13
	v_lshlrev_b32_e32 v12, 16, v6
	v_and_b32_e32 v13, 0xffff0000, v6
	v_pk_mul_f32 v[14:15], v[14:15], v[16:17]
	v_lshlrev_b32_e32 v16, 16, v91
	v_and_b32_e32 v17, 0xffff0000, v91
	v_mul_f32_e32 v3, 0xbfb8aa3b, v16
	v_exp_f32_e32 v3, v3
	v_mul_f32_e32 v6, 0xbfb8aa3b, v17
	v_exp_f32_e32 v6, v6
	v_pk_mul_f32 v[12:13], v[14:15], v[12:13]
	v_add_f32_e32 v3, 1.0, v3
	v_rcp_f32_e32 v14, v3
	v_add_f32_e32 v3, 1.0, v6
	v_rcp_f32_e32 v15, v3
	v_cvt_pk_bf16_f32 v6, v12, v13
	v_lshlrev_b32_e32 v12, 16, v7
	v_and_b32_e32 v13, 0xffff0000, v7
	v_pk_mul_f32 v[14:15], v[14:15], v[16:17]
	s_mov_b32 s82, 0x10000
	v_pk_mul_f32 v[12:13], v[14:15], v[12:13]
	s_waitcnt vmcnt(6)
	v_lshlrev_b32_e32 v14, 16, v84
	v_and_b32_e32 v15, 0xffff0000, v84
	v_mul_f32_e32 v3, 0xbfb8aa3b, v14
	v_exp_f32_e32 v3, v3
	v_mul_f32_e32 v16, 0xbfb8aa3b, v15
	v_exp_f32_e32 v17, v16
	v_cvt_pk_bf16_f32 v7, v12, v13
	v_mad_i64_i32 v[12:13], s[6:7], v46, s44, v[0:1]
	v_lshl_add_u64 v[12:13], v[12:13], 0, v[32:33]
	v_add_f32_e32 v3, 1.0, v3
	v_rcp_f32_e32 v16, v3
	v_add_f32_e32 v3, 1.0, v17
	global_store_dwordx4 v[12:13], v[4:7], off
	v_lshlrev_b32_e32 v12, 16, v85
	v_rcp_f32_e32 v17, v3
	v_and_b32_e32 v13, 0xffff0000, v85
	v_mul_f32_e32 v3, 0xbfb8aa3b, v12
	s_waitcnt lgkmcnt(0)
	v_lshlrev_b32_e32 v4, 16, v8
	v_and_b32_e32 v5, 0xffff0000, v8
	v_exp_f32_e32 v3, v3
	v_mul_f32_e32 v8, 0xbfb8aa3b, v13
	v_exp_f32_e32 v8, v8
	v_pk_mul_f32 v[6:7], v[16:17], v[14:15]
	v_add_f32_e32 v3, 1.0, v3
	v_pk_mul_f32 v[4:5], v[6:7], v[4:5]
	v_rcp_f32_e32 v6, v3
	v_add_f32_e32 v3, 1.0, v8
	v_rcp_f32_e32 v7, v3
	v_cvt_pk_bf16_f32 v4, v4, v5
	v_lshlrev_b32_e32 v8, 16, v9
	v_and_b32_e32 v9, 0xffff0000, v9
	v_pk_mul_f32 v[6:7], v[6:7], v[12:13]
	v_lshlrev_b32_e32 v12, 16, v86
	v_and_b32_e32 v13, 0xffff0000, v86
	v_mul_f32_e32 v3, 0xbfb8aa3b, v12
	v_exp_f32_e32 v3, v3
	v_mul_f32_e32 v5, 0xbfb8aa3b, v13
	v_exp_f32_e32 v5, v5
	v_pk_mul_f32 v[6:7], v[6:7], v[8:9]
	v_add_f32_e32 v3, 1.0, v3
	v_rcp_f32_e32 v8, v3
	v_add_f32_e32 v3, 1.0, v5
	v_rcp_f32_e32 v9, v3
	v_cvt_pk_bf16_f32 v5, v6, v7
	v_lshlrev_b32_e32 v6, 16, v10
	v_and_b32_e32 v7, 0xffff0000, v10
	v_pk_mul_f32 v[8:9], v[8:9], v[12:13]
	v_lshlrev_b32_e32 v12, 16, v87
	v_and_b32_e32 v13, 0xffff0000, v87
	v_mul_f32_e32 v3, 0xbfb8aa3b, v12
	v_exp_f32_e32 v3, v3
	v_mul_f32_e32 v10, 0xbfb8aa3b, v13
	v_exp_f32_e32 v10, v10
	v_pk_mul_f32 v[6:7], v[8:9], v[6:7]
	v_add_f32_e32 v3, 1.0, v3
	v_rcp_f32_e32 v8, v3
	v_add_f32_e32 v3, 1.0, v10
	v_rcp_f32_e32 v9, v3
	v_lshlrev_b32_e32 v10, 16, v11
	v_and_b32_e32 v11, 0xffff0000, v11
	v_cvt_pk_bf16_f32 v6, v6, v7
	v_pk_mul_f32 v[8:9], v[8:9], v[12:13]
	s_waitcnt vmcnt(6)
	v_lshlrev_b32_e32 v12, 16, v76
	v_pk_mul_f32 v[8:9], v[8:9], v[10:11]
	v_and_b32_e32 v13, 0xffff0000, v76
	v_cvt_pk_bf16_f32 v7, v8, v9
	v_mad_i64_i32 v[8:9], s[6:7], v38, s44, v[0:1]
	v_lshl_add_u64 v[8:9], v[8:9], 0, v[32:33]
	v_mul_f32_e32 v3, 0xbfb8aa3b, v12
	global_store_dwordx4 v[8:9], v[4:7], off
	v_exp_f32_e32 v3, v3
	s_nop 0
	v_mul_f32_e32 v4, 0xbfb8aa3b, v13
	v_exp_f32_e32 v8, v4
	v_add_f32_e32 v3, 1.0, v3
	v_rcp_f32_e32 v14, v3
	ds_read_b128 v[4:7], v2 offset:6912
	v_add_f32_e32 v3, 1.0, v8
	v_rcp_f32_e32 v15, v3
	ds_read_b128 v[8:11], v2 offset:8064
	s_waitcnt lgkmcnt(1)
	v_lshlrev_b32_e32 v2, 16, v4
	v_pk_mul_f32 v[12:13], v[14:15], v[12:13]
	v_lshlrev_b32_e32 v14, 16, v77
	v_and_b32_e32 v3, 0xffff0000, v4
	v_and_b32_e32 v15, 0xffff0000, v77
	v_mul_f32_e32 v4, 0xbfb8aa3b, v14
	v_exp_f32_e32 v4, v4
	v_mul_f32_e32 v16, 0xbfb8aa3b, v15
	v_exp_f32_e32 v16, v16
	v_pk_mul_f32 v[2:3], v[12:13], v[2:3]
	v_add_f32_e32 v4, 1.0, v4
	v_rcp_f32_e32 v12, v4
	v_add_f32_e32 v4, 1.0, v16
	v_rcp_f32_e32 v13, v4
	v_cvt_pk_bf16_f32 v2, v2, v3
	v_lshlrev_b32_e32 v4, 16, v5
	v_and_b32_e32 v5, 0xffff0000, v5
	v_pk_mul_f32 v[12:13], v[12:13], v[14:15]
	v_lshlrev_b32_e32 v14, 16, v78
	v_and_b32_e32 v15, 0xffff0000, v78
	v_mul_f32_e32 v3, 0xbfb8aa3b, v14
	v_exp_f32_e32 v3, v3
	v_mul_f32_e32 v16, 0xbfb8aa3b, v15
	v_exp_f32_e32 v16, v16
	v_pk_mul_f32 v[4:5], v[12:13], v[4:5]
	v_add_f32_e32 v3, 1.0, v3
	v_rcp_f32_e32 v12, v3
	v_add_f32_e32 v3, 1.0, v16
	v_rcp_f32_e32 v13, v3
	v_cvt_pk_bf16_f32 v3, v4, v5
	v_lshlrev_b32_e32 v4, 16, v6
	v_and_b32_e32 v5, 0xffff0000, v6
	v_pk_mul_f32 v[12:13], v[12:13], v[14:15]
	v_lshlrev_b32_e32 v14, 16, v79
	v_and_b32_e32 v15, 0xffff0000, v79
	v_mul_f32_e32 v6, 0xbfb8aa3b, v14
	v_exp_f32_e32 v6, v6
	v_mul_f32_e32 v16, 0xbfb8aa3b, v15
	v_exp_f32_e32 v16, v16
	v_pk_mul_f32 v[4:5], v[12:13], v[4:5]
	v_add_f32_e32 v6, 1.0, v6
	v_rcp_f32_e32 v12, v6
	v_add_f32_e32 v6, 1.0, v16
	v_rcp_f32_e32 v13, v6
	v_lshlrev_b32_e32 v6, 16, v7
	v_and_b32_e32 v7, 0xffff0000, v7
	v_cvt_pk_bf16_f32 v4, v4, v5
	v_pk_mul_f32 v[12:13], v[12:13], v[14:15]
	s_nop 0
	v_pk_mul_f32 v[6:7], v[12:13], v[6:7]
	s_waitcnt vmcnt(6)
	v_lshlrev_b32_e32 v12, 16, v72
	v_and_b32_e32 v13, 0xffff0000, v72
	v_mul_f32_e32 v14, 0xbfb8aa3b, v12
	v_mul_f32_e32 v15, 0xbfb8aa3b, v13
	v_exp_f32_e32 v14, v14
	v_exp_f32_e32 v15, v15
	v_cvt_pk_bf16_f32 v5, v6, v7
	v_mad_i64_i32 v[6:7], s[6:7], v34, s44, v[0:1]
	v_add_f32_e32 v14, 1.0, v14
	v_add_f32_e32 v15, 1.0, v15
	v_rcp_f32_e32 v14, v14
	v_rcp_f32_e32 v15, v15
	v_lshl_add_u64 v[6:7], v[6:7], 0, v[32:33]
	global_store_dwordx4 v[6:7], v[2:5], off
	v_lshlrev_b32_e32 v6, 16, v73
	v_and_b32_e32 v7, 0xffff0000, v73
	s_waitcnt lgkmcnt(0)
	v_lshlrev_b32_e32 v2, 16, v8
	v_and_b32_e32 v3, 0xffff0000, v8
	v_pk_mul_f32 v[4:5], v[14:15], v[12:13]
	v_mul_f32_e32 v8, 0xbfb8aa3b, v6
	v_mul_f32_e32 v12, 0xbfb8aa3b, v7
	v_exp_f32_e32 v8, v8
	v_exp_f32_e32 v12, v12
	v_pk_mul_f32 v[2:3], v[4:5], v[2:3]
	v_mad_i64_i32 v[0:1], s[6:7], v18, s44, v[0:1]
	v_add_f32_e32 v4, 1.0, v8
	v_add_f32_e32 v5, 1.0, v12
	v_rcp_f32_e32 v4, v4
	v_rcp_f32_e32 v5, v5
	v_cvt_pk_bf16_f32 v2, v2, v3
	v_lshlrev_b32_e32 v8, 16, v9
	v_and_b32_e32 v9, 0xffff0000, v9
	v_pk_mul_f32 v[4:5], v[4:5], v[6:7]
	v_lshlrev_b32_e32 v6, 16, v74
	v_and_b32_e32 v7, 0xffff0000, v74
	v_mul_f32_e32 v3, 0xbfb8aa3b, v6
	v_exp_f32_e32 v3, v3
	v_mul_f32_e32 v12, 0xbfb8aa3b, v7
	v_exp_f32_e32 v12, v12
	v_pk_mul_f32 v[4:5], v[4:5], v[8:9]
	v_add_f32_e32 v3, 1.0, v3
	v_rcp_f32_e32 v8, v3
	v_add_f32_e32 v3, 1.0, v12
	v_rcp_f32_e32 v9, v3
	v_cvt_pk_bf16_f32 v3, v4, v5
	v_lshlrev_b32_e32 v4, 16, v10
	v_and_b32_e32 v5, 0xffff0000, v10
	v_pk_mul_f32 v[6:7], v[8:9], v[6:7]
	v_lshlrev_b32_e32 v8, 16, v75
	v_and_b32_e32 v9, 0xffff0000, v75
	v_mul_f32_e32 v10, 0xbfb8aa3b, v8
	v_mul_f32_e32 v12, 0xbfb8aa3b, v9
	v_exp_f32_e32 v10, v10
	v_exp_f32_e32 v12, v12
	v_pk_mul_f32 v[4:5], v[6:7], v[4:5]
	v_lshl_add_u64 v[0:1], v[0:1], 0, v[32:33]
	v_add_f32_e32 v6, 1.0, v10
	v_add_f32_e32 v7, 1.0, v12
	v_rcp_f32_e32 v6, v6
	v_rcp_f32_e32 v7, v7
	v_lshlrev_b32_e32 v10, 16, v11
	v_and_b32_e32 v11, 0xffff0000, v11
	v_cvt_pk_bf16_f32 v4, v4, v5
	v_pk_mul_f32 v[6:7], v[6:7], v[8:9]
	s_mov_b64 s[6:7], s[76:77]
	v_pk_mul_f32 v[6:7], v[6:7], v[10:11]
	s_nop 0
	v_cvt_pk_bf16_f32 v5, v6, v7
	global_store_dwordx4 v[0:1], v[2:5], off
